# on top of v29: accumulator zeroing with v_mov_b64 in three GEMM instances and the duplicate s[100:101] base copy dropped
# speedup vs baseline: 1.0088x; 1.0088x over previous
; #define PG8_STAGE(bufoff, gbase) do { _Pragma("unroll") for (int _i = 0; _i < 2; ++_i) \
;         __builtin_amdgcn_global_load_lds((const unsigned*)((const char*)(gbase) + voff[_i]), (LAS unsigned*)(lds + (bufoff) + ldsw + _i * 8192), 16, 0, 0); } while (0)
; #define PG8_LDA(dst, b, h) do { _Pragma("unroll") for (int m = 0; m < 4; ++m) _Pragma("unroll") for (int k = 0; k < 2; ++k) dst[m][k] = *(const LAS bf16x8*)(lds + PG8_SA(b, h) + aoff + m * 2048 + k * 1024); } while (0)
; #define PG8_LDB(dst, b, h) do { _Pragma("unroll") for (int n = 0; n < 2; ++n) _Pragma("unroll") for (int k = 0; k < 2; ++k) dst[n][k] = *(const LAS bf16x8*)(lds + PG8_SB(b, h) + boff + n * 2048 + k * 1024); } while (0)
; #define PG8_WAIT_L(n) asm volatile("s_waitcnt lgkmcnt(" #n ")" ::: "memory")
; #define PG8_BAR __builtin_amdgcn_s_barrier()
; #define PG8_SCHED __builtin_amdgcn_sched_barrier(0)
; template <class Epi>
; DI void gemm_phase(LAS unsigned char* lds, const Gemm g, const StaticOrder& S, const Epi& E) {
;     ...
;         const bool has_next = S.next(ui + 1, nxt);
;         const char* nA = has_next ? (const char*)g.A + (size_t)nxt.pm * tstep : cA; const char* nB = has_next ? (const char*)g.Bt + (size_t)nxt.pn * tstep : cB;
;         for (int t = 0; t < nt; t += 2) {
;             const bool last = (t == nt - 2);
;             const char* a1 = cA + (size_t)(t + 1) * kstep;
;             const char* a2 = last ? nA : cA + (size_t)(t + 2) * kstep; const char* b2 = last ? nB : cB + (size_t)(t + 2) * kstep;
;             const char* a3 = a2 + kstep; const char* b3 = b2 + kstep;
;             PG8_LDB(B0, 0, 0); PG8_SCHED; PG8_LDA(At, 0, 0); PG8_STAGE(PG8_SA(1, 1), a1 + hstep);
;             PG8_WAIT_L(8); PG8_BAR; PG8_WAIT_L(0); PG8_MMA(0, 0, At, B0); PG8_BAR; PG8_SCHED;
;             PG8_LDB(B1, 0, 1); PG8_STAGE(PG8_SB(0, 0), b2);
;             PG8_BAR; PG8_WAIT_L(0); PG8_MMA(0, 1, At, B1); PG8_BAR;
;             PG8_LDA(At, 0, 1); PG8_STAGE(PG8_SA(0, 0), a2);
;     ...
;         for (int a = 0; a < 2; ++a)
; #pragma unroll
;             for (int b = 0; b < 2; ++b)
; #pragma unroll
;                 for (int m = 0; m < 4; ++m)
; #pragma unroll
;                     for (int n = 0; n < 2; ++n) acc[a][b][m][n] = (f32x4){0.f, 0.f, 0.f, 0.f};
.LBB0_36:
	s_ashr_i32 s11, s10, 31
	v_mov_b64_e32 v[0:1], 0xb00
	s_lshl_b64 s[4:5], s[10:11], 20
	v_cmp_lt_i64_e32 vcc, s[14:15], v[0:1]
	s_add_u32 s14, s92, s4
	s_addc_u32 s15, s93, s5
	s_and_b64 s[4:5], vcc, exec
	s_cselect_b32 s4, s15, s19
	s_cselect_b32 s5, s14, s18
	s_ashr_i32 s9, s8, 31
	s_lshl_b64 s[16:17], s[8:9], 20
	s_add_u32 s16, s25, s16
	s_addc_u32 s17, s26, s17
	s_and_b64 s[22:23], vcc, exec
	s_cselect_b32 s9, s17, s21
	s_cselect_b32 s11, s16, s20
	s_add_u32 s18, s18, 0x80080
	s_addc_u32 s19, s19, 0
	s_add_u32 s33, s20, 0x100
	v_mov_b32_e32 v0, 0
	v_mov_b32_e32 v1, 0
	s_addc_u32 s37, s21, 0
	s_mov_b32 s38, -2
	v_mov_b64_e32 v[2:3], v[0:1]
	v_mov_b64_e32 v[4:5], v[0:1]
	v_mov_b64_e32 v[6:7], v[0:1]
	v_mov_b64_e32 v[8:9], v[0:1]
	v_mov_b64_e32 v[10:11], v[0:1]
	v_mov_b64_e32 v[12:13], v[0:1]
	v_mov_b64_e32 v[14:15], v[0:1]
	v_mov_b64_e32 v[16:17], v[0:1]
	v_mov_b64_e32 v[18:19], v[0:1]
	v_mov_b64_e32 v[20:21], v[0:1]
	v_mov_b64_e32 v[22:23], v[0:1]
	v_mov_b64_e32 v[24:25], v[0:1]
	v_mov_b64_e32 v[26:27], v[0:1]
	v_mov_b64_e32 v[28:29], v[0:1]
	v_mov_b64_e32 v[30:31], v[0:1]
	v_mov_b64_e32 v[32:33], v[0:1]
	v_mov_b64_e32 v[34:35], v[0:1]
	v_mov_b64_e32 v[36:37], v[0:1]
	v_mov_b64_e32 v[38:39], v[0:1]
	v_mov_b64_e32 v[40:41], v[0:1]
	v_mov_b64_e32 v[42:43], v[0:1]
	v_mov_b64_e32 v[44:45], v[0:1]
	v_mov_b64_e32 v[46:47], v[0:1]
	v_mov_b64_e32 v[48:49], v[0:1]
	v_mov_b64_e32 v[50:51], v[0:1]
	v_mov_b64_e32 v[52:53], v[0:1]
	v_mov_b64_e32 v[54:55], v[0:1]
	v_mov_b64_e32 v[56:57], v[0:1]
	v_mov_b64_e32 v[58:59], v[0:1]
	v_mov_b64_e32 v[60:61], v[0:1]
	v_mov_b64_e32 v[62:63], v[0:1]
	v_mov_b64_e32 v[64:65], v[0:1]
	v_mov_b64_e32 v[66:67], v[0:1]
	v_mov_b64_e32 v[68:69], v[0:1]
	v_mov_b64_e32 v[70:71], v[0:1]
	v_mov_b64_e32 v[72:73], v[0:1]
	v_mov_b64_e32 v[74:75], v[0:1]
	v_mov_b64_e32 v[76:77], v[0:1]
	v_mov_b64_e32 v[78:79], v[0:1]
	v_mov_b64_e32 v[80:81], v[0:1]
	v_mov_b64_e32 v[82:83], v[0:1]
	v_mov_b64_e32 v[84:85], v[0:1]
	v_mov_b64_e32 v[86:87], v[0:1]
	v_mov_b64_e32 v[88:89], v[0:1]
	v_mov_b64_e32 v[90:91], v[0:1]
	v_mov_b64_e32 v[92:93], v[0:1]
	v_mov_b64_e32 v[94:95], v[0:1]
	v_mov_b64_e32 v[96:97], v[0:1]
	v_mov_b64_e32 v[98:99], v[0:1]
	v_mov_b64_e32 v[100:101], v[0:1]
	v_mov_b64_e32 v[102:103], v[0:1]
	v_mov_b64_e32 v[104:105], v[0:1]
	v_mov_b64_e32 v[106:107], v[0:1]
	v_mov_b64_e32 v[108:109], v[0:1]
	v_mov_b64_e32 v[110:111], v[0:1]
	v_mov_b64_e32 v[112:113], v[0:1]
	v_mov_b64_e32 v[114:115], v[0:1]
	v_mov_b64_e32 v[116:117], v[0:1]
	v_mov_b64_e32 v[118:119], v[0:1]
	v_mov_b64_e32 v[120:121], v[0:1]
	v_mov_b64_e32 v[122:123], v[0:1]
	v_mov_b64_e32 v[124:125], v[0:1]
	v_mov_b64_e32 v[126:127], v[0:1]
.LBB0_37:
	ds_read_b128 v[138:141], v135
	ds_read_b128 v[142:145], v135 offset:1024
	ds_read_b128 v[146:149], v135 offset:2048
	ds_read_b128 v[150:153], v135 offset:3072
	ds_read_b128 v[186:189], v137
	ds_read_b128 v[190:193], v137 offset:1024
	ds_read_b128 v[194:197], v137 offset:2048
	ds_read_b128 v[198:201], v137 offset:3072
	ds_read_b128 v[202:205], v137 offset:4096
	ds_read_b128 v[206:209], v137 offset:5120
	ds_read_b128 v[210:213], v137 offset:6144
	ds_read_b128 v[214:217], v137 offset:7168
	s_add_u32 s20, s18, 0xfff80080
	s_addc_u32 s21, s19, -1
	s_add_i32 s39, 0, 0x10000
	s_cmp_eq_u32 s38, 28
	s_cselect_b32 s23, s4, s21
	s_cselect_b32 s22, s5, s20
	s_cselect_b32 s21, s9, s37
	s_cselect_b32 s20, s11, s33
	s_add_i32 m0, s28, 0xc000
	s_nop 0
	global_load_lds_dwordx4 v130, s[18:19]
	s_add_i32 m0, s28, 0xe000
	s_nop 0
	global_load_lds_dwordx4 v132, s[18:19]
	s_waitcnt lgkmcnt(8)
	s_setprio 1
	s_barrier
	s_waitcnt lgkmcnt(0)
	v_mfma_f32_16x16x32_bf16 v[124:127], v[138:141], v[186:189], v[124:127]
	v_mfma_f32_16x16x32_bf16 v[120:123], v[146:149], v[186:189], v[120:123]
	v_mfma_f32_16x16x32_bf16 v[108:111], v[138:141], v[194:197], v[108:111]
	v_mfma_f32_16x16x32_bf16 v[104:107], v[146:149], v[194:197], v[104:107]
	v_mfma_f32_16x16x32_bf16 v[92:95], v[138:141], v[202:205], v[92:95]
	v_mfma_f32_16x16x32_bf16 v[88:91], v[146:149], v[202:205], v[88:91]
	v_mfma_f32_16x16x32_bf16 v[76:79], v[138:141], v[210:213], v[76:79]
	v_mfma_f32_16x16x32_bf16 v[72:75], v[146:149], v[210:213], v[72:75]
	v_mfma_f32_16x16x32_bf16 v[124:127], v[142:145], v[190:193], v[124:127]
	v_mfma_f32_16x16x32_bf16 v[120:123], v[150:153], v[190:193], v[120:123]
	v_mfma_f32_16x16x32_bf16 v[108:111], v[142:145], v[198:201], v[108:111]
	v_mfma_f32_16x16x32_bf16 v[104:107], v[150:153], v[198:201], v[104:107]
	v_mfma_f32_16x16x32_bf16 v[92:95], v[142:145], v[206:209], v[92:95]
	v_mfma_f32_16x16x32_bf16 v[88:91], v[150:153], v[206:209], v[88:91]
	v_mfma_f32_16x16x32_bf16 v[76:79], v[142:145], v[214:217], v[76:79]
	s_setprio 0
	v_mfma_f32_16x16x32_bf16 v[72:75], v[150:153], v[214:217], v[72:75]
	s_barrier
	ds_read_b128 v[226:229], v135 offset:16384
	ds_read_b128 v[230:233], v135 offset:17408
	ds_read_b128 v[234:237], v135 offset:18432
	ds_read_b128 v[238:241], v135 offset:19456
	s_add_i32 s42, 0, 0x14000
	s_add_i32 s39, s39, s27
	s_mov_b32 m0, s39
	s_nop 0
	global_load_lds_dwordx4 v158, s[20:21]
	s_add_i32 m0, s39, 0x2000
	s_nop 0
	global_load_lds_dwordx4 v128, s[20:21]
	s_waitcnt lgkmcnt(0)
	s_setprio 1
	s_barrier
; #define PG8_STAGE(bufoff, gbase) do { _Pragma("unroll") for (int _i = 0; _i < 2; ++_i) \
;         __builtin_amdgcn_global_load_lds((const unsigned*)((const char*)(gbase) + voff[_i]), (LAS unsigned*)(lds + (bufoff) + ldsw + _i * 8192), 16, 0, 0); } while (0)
; #define PG8_LDA(dst, b, h) do { _Pragma("unroll") for (int m = 0; m < 4; ++m) _Pragma("unroll") for (int k = 0; k < 2; ++k) dst[m][k] = *(const LAS bf16x8*)(lds + PG8_SA(b, h) + aoff + m * 2048 + k * 1024); } while (0)
; #define PG8_LDB(dst, b, h) do { _Pragma("unroll") for (int n = 0; n < 2; ++n) _Pragma("unroll") for (int k = 0; k < 2; ++k) dst[n][k] = *(const LAS bf16x8*)(lds + PG8_SB(b, h) + boff + n * 2048 + k * 1024); } while (0)
; #define PG8_MMA(ai, bj, At, Bt) do { __builtin_amdgcn_s_setprio(1); _Pragma("unroll") for (int m = 0; m < 4; ++m) _Pragma("unroll") for (int n = 0; n < 2; ++n) _Pragma("unroll") for (int k = 0; k < 2; ++k) \
;         acc[ai][bj][m][n] = __builtin_amdgcn_mfma_f32_16x16x32_bf16(Bt[n][k], At[m][k], acc[ai][bj][m][n], 0, 0, 0); __builtin_amdgcn_s_setprio(0); } while (0)
; #define PG8_WAIT_V(n) asm volatile("s_waitcnt vmcnt(" #n ")" ::: "memory")
; #define PG8_WAIT_L(n) asm volatile("s_waitcnt lgkmcnt(" #n ")" ::: "memory")
; #define PG8_BAR __builtin_amdgcn_s_barrier()
; #define PG8_SCHED __builtin_amdgcn_sched_barrier(0)
; template <class Epi>
; DI void gemm_phase(LAS unsigned char* lds, const Gemm g, const StaticOrder& S, const Epi& E) {
;     ...
;             PG8_BAR; PG8_WAIT_L(0); PG8_MMA(0, 1, At, B1); PG8_BAR;
;             PG8_LDA(At, 0, 1); PG8_STAGE(PG8_SA(0, 0), a2);
;             PG8_BAR; PG8_WAIT_L(0); PG8_MMA(1, 0, At, B0); PG8_BAR; PG8_SCHED;
;             PG8_STAGE(PG8_SB(0, 1), b2 + hstep);
;             PG8_WAIT_V(6); PG8_BAR; PG8_MMA(1, 1, At, B1); PG8_BAR;
;             PG8_LDB(B0, 1, 0); PG8_SCHED; PG8_LDA(At, 1, 0); PG8_STAGE(PG8_SA(0, 1), a2 + hstep);
;             PG8_WAIT_L(8); PG8_BAR; PG8_WAIT_L(0); PG8_MMA(0, 0, At, B0); PG8_BAR; PG8_SCHED;
;             PG8_LDB(B1, 1, 1); PG8_STAGE(PG8_SB(1, 0), b3);
;             PG8_BAR; PG8_WAIT_L(0); PG8_MMA(0, 1, At, B1); PG8_BAR;
	v_mfma_f32_16x16x32_bf16 v[116:119], v[226:229], v[186:189], v[116:119]
	v_mfma_f32_16x16x32_bf16 v[112:115], v[234:237], v[186:189], v[112:115]
	v_mfma_f32_16x16x32_bf16 v[100:103], v[226:229], v[194:197], v[100:103]
	v_mfma_f32_16x16x32_bf16 v[96:99], v[234:237], v[194:197], v[96:99]
	v_mfma_f32_16x16x32_bf16 v[84:87], v[226:229], v[202:205], v[84:87]
	v_mfma_f32_16x16x32_bf16 v[80:83], v[234:237], v[202:205], v[80:83]
	v_mfma_f32_16x16x32_bf16 v[68:71], v[226:229], v[210:213], v[68:71]
	v_mfma_f32_16x16x32_bf16 v[64:67], v[234:237], v[210:213], v[64:67]
	v_mfma_f32_16x16x32_bf16 v[116:119], v[230:233], v[190:193], v[116:119]
	s_mov_b32 m0, s28
	v_mfma_f32_16x16x32_bf16 v[112:115], v[238:241], v[190:193], v[112:115]
	v_mfma_f32_16x16x32_bf16 v[100:103], v[230:233], v[198:201], v[100:103]
	v_mfma_f32_16x16x32_bf16 v[96:99], v[238:241], v[198:201], v[96:99]
	v_mfma_f32_16x16x32_bf16 v[84:87], v[230:233], v[206:209], v[84:87]
	v_mfma_f32_16x16x32_bf16 v[80:83], v[238:241], v[206:209], v[80:83]
	v_mfma_f32_16x16x32_bf16 v[68:71], v[230:233], v[214:217], v[68:71]
	s_setprio 0
	v_mfma_f32_16x16x32_bf16 v[64:67], v[238:241], v[214:217], v[64:67]
	s_barrier
	ds_read_b128 v[186:189], v137 offset:16384
	ds_read_b128 v[190:193], v137 offset:17408
	ds_read_b128 v[194:197], v137 offset:18432
	ds_read_b128 v[198:201], v137 offset:19456
	ds_read_b128 v[202:205], v137 offset:20480
	ds_read_b128 v[206:209], v137 offset:21504
	ds_read_b128 v[210:213], v137 offset:22528
	ds_read_b128 v[214:217], v137 offset:23552
	global_load_lds_dwordx4 v158, s[22:23]
	s_mov_b64 s[100:101], s[22:23]
	s_mov_b32 m0, s29
	s_nop 0
	global_load_lds_dwordx4 v128, s[22:23]
	s_waitcnt lgkmcnt(0)
	s_setprio 1
	s_barrier
	v_mfma_f32_16x16x32_bf16 v[60:63], v[138:141], v[186:189], v[60:63]
	v_mfma_f32_16x16x32_bf16 v[56:59], v[146:149], v[186:189], v[56:59]
	v_mfma_f32_16x16x32_bf16 v[44:47], v[138:141], v[194:197], v[44:47]
	v_mfma_f32_16x16x32_bf16 v[40:43], v[146:149], v[194:197], v[40:43]
	v_mfma_f32_16x16x32_bf16 v[28:31], v[138:141], v[202:205], v[28:31]
	v_mfma_f32_16x16x32_bf16 v[24:27], v[146:149], v[202:205], v[24:27]
	v_mfma_f32_16x16x32_bf16 v[12:15], v[138:141], v[210:213], v[12:15]
	v_mfma_f32_16x16x32_bf16 v[8:11], v[146:149], v[210:213], v[8:11]
	v_mfma_f32_16x16x32_bf16 v[60:63], v[142:145], v[190:193], v[60:63]
	v_mfma_f32_16x16x32_bf16 v[56:59], v[150:153], v[190:193], v[56:59]
	v_mfma_f32_16x16x32_bf16 v[44:47], v[142:145], v[198:201], v[44:47]
	v_mfma_f32_16x16x32_bf16 v[40:43], v[150:153], v[198:201], v[40:43]
	v_mfma_f32_16x16x32_bf16 v[28:31], v[142:145], v[206:209], v[28:31]
	v_mfma_f32_16x16x32_bf16 v[24:27], v[150:153], v[206:209], v[24:27]
	v_mfma_f32_16x16x32_bf16 v[12:15], v[142:145], v[214:217], v[12:15]
	s_setprio 0
	v_mfma_f32_16x16x32_bf16 v[8:11], v[150:153], v[214:217], v[8:11]
	s_barrier
	s_add_u32 s40, s20, 0x80000
	s_addc_u32 s41, s21, 0
	s_add_i32 s39, s42, s27
	s_mov_b32 m0, s39
	s_nop 0
	global_load_lds_dwordx4 v158, s[40:41]
	s_add_i32 m0, s39, 0x2000
	s_nop 0
	global_load_lds_dwordx4 v128, s[40:41]
	s_waitcnt vmcnt(6)
	s_setprio 1
	s_barrier
	v_mfma_f32_16x16x32_bf16 v[52:55], v[226:229], v[186:189], v[52:55]
	v_mfma_f32_16x16x32_bf16 v[48:51], v[234:237], v[186:189], v[48:51]
	v_mfma_f32_16x16x32_bf16 v[36:39], v[226:229], v[194:197], v[36:39]
	v_mfma_f32_16x16x32_bf16 v[32:35], v[234:237], v[194:197], v[32:35]
	v_mfma_f32_16x16x32_bf16 v[20:23], v[226:229], v[202:205], v[20:23]
	v_mfma_f32_16x16x32_bf16 v[16:19], v[234:237], v[202:205], v[16:19]
	v_mfma_f32_16x16x32_bf16 v[4:7], v[226:229], v[210:213], v[4:7]
	v_mfma_f32_16x16x32_bf16 v[0:3], v[234:237], v[210:213], v[0:3]
	v_mfma_f32_16x16x32_bf16 v[52:55], v[230:233], v[190:193], v[52:55]
	s_add_i32 s39, 0, 0x18000
	v_mfma_f32_16x16x32_bf16 v[48:51], v[238:241], v[190:193], v[48:51]
	v_mfma_f32_16x16x32_bf16 v[36:39], v[230:233], v[198:201], v[36:39]
	v_mfma_f32_16x16x32_bf16 v[32:35], v[238:241], v[198:201], v[32:35]
	v_mfma_f32_16x16x32_bf16 v[20:23], v[230:233], v[206:209], v[20:23]
	v_mfma_f32_16x16x32_bf16 v[16:19], v[238:241], v[206:209], v[16:19]
	v_mfma_f32_16x16x32_bf16 v[4:7], v[230:233], v[214:217], v[4:7]
	s_setprio 0
	v_mfma_f32_16x16x32_bf16 v[0:3], v[238:241], v[214:217], v[0:3]
	s_barrier
	ds_read_b128 v[138:141], v135 offset:32768
	ds_read_b128 v[142:145], v135 offset:33792
	ds_read_b128 v[146:149], v135 offset:34816
	ds_read_b128 v[150:153], v135 offset:35840
	ds_read_b128 v[186:189], v137 offset:32768
	ds_read_b128 v[190:193], v137 offset:33792
	ds_read_b128 v[194:197], v137 offset:34816
	ds_read_b128 v[198:201], v137 offset:35840
	ds_read_b128 v[202:205], v137 offset:36864
	ds_read_b128 v[206:209], v137 offset:37888
	ds_read_b128 v[210:213], v137 offset:38912
	ds_read_b128 v[214:217], v137 offset:39936
	s_add_u32 s22, s22, 0x80000
	s_addc_u32 s23, s23, 0
	s_mov_b32 m0, s30
	s_nop 0
	global_load_lds_dwordx4 v158, s[22:23]
	s_mov_b32 m0, s31
	s_nop 0
	global_load_lds_dwordx4 v128, s[22:23]
	s_waitcnt lgkmcnt(8)
	s_setprio 1
	s_barrier
	s_waitcnt lgkmcnt(0)
	v_mfma_f32_16x16x32_bf16 v[124:127], v[138:141], v[186:189], v[124:127]
	v_mfma_f32_16x16x32_bf16 v[120:123], v[146:149], v[186:189], v[120:123]
	v_mfma_f32_16x16x32_bf16 v[108:111], v[138:141], v[194:197], v[108:111]
	v_mfma_f32_16x16x32_bf16 v[104:107], v[146:149], v[194:197], v[104:107]
	v_mfma_f32_16x16x32_bf16 v[92:95], v[138:141], v[202:205], v[92:95]
	v_mfma_f32_16x16x32_bf16 v[88:91], v[146:149], v[202:205], v[88:91]
	v_mfma_f32_16x16x32_bf16 v[76:79], v[138:141], v[210:213], v[76:79]
	v_mfma_f32_16x16x32_bf16 v[72:75], v[146:149], v[210:213], v[72:75]
	v_mfma_f32_16x16x32_bf16 v[124:127], v[142:145], v[190:193], v[124:127]
	v_mfma_f32_16x16x32_bf16 v[120:123], v[150:153], v[190:193], v[120:123]
	v_mfma_f32_16x16x32_bf16 v[108:111], v[142:145], v[198:201], v[108:111]
	v_mfma_f32_16x16x32_bf16 v[104:107], v[150:153], v[198:201], v[104:107]
	v_mfma_f32_16x16x32_bf16 v[92:95], v[142:145], v[206:209], v[92:95]
	v_mfma_f32_16x16x32_bf16 v[88:91], v[150:153], v[206:209], v[88:91]
	v_mfma_f32_16x16x32_bf16 v[76:79], v[142:145], v[214:217], v[76:79]
	s_setprio 0
	v_mfma_f32_16x16x32_bf16 v[72:75], v[150:153], v[214:217], v[72:75]
	s_barrier
; #define PG8_STAGE(bufoff, gbase) do { _Pragma("unroll") for (int _i = 0; _i < 2; ++_i) \
;         __builtin_amdgcn_global_load_lds((const unsigned*)((const char*)(gbase) + voff[_i]), (LAS unsigned*)(lds + (bufoff) + ldsw + _i * 8192), 16, 0, 0); } while (0)
; #define PG8_LDA(dst, b, h) do { _Pragma("unroll") for (int m = 0; m < 4; ++m) _Pragma("unroll") for (int k = 0; k < 2; ++k) dst[m][k] = *(const LAS bf16x8*)(lds + PG8_SA(b, h) + aoff + m * 2048 + k * 1024); } while (0)
; #define PG8_MMA(ai, bj, At, Bt) do { __builtin_amdgcn_s_setprio(1); _Pragma("unroll") for (int m = 0; m < 4; ++m) _Pragma("unroll") for (int n = 0; n < 2; ++n) _Pragma("unroll") for (int k = 0; k < 2; ++k) \
;         acc[ai][bj][m][n] = __builtin_amdgcn_mfma_f32_16x16x32_bf16(Bt[n][k], At[m][k], acc[ai][bj][m][n], 0, 0, 0); __builtin_amdgcn_s_setprio(0); } while (0)
; #define PG8_WAIT_V(n) asm volatile("s_waitcnt vmcnt(" #n ")" ::: "memory")
; #define PG8_WAIT_L(n) asm volatile("s_waitcnt lgkmcnt(" #n ")" ::: "memory")
; #define PG8_BAR __builtin_amdgcn_s_barrier()
; #define PG8_SCHED __builtin_amdgcn_sched_barrier(0)
; template <class Epi>
; DI void gemm_phase(LAS unsigned char* lds, const Gemm g, const StaticOrder& S, const Epi& E) {
;     ...
;             PG8_BAR; PG8_WAIT_L(0); PG8_MMA(0, 1, At, B1); PG8_BAR;
;             PG8_LDA(At, 1, 1); PG8_STAGE(PG8_SA(1, 0), a3);
;             PG8_BAR; PG8_WAIT_L(0); PG8_MMA(1, 0, At, B0); PG8_BAR; PG8_SCHED;
;             PG8_STAGE(PG8_SB(1, 1), b3 + hstep);
;             PG8_WAIT_V(6); PG8_BAR; PG8_MMA(1, 1, At, B1); PG8_BAR;
	ds_read_b128 v[226:229], v135 offset:49152
	ds_read_b128 v[230:233], v135 offset:50176
	ds_read_b128 v[234:237], v135 offset:51200
	ds_read_b128 v[238:241], v135 offset:52224
	s_add_i32 s22, 0, 0x1c000
	s_add_i32 s23, s39, s27
	s_add_i32 m0, s23, 0xffffff80
	s_nop 0
	global_load_lds_dwordx4 v158, s[20:21] offset:128
	s_add_i32 m0, s23, 0x1f80
	s_nop 0
	global_load_lds_dwordx4 v128, s[20:21] offset:128
	s_waitcnt lgkmcnt(0)
	s_setprio 1
	s_barrier
	v_mfma_f32_16x16x32_bf16 v[116:119], v[226:229], v[186:189], v[116:119]
	v_mfma_f32_16x16x32_bf16 v[112:115], v[234:237], v[186:189], v[112:115]
	v_mfma_f32_16x16x32_bf16 v[100:103], v[226:229], v[194:197], v[100:103]
	v_mfma_f32_16x16x32_bf16 v[96:99], v[234:237], v[194:197], v[96:99]
	v_mfma_f32_16x16x32_bf16 v[84:87], v[226:229], v[202:205], v[84:87]
	v_mfma_f32_16x16x32_bf16 v[80:83], v[234:237], v[202:205], v[80:83]
	v_mfma_f32_16x16x32_bf16 v[68:71], v[226:229], v[210:213], v[68:71]
	v_mfma_f32_16x16x32_bf16 v[64:67], v[234:237], v[210:213], v[64:67]
	v_mfma_f32_16x16x32_bf16 v[116:119], v[230:233], v[190:193], v[116:119]
	s_add_i32 m0, s34, 0xffffff80
	v_mfma_f32_16x16x32_bf16 v[112:115], v[238:241], v[190:193], v[112:115]
	v_mfma_f32_16x16x32_bf16 v[100:103], v[230:233], v[198:201], v[100:103]
	v_mfma_f32_16x16x32_bf16 v[96:99], v[238:241], v[198:201], v[96:99]
	v_mfma_f32_16x16x32_bf16 v[84:87], v[230:233], v[206:209], v[84:87]
	v_mfma_f32_16x16x32_bf16 v[80:83], v[238:241], v[206:209], v[80:83]
	v_mfma_f32_16x16x32_bf16 v[68:71], v[230:233], v[214:217], v[68:71]
	s_setprio 0
	v_mfma_f32_16x16x32_bf16 v[64:67], v[238:241], v[214:217], v[64:67]
	s_barrier
	ds_read_b128 v[186:189], v137 offset:49152
	ds_read_b128 v[190:193], v137 offset:50176
	ds_read_b128 v[194:197], v137 offset:51200
	ds_read_b128 v[198:201], v137 offset:52224
	ds_read_b128 v[202:205], v137 offset:53248
	ds_read_b128 v[206:209], v137 offset:54272
	ds_read_b128 v[210:213], v137 offset:55296
	ds_read_b128 v[214:217], v137 offset:56320
	global_load_lds_dwordx4 v158, s[100:101] offset:128
	s_add_i32 m0, s35, 0xffffff80
	s_nop 0
	global_load_lds_dwordx4 v128, s[100:101] offset:128
	s_waitcnt lgkmcnt(0)
	s_setprio 1
	s_barrier
	v_mfma_f32_16x16x32_bf16 v[60:63], v[138:141], v[186:189], v[60:63]
	v_mfma_f32_16x16x32_bf16 v[56:59], v[146:149], v[186:189], v[56:59]
	v_mfma_f32_16x16x32_bf16 v[44:47], v[138:141], v[194:197], v[44:47]
	v_mfma_f32_16x16x32_bf16 v[40:43], v[146:149], v[194:197], v[40:43]
	v_mfma_f32_16x16x32_bf16 v[28:31], v[138:141], v[202:205], v[28:31]
	v_mfma_f32_16x16x32_bf16 v[24:27], v[146:149], v[202:205], v[24:27]
	v_mfma_f32_16x16x32_bf16 v[12:15], v[138:141], v[210:213], v[12:15]
	v_mfma_f32_16x16x32_bf16 v[8:11], v[146:149], v[210:213], v[8:11]
	v_mfma_f32_16x16x32_bf16 v[60:63], v[142:145], v[190:193], v[60:63]
	v_mfma_f32_16x16x32_bf16 v[56:59], v[150:153], v[190:193], v[56:59]
	v_mfma_f32_16x16x32_bf16 v[44:47], v[142:145], v[198:201], v[44:47]
	v_mfma_f32_16x16x32_bf16 v[40:43], v[150:153], v[198:201], v[40:43]
	v_mfma_f32_16x16x32_bf16 v[28:31], v[142:145], v[206:209], v[28:31]
	v_mfma_f32_16x16x32_bf16 v[24:27], v[150:153], v[206:209], v[24:27]
	v_mfma_f32_16x16x32_bf16 v[12:15], v[142:145], v[214:217], v[12:15]
	s_setprio 0
	v_mfma_f32_16x16x32_bf16 v[8:11], v[150:153], v[214:217], v[8:11]
	s_barrier
	s_add_u32 s20, s20, 0x80080
	s_addc_u32 s21, s21, 0
	s_add_i32 s22, s22, s27
	s_mov_b32 m0, s22
	s_nop 0
	global_load_lds_dwordx4 v158, s[20:21]
	s_add_i32 m0, s22, 0x2000
	s_nop 0
	global_load_lds_dwordx4 v128, s[20:21]
	s_waitcnt vmcnt(6)
	s_setprio 1
	s_barrier
	v_mfma_f32_16x16x32_bf16 v[52:55], v[226:229], v[186:189], v[52:55]
	v_mfma_f32_16x16x32_bf16 v[48:51], v[234:237], v[186:189], v[48:51]
	v_mfma_f32_16x16x32_bf16 v[36:39], v[226:229], v[194:197], v[36:39]
	v_mfma_f32_16x16x32_bf16 v[32:35], v[234:237], v[194:197], v[32:35]
	v_mfma_f32_16x16x32_bf16 v[20:23], v[226:229], v[202:205], v[20:23]
	v_mfma_f32_16x16x32_bf16 v[16:19], v[234:237], v[202:205], v[16:19]
	v_mfma_f32_16x16x32_bf16 v[4:7], v[226:229], v[210:213], v[4:7]
	v_mfma_f32_16x16x32_bf16 v[0:3], v[234:237], v[210:213], v[0:3]
	v_mfma_f32_16x16x32_bf16 v[52:55], v[230:233], v[190:193], v[52:55]
	s_add_i32 s38, s38, 2
	v_mfma_f32_16x16x32_bf16 v[48:51], v[238:241], v[190:193], v[48:51]
	s_add_u32 s18, s18, 0x100
	v_mfma_f32_16x16x32_bf16 v[36:39], v[230:233], v[198:201], v[36:39]
	s_addc_u32 s19, s19, 0
	v_mfma_f32_16x16x32_bf16 v[32:35], v[238:241], v[198:201], v[32:35]
	s_add_u32 s33, s33, 0x100
	v_mfma_f32_16x16x32_bf16 v[20:23], v[230:233], v[206:209], v[20:23]
	s_addc_u32 s37, s37, 0
	v_mfma_f32_16x16x32_bf16 v[16:19], v[238:241], v[206:209], v[16:19]
	s_cmp_gt_u32 s38, 29
	v_mfma_f32_16x16x32_bf16 v[4:7], v[230:233], v[214:217], v[4:7]
	s_setprio 0
	v_mfma_f32_16x16x32_bf16 v[0:3], v[238:241], v[214:217], v[0:3]
	s_barrier
	s_cbranch_scc0 .LBB0_37
;     DI void operator()(const f32x4 (&acc)[2][2][4][2], const Unit& u, int wr, int wc, int fr, int fq) const {
;         const int row0 = u.pm * BM + wr * 64 + fr, col0 = u.pn * HALF + wc * 32 + 8 * fq;
; #pragma unroll
;         for (int ai = 0; ai < 2; ++ai)
; #pragma unroll
;             for (int m = 0; m < 4; ++m) { float hv[8];
; #pragma unroll
;                 for (int n = 0; n < 2; ++n)
; #pragma unroll
;                     for (int e = 0; e < 4; ++e) { const float gt = acc[ai][0][m][n][e], up = acc[ai][1][m][n][e];
;                         hv[n * 4 + e] = gt * __builtin_amdgcn_rcpf(1.f + __builtin_amdgcn_exp2f(-1.4426950408889634f * gt)) * up; }
;                 *(u32x4*)(H + (size_t)(row0 + ai * HALF + m * 16) * DFF + col0) = (u32x4){pk(hv[0], hv[1]), pk(hv[2], hv[3]), pk(hv[4], hv[5]), pk(hv[6], hv[7])}; }
;     }
	v_mul_f32_e32 v139, 0xbfb8aa3b, v124
	v_exp_f32_e32 v139, v139
	v_lshl_or_b32 v140, s2, 7, v136
	v_lshl_add_u32 v138, s3, 8, v134
	v_ashrrev_i32_e32 v141, 31, v140
	v_add_f32_e32 v139, 1.0, v139
	v_rcp_f32_e32 v142, v139
	v_mul_f32_e32 v139, 0xbfb8aa3b, v125
	v_exp_f32_e32 v139, v139
	s_movk_i32 s4, 0x2c00
	s_and_b64 vcc, exec, s[6:7]
	s_mov_b64 s[20:21], s[16:17]
	v_add_f32_e32 v139, 1.0, v139
	v_rcp_f32_e32 v143, v139
	v_mul_f32_e32 v139, 0xbfb8aa3b, v126
	v_exp_f32_e32 v139, v139
	s_mov_b64 s[18:19], s[14:15]
	v_pk_mul_f32 v[124:125], v[124:125], v[142:143]
	v_add_f32_e32 v139, 1.0, v139
	v_rcp_f32_e32 v144, v139
	v_mul_f32_e32 v139, 0xbfb8aa3b, v127
	v_exp_f32_e32 v139, v139
	v_pk_mul_f32 v[116:117], v[124:125], v[116:117]
	v_add_f32_e32 v139, 1.0, v139
	v_rcp_f32_e32 v145, v139
	v_mul_f32_e32 v139, 0xbfb8aa3b, v120
	v_exp_f32_e32 v139, v139
	v_cvt_pk_bf16_f32 v116, v116, v117
	v_pk_mul_f32 v[124:125], v[126:127], v[144:145]
	v_add_f32_e32 v139, 1.0, v139
	v_rcp_f32_e32 v146, v139
	v_mul_f32_e32 v139, 0xbfb8aa3b, v121
	v_exp_f32_e32 v139, v139
	v_pk_mul_f32 v[118:119], v[124:125], v[118:119]
	v_add_f32_e32 v139, 1.0, v139
	v_rcp_f32_e32 v147, v139
	v_mul_f32_e32 v139, 0xbfb8aa3b, v122
	v_exp_f32_e32 v139, v139
	v_cvt_pk_bf16_f32 v117, v118, v119
	v_pk_mul_f32 v[118:119], v[120:121], v[146:147]
	v_add_f32_e32 v139, 1.0, v139
	v_rcp_f32_e32 v148, v139
	v_mul_f32_e32 v139, 0xbfb8aa3b, v123
	v_exp_f32_e32 v139, v139
	v_pk_mul_f32 v[112:113], v[118:119], v[112:113]
	v_add_f32_e32 v139, 1.0, v139
	v_rcp_f32_e32 v149, v139
	v_cvt_pk_bf16_f32 v118, v112, v113
	v_pk_mul_f32 v[112:113], v[122:123], v[148:149]
	s_nop 0
	v_pk_mul_f32 v[112:113], v[112:113], v[114:115]
	v_lshlrev_b64 v[114:115], 1, v[140:141]
	v_cvt_pk_bf16_f32 v119, v112, v113
	v_mov_b64_e32 v[112:113], s[54:55]
	v_mad_i64_i32 v[120:121], s[2:3], v138, s4, v[112:113]
	v_lshl_add_u64 v[120:121], v[120:121], 0, v[114:115]
	global_store_dwordx4 v[120:121], v[116:119], off
	v_mul_f32_e32 v120, 0xbfb8aa3b, v104
	v_mul_f32_e32 v121, 0xbfb8aa3b, v105
	v_mul_f32_e32 v116, 0xbfb8aa3b, v108
	v_mul_f32_e32 v117, 0xbfb8aa3b, v109
	v_exp_f32_e32 v116, v116
	v_exp_f32_e32 v117, v117
	v_mul_f32_e32 v118, 0xbfb8aa3b, v110
	v_mul_f32_e32 v119, 0xbfb8aa3b, v111
	v_exp_f32_e32 v118, v118
	v_exp_f32_e32 v119, v119
	v_exp_f32_e32 v120, v120
	v_exp_f32_e32 v121, v121
	v_add_f32_e32 v116, 1.0, v116
	v_add_f32_e32 v117, 1.0, v117
	v_mul_f32_e32 v122, 0xbfb8aa3b, v106
	v_mul_f32_e32 v123, 0xbfb8aa3b, v107
	v_rcp_f32_e32 v116, v116
	v_rcp_f32_e32 v117, v117
	v_add_f32_e32 v118, 1.0, v118
	v_add_f32_e32 v119, 1.0, v119
	v_exp_f32_e32 v122, v122
	v_exp_f32_e32 v123, v123
	v_rcp_f32_e32 v118, v118
	v_rcp_f32_e32 v119, v119
	v_add_f32_e32 v120, 1.0, v120
	v_add_f32_e32 v121, 1.0, v121
	v_rcp_f32_e32 v120, v120
	v_rcp_f32_e32 v121, v121
	v_add_f32_e32 v122, 1.0, v122
	v_add_f32_e32 v123, 1.0, v123
	v_pk_mul_f32 v[108:109], v[108:109], v[116:117]
	v_rcp_f32_e32 v122, v122
	v_rcp_f32_e32 v123, v123
	v_pk_mul_f32 v[100:101], v[108:109], v[100:101]
	v_pk_mul_f32 v[108:109], v[110:111], v[118:119]
	v_cvt_pk_bf16_f32 v100, v100, v101
	v_pk_mul_f32 v[102:103], v[108:109], v[102:103]
	s_nop 0
	v_cvt_pk_bf16_f32 v101, v102, v103
	v_pk_mul_f32 v[102:103], v[104:105], v[120:121]
	s_nop 0
	v_pk_mul_f32 v[96:97], v[102:103], v[96:97]
	s_nop 0
	v_cvt_pk_bf16_f32 v102, v96, v97
	v_pk_mul_f32 v[96:97], v[106:107], v[122:123]
	s_nop 0
	v_pk_mul_f32 v[96:97], v[96:97], v[98:99]
	v_mul_f32_e32 v98, 0xbfb8aa3b, v94
	v_cvt_pk_bf16_f32 v103, v96, v97
	v_or_b32_e32 v96, 16, v138
	v_mad_i64_i32 v[96:97], s[2:3], v96, s4, v[112:113]
	v_lshl_add_u64 v[96:97], v[96:97], 0, v[114:115]
	global_store_dwordx4 v[96:97], v[100:103], off
	v_mul_f32_e32 v96, 0xbfb8aa3b, v92
	v_mul_f32_e32 v97, 0xbfb8aa3b, v93
	v_exp_f32_e32 v96, v96
	v_exp_f32_e32 v97, v97
	v_mul_f32_e32 v99, 0xbfb8aa3b, v95
	v_exp_f32_e32 v98, v98
	v_exp_f32_e32 v99, v99
	v_mul_f32_e32 v100, 0xbfb8aa3b, v88
	v_mul_f32_e32 v101, 0xbfb8aa3b, v89
	v_exp_f32_e32 v100, v100
	v_exp_f32_e32 v101, v101
	v_add_f32_e32 v96, 1.0, v96
	v_add_f32_e32 v97, 1.0, v97
	v_mul_f32_e32 v102, 0xbfb8aa3b, v90
	v_mul_f32_e32 v103, 0xbfb8aa3b, v91
	v_rcp_f32_e32 v96, v96
	v_rcp_f32_e32 v97, v97
	v_add_f32_e32 v98, 1.0, v98
	v_add_f32_e32 v99, 1.0, v99
	v_exp_f32_e32 v102, v102
	v_exp_f32_e32 v103, v103
	v_rcp_f32_e32 v98, v98
	v_rcp_f32_e32 v99, v99
	v_add_f32_e32 v100, 1.0, v100
	v_add_f32_e32 v101, 1.0, v101
	v_rcp_f32_e32 v100, v100
	v_rcp_f32_e32 v101, v101
	v_add_f32_e32 v102, 1.0, v102
	v_add_f32_e32 v103, 1.0, v103
	v_pk_mul_f32 v[92:93], v[92:93], v[96:97]
	v_rcp_f32_e32 v102, v102
	v_rcp_f32_e32 v103, v103
	v_pk_mul_f32 v[84:85], v[92:93], v[84:85]
	v_pk_mul_f32 v[92:93], v[94:95], v[98:99]
	v_cvt_pk_bf16_f32 v84, v84, v85
	v_pk_mul_f32 v[86:87], v[92:93], v[86:87]
	s_nop 0
	v_cvt_pk_bf16_f32 v85, v86, v87
	v_pk_mul_f32 v[86:87], v[88:89], v[100:101]
	s_nop 0
	v_pk_mul_f32 v[80:81], v[86:87], v[80:81]
	s_nop 0
	v_cvt_pk_bf16_f32 v86, v80, v81
	v_pk_mul_f32 v[80:81], v[90:91], v[102:103]
	s_nop 0
	v_pk_mul_f32 v[80:81], v[80:81], v[82:83]
	v_mul_f32_e32 v82, 0xbfb8aa3b, v78
	v_cvt_pk_bf16_f32 v87, v80, v81
	v_or_b32_e32 v80, 32, v138
	v_mad_i64_i32 v[80:81], s[2:3], v80, s4, v[112:113]
	v_lshl_add_u64 v[80:81], v[80:81], 0, v[114:115]
	global_store_dwordx4 v[80:81], v[84:87], off
	v_mul_f32_e32 v80, 0xbfb8aa3b, v76
	v_mul_f32_e32 v81, 0xbfb8aa3b, v77
	v_exp_f32_e32 v80, v80
	v_exp_f32_e32 v81, v81
	v_mul_f32_e32 v83, 0xbfb8aa3b, v79
	v_exp_f32_e32 v82, v82
	v_exp_f32_e32 v83, v83
	v_mul_f32_e32 v84, 0xbfb8aa3b, v72
	v_mul_f32_e32 v85, 0xbfb8aa3b, v73
	v_exp_f32_e32 v84, v84
	v_exp_f32_e32 v85, v85
;     DI void operator()(const f32x4 (&acc)[2][2][4][2], const Unit& u, int wr, int wc, int fr, int fq) const {
;         const int row0 = u.pm * BM + wr * 64 + fr, col0 = u.pn * HALF + wc * 32 + 8 * fq;
; #pragma unroll
;         for (int ai = 0; ai < 2; ++ai)
; #pragma unroll
;             for (int m = 0; m < 4; ++m) { float hv[8];
; #pragma unroll
;                 for (int n = 0; n < 2; ++n)
; #pragma unroll
;                     for (int e = 0; e < 4; ++e) { const float gt = acc[ai][0][m][n][e], up = acc[ai][1][m][n][e];
;                         hv[n * 4 + e] = gt * __builtin_amdgcn_rcpf(1.f + __builtin_amdgcn_exp2f(-1.4426950408889634f * gt)) * up; }
;                 *(u32x4*)(H + (size_t)(row0 + ai * HALF + m * 16) * DFF + col0) = (u32x4){pk(hv[0], hv[1]), pk(hv[2], hv[3]), pk(hv[4], hv[5]), pk(hv[6], hv[7])}; }
;     }
	v_add_f32_e32 v80, 1.0, v80
	v_add_f32_e32 v81, 1.0, v81
	v_mul_f32_e32 v86, 0xbfb8aa3b, v74
	v_mul_f32_e32 v87, 0xbfb8aa3b, v75
	v_rcp_f32_e32 v80, v80
	v_rcp_f32_e32 v81, v81
	v_add_f32_e32 v82, 1.0, v82
	v_add_f32_e32 v83, 1.0, v83
	v_exp_f32_e32 v86, v86
	v_exp_f32_e32 v87, v87
	v_rcp_f32_e32 v82, v82
	v_rcp_f32_e32 v83, v83
	v_add_f32_e32 v84, 1.0, v84
	v_add_f32_e32 v85, 1.0, v85
	v_rcp_f32_e32 v84, v84
	v_rcp_f32_e32 v85, v85
	v_add_f32_e32 v86, 1.0, v86
	v_add_f32_e32 v87, 1.0, v87
	v_pk_mul_f32 v[76:77], v[76:77], v[80:81]
	v_rcp_f32_e32 v86, v86
	v_rcp_f32_e32 v87, v87
	v_pk_mul_f32 v[68:69], v[76:77], v[68:69]
	v_pk_mul_f32 v[76:77], v[78:79], v[82:83]
	v_cvt_pk_bf16_f32 v68, v68, v69
	v_pk_mul_f32 v[70:71], v[76:77], v[70:71]
	s_nop 0
	v_cvt_pk_bf16_f32 v69, v70, v71
	v_pk_mul_f32 v[70:71], v[72:73], v[84:85]
	v_add_u32_e32 v72, 0x80, v138
	v_pk_mul_f32 v[64:65], v[70:71], v[64:65]
	s_nop 0
	v_cvt_pk_bf16_f32 v70, v64, v65
	v_pk_mul_f32 v[64:65], v[74:75], v[86:87]
	s_nop 0
	v_pk_mul_f32 v[64:65], v[64:65], v[66:67]
	v_mul_f32_e32 v66, 0xbfb8aa3b, v62
	v_cvt_pk_bf16_f32 v71, v64, v65
	v_or_b32_e32 v64, 48, v138
	v_mad_i64_i32 v[64:65], s[2:3], v64, s4, v[112:113]
	v_lshl_add_u64 v[64:65], v[64:65], 0, v[114:115]
	global_store_dwordx4 v[64:65], v[68:71], off
	v_mul_f32_e32 v64, 0xbfb8aa3b, v60
	v_mul_f32_e32 v65, 0xbfb8aa3b, v61
	v_exp_f32_e32 v64, v64
	v_exp_f32_e32 v65, v65
	v_mul_f32_e32 v67, 0xbfb8aa3b, v63
	v_exp_f32_e32 v66, v66
	v_exp_f32_e32 v67, v67
	v_mul_f32_e32 v68, 0xbfb8aa3b, v56
	v_mul_f32_e32 v69, 0xbfb8aa3b, v57
	v_exp_f32_e32 v68, v68
	v_exp_f32_e32 v69, v69
	v_add_f32_e32 v64, 1.0, v64
	v_add_f32_e32 v65, 1.0, v65
	v_mul_f32_e32 v70, 0xbfb8aa3b, v58
	v_mul_f32_e32 v71, 0xbfb8aa3b, v59
	v_rcp_f32_e32 v64, v64
	v_rcp_f32_e32 v65, v65
	v_add_f32_e32 v66, 1.0, v66
	v_add_f32_e32 v67, 1.0, v67
	v_exp_f32_e32 v70, v70
	v_exp_f32_e32 v71, v71
	v_rcp_f32_e32 v66, v66
	v_rcp_f32_e32 v67, v67
	v_add_f32_e32 v68, 1.0, v68
	v_add_f32_e32 v69, 1.0, v69
	v_rcp_f32_e32 v68, v68
	v_rcp_f32_e32 v69, v69
	v_add_f32_e32 v70, 1.0, v70
	v_add_f32_e32 v71, 1.0, v71
	v_pk_mul_f32 v[60:61], v[60:61], v[64:65]
	v_rcp_f32_e32 v70, v70
	v_rcp_f32_e32 v71, v71
	v_pk_mul_f32 v[52:53], v[60:61], v[52:53]
	v_pk_mul_f32 v[60:61], v[62:63], v[66:67]
	v_cvt_pk_bf16_f32 v52, v52, v53
	v_pk_mul_f32 v[54:55], v[60:61], v[54:55]
	s_nop 0
	v_cvt_pk_bf16_f32 v53, v54, v55
	v_pk_mul_f32 v[54:55], v[56:57], v[68:69]
	s_nop 0
	v_pk_mul_f32 v[48:49], v[54:55], v[48:49]
	s_nop 0
	v_cvt_pk_bf16_f32 v54, v48, v49
	v_pk_mul_f32 v[48:49], v[58:59], v[70:71]
	s_nop 0
	v_pk_mul_f32 v[48:49], v[48:49], v[50:51]
	v_mul_f32_e32 v50, 0xbfb8aa3b, v46
	v_cvt_pk_bf16_f32 v55, v48, v49
	v_mad_i64_i32 v[48:49], s[2:3], v72, s4, v[112:113]
	v_lshl_add_u64 v[48:49], v[48:49], 0, v[114:115]
	global_store_dwordx4 v[48:49], v[52:55], off
	v_mul_f32_e32 v48, 0xbfb8aa3b, v44
	v_mul_f32_e32 v49, 0xbfb8aa3b, v45
	v_exp_f32_e32 v48, v48
	v_exp_f32_e32 v49, v49
	v_mul_f32_e32 v51, 0xbfb8aa3b, v47
	v_exp_f32_e32 v50, v50
	v_exp_f32_e32 v51, v51
	v_mul_f32_e32 v52, 0xbfb8aa3b, v40
	v_mul_f32_e32 v53, 0xbfb8aa3b, v41
	v_exp_f32_e32 v52, v52
	v_exp_f32_e32 v53, v53
	v_add_f32_e32 v48, 1.0, v48
	v_add_f32_e32 v49, 1.0, v49
	v_mul_f32_e32 v54, 0xbfb8aa3b, v42
	v_mul_f32_e32 v55, 0xbfb8aa3b, v43
	v_rcp_f32_e32 v48, v48
	v_rcp_f32_e32 v49, v49
	v_add_f32_e32 v50, 1.0, v50
	v_add_f32_e32 v51, 1.0, v51
	v_exp_f32_e32 v54, v54
	v_exp_f32_e32 v55, v55
	v_rcp_f32_e32 v50, v50
	v_rcp_f32_e32 v51, v51
	v_add_f32_e32 v52, 1.0, v52
	v_add_f32_e32 v53, 1.0, v53
	v_rcp_f32_e32 v52, v52
	v_rcp_f32_e32 v53, v53
	v_add_f32_e32 v54, 1.0, v54
	v_add_f32_e32 v55, 1.0, v55
	v_pk_mul_f32 v[44:45], v[44:45], v[48:49]
	v_rcp_f32_e32 v54, v54
	v_rcp_f32_e32 v55, v55
	v_pk_mul_f32 v[36:37], v[44:45], v[36:37]
	v_pk_mul_f32 v[44:45], v[46:47], v[50:51]
; #define PG8_WAIT_V(n) asm volatile("s_waitcnt vmcnt(" #n ")" ::: "memory")
; #define PG8_BAR __builtin_amdgcn_s_barrier()
; template <class Epi>
; DI void gemm_phase(LAS unsigned char* lds, const Gemm g, const StaticOrder& S, const Epi& E) {
;     ...
;     PG8_WAIT_V(0);
;     if (wr == 0) PG8_BAR;
;     PG8_BAR;
;     DI void operator()(const f32x4 (&acc)[2][2][4][2], const Unit& u, int wr, int wc, int fr, int fq) const {
;         const int row0 = u.pm * BM + wr * 64 + fr, col0 = u.pn * HALF + wc * 32 + 8 * fq;
; #pragma unroll
;         for (int ai = 0; ai < 2; ++ai)
; #pragma unroll
;             for (int m = 0; m < 4; ++m) { float hv[8];
; #pragma unroll
;                 for (int n = 0; n < 2; ++n)
; #pragma unroll
;                     for (int e = 0; e < 4; ++e) { const float gt = acc[ai][0][m][n][e], up = acc[ai][1][m][n][e];
;                         hv[n * 4 + e] = gt * __builtin_amdgcn_rcpf(1.f + __builtin_amdgcn_exp2f(-1.4426950408889634f * gt)) * up; }
;                 *(u32x4*)(H + (size_t)(row0 + ai * HALF + m * 16) * DFF + col0) = (u32x4){pk(hv[0], hv[1]), pk(hv[2], hv[3]), pk(hv[4], hv[5]), pk(hv[6], hv[7])}; }
;     }
	v_cvt_pk_bf16_f32 v36, v36, v37
	v_pk_mul_f32 v[38:39], v[44:45], v[38:39]
	s_nop 0
	v_cvt_pk_bf16_f32 v37, v38, v39
	v_pk_mul_f32 v[38:39], v[40:41], v[52:53]
	s_nop 0
	v_pk_mul_f32 v[32:33], v[38:39], v[32:33]
	s_nop 0
	v_cvt_pk_bf16_f32 v38, v32, v33
	v_pk_mul_f32 v[32:33], v[42:43], v[54:55]
	s_nop 0
	v_pk_mul_f32 v[32:33], v[32:33], v[34:35]
	v_mul_f32_e32 v34, 0xbfb8aa3b, v30
	v_cvt_pk_bf16_f32 v39, v32, v33
	v_add_u32_e32 v32, 0x90, v138
	v_mad_i64_i32 v[32:33], s[2:3], v32, s4, v[112:113]
	v_lshl_add_u64 v[32:33], v[32:33], 0, v[114:115]
	global_store_dwordx4 v[32:33], v[36:39], off
	v_mul_f32_e32 v32, 0xbfb8aa3b, v28
	v_mul_f32_e32 v33, 0xbfb8aa3b, v29
	v_exp_f32_e32 v32, v32
	v_exp_f32_e32 v33, v33
	v_mul_f32_e32 v35, 0xbfb8aa3b, v31
	v_exp_f32_e32 v34, v34
	v_exp_f32_e32 v35, v35
	v_mul_f32_e32 v36, 0xbfb8aa3b, v24
	v_mul_f32_e32 v37, 0xbfb8aa3b, v25
	v_exp_f32_e32 v36, v36
	v_exp_f32_e32 v37, v37
	v_add_f32_e32 v32, 1.0, v32
	v_add_f32_e32 v33, 1.0, v33
	v_mul_f32_e32 v38, 0xbfb8aa3b, v26
	v_mul_f32_e32 v39, 0xbfb8aa3b, v27
	v_rcp_f32_e32 v32, v32
	v_rcp_f32_e32 v33, v33
	v_add_f32_e32 v34, 1.0, v34
	v_add_f32_e32 v35, 1.0, v35
	v_exp_f32_e32 v38, v38
	v_exp_f32_e32 v39, v39
	v_rcp_f32_e32 v34, v34
	v_rcp_f32_e32 v35, v35
	v_add_f32_e32 v36, 1.0, v36
	v_add_f32_e32 v37, 1.0, v37
	v_rcp_f32_e32 v36, v36
	v_rcp_f32_e32 v37, v37
	v_add_f32_e32 v38, 1.0, v38
	v_add_f32_e32 v39, 1.0, v39
	v_pk_mul_f32 v[28:29], v[28:29], v[32:33]
	v_rcp_f32_e32 v38, v38
	v_rcp_f32_e32 v39, v39
	v_pk_mul_f32 v[20:21], v[28:29], v[20:21]
	v_pk_mul_f32 v[28:29], v[30:31], v[34:35]
	v_cvt_pk_bf16_f32 v20, v20, v21
	v_pk_mul_f32 v[22:23], v[28:29], v[22:23]
	s_nop 0
	v_cvt_pk_bf16_f32 v21, v22, v23
	v_pk_mul_f32 v[22:23], v[24:25], v[36:37]
	s_nop 0
	v_pk_mul_f32 v[16:17], v[22:23], v[16:17]
	s_nop 0
	v_cvt_pk_bf16_f32 v22, v16, v17
	v_pk_mul_f32 v[16:17], v[26:27], v[38:39]
	s_nop 0
	v_pk_mul_f32 v[16:17], v[16:17], v[18:19]
	v_mul_f32_e32 v18, 0xbfb8aa3b, v14
	v_cvt_pk_bf16_f32 v23, v16, v17
	v_add_u32_e32 v16, 0xa0, v138
	v_mad_i64_i32 v[16:17], s[2:3], v16, s4, v[112:113]
	v_lshl_add_u64 v[16:17], v[16:17], 0, v[114:115]
	global_store_dwordx4 v[16:17], v[20:23], off
	v_mul_f32_e32 v16, 0xbfb8aa3b, v12
	v_mul_f32_e32 v17, 0xbfb8aa3b, v13
	v_exp_f32_e32 v16, v16
	v_exp_f32_e32 v17, v17
	v_mul_f32_e32 v19, 0xbfb8aa3b, v15
	v_exp_f32_e32 v18, v18
	v_exp_f32_e32 v19, v19
	v_mul_f32_e32 v20, 0xbfb8aa3b, v8
	v_mul_f32_e32 v21, 0xbfb8aa3b, v9
	v_exp_f32_e32 v20, v20
	v_exp_f32_e32 v21, v21
	v_add_f32_e32 v16, 1.0, v16
	v_add_f32_e32 v17, 1.0, v17
	v_mul_f32_e32 v22, 0xbfb8aa3b, v10
	v_mul_f32_e32 v23, 0xbfb8aa3b, v11
	v_rcp_f32_e32 v16, v16
	v_rcp_f32_e32 v17, v17
	v_add_f32_e32 v18, 1.0, v18
	v_add_f32_e32 v19, 1.0, v19
	v_exp_f32_e32 v22, v22
	v_exp_f32_e32 v23, v23
	v_rcp_f32_e32 v18, v18
	v_rcp_f32_e32 v19, v19
	v_add_f32_e32 v20, 1.0, v20
	v_add_f32_e32 v21, 1.0, v21
	v_rcp_f32_e32 v20, v20
	v_rcp_f32_e32 v21, v21
	v_add_f32_e32 v22, 1.0, v22
	v_add_f32_e32 v23, 1.0, v23
	v_pk_mul_f32 v[12:13], v[12:13], v[16:17]
	v_rcp_f32_e32 v22, v22
	v_rcp_f32_e32 v23, v23
	v_pk_mul_f32 v[4:5], v[12:13], v[4:5]
	v_pk_mul_f32 v[12:13], v[14:15], v[18:19]
	v_cvt_pk_bf16_f32 v4, v4, v5
	v_pk_mul_f32 v[6:7], v[12:13], v[6:7]
	s_nop 0
	v_cvt_pk_bf16_f32 v5, v6, v7
	v_pk_mul_f32 v[6:7], v[8:9], v[20:21]
	s_nop 0
	v_pk_mul_f32 v[0:1], v[6:7], v[0:1]
	s_nop 0
	v_cvt_pk_bf16_f32 v6, v0, v1
	v_pk_mul_f32 v[0:1], v[10:11], v[22:23]
	s_nop 0
	v_pk_mul_f32 v[0:1], v[0:1], v[2:3]
	s_nop 0
	v_cvt_pk_bf16_f32 v7, v0, v1
	v_add_u32_e32 v0, 0xb0, v138
	v_mad_i64_i32 v[0:1], s[2:3], v0, s4, v[112:113]
	v_lshl_add_u64 v[0:1], v[0:1], 0, v[114:115]
	s_mov_b32 s2, s8
	s_mov_b32 s3, s10
	global_store_dwordx4 v[0:1], v[4:7], off
	s_cbranch_vccz .LBB0_34
	s_waitcnt vmcnt(0)
	s_cmpk_gt_u32 s24, 0xff
	s_cbranch_scc1 .LBB0_41
	s_barrier

; #define PG8_STAGE(bufoff, gbase) do { _Pragma("unroll") for (int _i = 0; _i < 2; ++_i) \
;         __builtin_amdgcn_global_load_lds((const unsigned*)((const char*)(gbase) + voff[_i]), (LAS unsigned*)(lds + (bufoff) + ldsw + _i * 8192), 16, 0, 0); } while (0)
; #define PG8_LDA(dst, b, h) do { _Pragma("unroll") for (int m = 0; m < 4; ++m) _Pragma("unroll") for (int k = 0; k < 2; ++k) dst[m][k] = *(const LAS bf16x8*)(lds + PG8_SA(b, h) + aoff + m * 2048 + k * 1024); } while (0)
; #define PG8_LDB(dst, b, h) do { _Pragma("unroll") for (int n = 0; n < 2; ++n) _Pragma("unroll") for (int k = 0; k < 2; ++k) dst[n][k] = *(const LAS bf16x8*)(lds + PG8_SB(b, h) + boff + n * 2048 + k * 1024); } while (0)
; #define PG8_MMA(ai, bj, At, Bt) do { __builtin_amdgcn_s_setprio(1); _Pragma("unroll") for (int m = 0; m < 4; ++m) _Pragma("unroll") for (int n = 0; n < 2; ++n) _Pragma("unroll") for (int k = 0; k < 2; ++k) \
;         acc[ai][bj][m][n] = __builtin_amdgcn_mfma_f32_16x16x32_bf16(Bt[n][k], At[m][k], acc[ai][bj][m][n], 0, 0, 0); __builtin_amdgcn_s_setprio(0); } while (0)
; #define PG8_WAIT_L(n) asm volatile("s_waitcnt lgkmcnt(" #n ")" ::: "memory")
; #define PG8_BAR __builtin_amdgcn_s_barrier()
; #define PG8_SCHED __builtin_amdgcn_sched_barrier(0)
; template <class Epi>
; DI void gemm_phase(LAS unsigned char* lds, const Gemm g, const StaticOrder& S, const Epi& E) {
;     ...
;         for (int t = 0; t < nt; t += 2) {
;             const bool last = (t == nt - 2);
;             const char* a1 = cA + (size_t)(t + 1) * kstep;
;             const char* a2 = last ? nA : cA + (size_t)(t + 2) * kstep; const char* b2 = last ? nB : cB + (size_t)(t + 2) * kstep;
;             const char* a3 = a2 + kstep; const char* b3 = b2 + kstep;
;             PG8_LDB(B0, 0, 0); PG8_SCHED; PG8_LDA(At, 0, 0); PG8_STAGE(PG8_SA(1, 1), a1 + hstep);
;             PG8_WAIT_L(8); PG8_BAR; PG8_WAIT_L(0); PG8_MMA(0, 0, At, B0); PG8_BAR; PG8_SCHED;
;             PG8_LDB(B1, 0, 1); PG8_STAGE(PG8_SB(0, 0), b2);
;             PG8_BAR; PG8_WAIT_L(0); PG8_MMA(0, 1, At, B1); PG8_BAR;
;             PG8_LDA(At, 0, 1); PG8_STAGE(PG8_SA(0, 0), a2);
;             PG8_BAR; PG8_WAIT_L(0); PG8_MMA(1, 0, At, B0); PG8_BAR; PG8_SCHED;
.LBB0_77:
	ds_read_b128 v[128:131], v226
	ds_read_b128 v[132:135], v226 offset:1024
	ds_read_b128 v[136:139], v226 offset:2048
	ds_read_b128 v[140:143], v226 offset:3072
	ds_read_b128 v[144:147], v228
	ds_read_b128 v[148:151], v228 offset:1024
	ds_read_b128 v[152:155], v228 offset:2048
	ds_read_b128 v[194:197], v228 offset:3072
	ds_read_b128 v[198:201], v228 offset:4096
	ds_read_b128 v[202:205], v228 offset:5120
	ds_read_b128 v[206:209], v228 offset:6144
	ds_read_b128 v[210:213], v228 offset:7168
	s_add_u32 s22, s20, 0x100
	s_addc_u32 s23, s21, 0
	s_add_i32 s43, 0, 0x10000
	s_cmp_eq_u32 s33, 32
	s_cselect_b32 s27, s9, s23
	s_cselect_b32 s26, s8, s22
	s_cselect_b32 s25, s11, s5
	s_cselect_b32 s24, s10, s4
	s_add_i32 m0, s34, 0xc000
	s_nop 0
	global_load_lds_dwordx4 v190, s[20:21]
	s_add_i32 m0, s34, 0xe000
	s_nop 0
	global_load_lds_dwordx4 v192, s[20:21]
	s_waitcnt lgkmcnt(8)
	s_setprio 1
	s_barrier
	s_waitcnt lgkmcnt(0)
	v_mfma_f32_16x16x32_bf16 v[124:127], v[128:131], v[144:147], v[124:127]
	v_mfma_f32_16x16x32_bf16 v[120:123], v[136:139], v[144:147], v[120:123]
	v_mfma_f32_16x16x32_bf16 v[116:119], v[128:131], v[152:155], v[116:119]
	v_mfma_f32_16x16x32_bf16 v[112:115], v[136:139], v[152:155], v[112:115]
	v_mfma_f32_16x16x32_bf16 v[108:111], v[128:131], v[198:201], v[108:111]
	v_mfma_f32_16x16x32_bf16 v[104:107], v[136:139], v[198:201], v[104:107]
	v_mfma_f32_16x16x32_bf16 v[100:103], v[128:131], v[206:209], v[100:103]
	v_mfma_f32_16x16x32_bf16 v[96:99], v[136:139], v[206:209], v[96:99]
	v_mfma_f32_16x16x32_bf16 v[124:127], v[132:135], v[148:151], v[124:127]
	v_mfma_f32_16x16x32_bf16 v[120:123], v[140:143], v[148:151], v[120:123]
	v_mfma_f32_16x16x32_bf16 v[116:119], v[132:135], v[194:197], v[116:119]
	v_mfma_f32_16x16x32_bf16 v[112:115], v[140:143], v[194:197], v[112:115]
	v_mfma_f32_16x16x32_bf16 v[108:111], v[132:135], v[202:205], v[108:111]
	v_mfma_f32_16x16x32_bf16 v[104:107], v[140:143], v[202:205], v[104:107]
	v_mfma_f32_16x16x32_bf16 v[100:103], v[132:135], v[210:213], v[100:103]
	s_setprio 0
	v_mfma_f32_16x16x32_bf16 v[96:99], v[140:143], v[210:213], v[96:99]
	s_barrier
	ds_read_b128 v[214:217], v226 offset:16384
	ds_read_b128 v[230:233], v226 offset:17408
	ds_read_b128 v[234:237], v226 offset:18432
	ds_read_b128 v[238:241], v226 offset:19456
	s_add_i32 s44, 0, 0x14000
	s_add_i32 s20, s43, s31
	s_mov_b32 m0, s20
	s_nop 0
	global_load_lds_dwordx4 v188, s[24:25]
	s_add_i32 m0, s20, 0x2000
	s_nop 0
	global_load_lds_dwordx4 v186, s[24:25]
	s_waitcnt lgkmcnt(0)
	s_setprio 1
	s_barrier
	v_mfma_f32_16x16x32_bf16 v[60:63], v[214:217], v[144:147], v[60:63]
	v_mfma_f32_16x16x32_bf16 v[56:59], v[234:237], v[144:147], v[56:59]
	v_mfma_f32_16x16x32_bf16 v[52:55], v[214:217], v[152:155], v[52:55]
	v_mfma_f32_16x16x32_bf16 v[48:51], v[234:237], v[152:155], v[48:51]
	v_mfma_f32_16x16x32_bf16 v[44:47], v[214:217], v[198:201], v[44:47]
	v_mfma_f32_16x16x32_bf16 v[40:43], v[234:237], v[198:201], v[40:43]
	v_mfma_f32_16x16x32_bf16 v[36:39], v[214:217], v[206:209], v[36:39]
	v_mfma_f32_16x16x32_bf16 v[32:35], v[234:237], v[206:209], v[32:35]
	v_mfma_f32_16x16x32_bf16 v[60:63], v[230:233], v[148:151], v[60:63]
	s_mov_b32 m0, s34
	v_mfma_f32_16x16x32_bf16 v[56:59], v[238:241], v[148:151], v[56:59]
	v_mfma_f32_16x16x32_bf16 v[52:55], v[230:233], v[194:197], v[52:55]
	v_mfma_f32_16x16x32_bf16 v[48:51], v[238:241], v[194:197], v[48:51]
	v_mfma_f32_16x16x32_bf16 v[44:47], v[230:233], v[202:205], v[44:47]
	v_mfma_f32_16x16x32_bf16 v[40:43], v[238:241], v[202:205], v[40:43]
	v_mfma_f32_16x16x32_bf16 v[36:39], v[230:233], v[210:213], v[36:39]
	s_setprio 0
	v_mfma_f32_16x16x32_bf16 v[32:35], v[238:241], v[210:213], v[32:35]
	s_barrier
	ds_read_b128 v[144:147], v228 offset:16384
	ds_read_b128 v[148:151], v228 offset:17408
	ds_read_b128 v[152:155], v228 offset:18432
	ds_read_b128 v[194:197], v228 offset:19456
	ds_read_b128 v[198:201], v228 offset:20480
	ds_read_b128 v[202:205], v228 offset:21504
	ds_read_b128 v[206:209], v228 offset:22528
	ds_read_b128 v[210:213], v228 offset:23552
	global_load_lds_dwordx4 v188, s[26:27]
	s_mov_b64 s[100:101], s[26:27]
	s_mov_b32 m0, s35
	s_nop 0
	global_load_lds_dwordx4 v186, s[26:27]
	s_waitcnt lgkmcnt(0)
	s_setprio 1
	s_barrier
	v_mfma_f32_16x16x32_bf16 v[92:95], v[128:131], v[144:147], v[92:95]
	v_mfma_f32_16x16x32_bf16 v[88:91], v[136:139], v[144:147], v[88:91]
	v_mfma_f32_16x16x32_bf16 v[84:87], v[128:131], v[152:155], v[84:87]
	v_mfma_f32_16x16x32_bf16 v[80:83], v[136:139], v[152:155], v[80:83]
	v_mfma_f32_16x16x32_bf16 v[76:79], v[128:131], v[198:201], v[76:79]
	v_mfma_f32_16x16x32_bf16 v[72:75], v[136:139], v[198:201], v[72:75]
	v_mfma_f32_16x16x32_bf16 v[68:71], v[128:131], v[206:209], v[68:71]
	v_mfma_f32_16x16x32_bf16 v[64:67], v[136:139], v[206:209], v[64:67]
	v_mfma_f32_16x16x32_bf16 v[92:95], v[132:135], v[148:151], v[92:95]
	v_mfma_f32_16x16x32_bf16 v[88:91], v[140:143], v[148:151], v[88:91]
	v_mfma_f32_16x16x32_bf16 v[84:87], v[132:135], v[194:197], v[84:87]
	v_mfma_f32_16x16x32_bf16 v[80:83], v[140:143], v[194:197], v[80:83]
	v_mfma_f32_16x16x32_bf16 v[76:79], v[132:135], v[202:205], v[76:79]
	v_mfma_f32_16x16x32_bf16 v[72:75], v[140:143], v[202:205], v[72:75]
	v_mfma_f32_16x16x32_bf16 v[68:71], v[132:135], v[210:213], v[68:71]
	s_setprio 0
	v_mfma_f32_16x16x32_bf16 v[64:67], v[140:143], v[210:213], v[64:67]
	s_barrier
	s_add_u32 s20, s24, 0x90000
	s_addc_u32 s21, s25, 0
	s_add_i32 s43, s44, s31
	s_mov_b32 m0, s43
	s_nop 0
	global_load_lds_dwordx4 v188, s[20:21]
	s_add_i32 m0, s43, 0x2000
	s_nop 0
	global_load_lds_dwordx4 v186, s[20:21]
	s_waitcnt vmcnt(6)
	s_setprio 1
	s_barrier
; #define PG8_STAGE(bufoff, gbase) do { _Pragma("unroll") for (int _i = 0; _i < 2; ++_i) \
;         __builtin_amdgcn_global_load_lds((const unsigned*)((const char*)(gbase) + voff[_i]), (LAS unsigned*)(lds + (bufoff) + ldsw + _i * 8192), 16, 0, 0); } while (0)
; #define PG8_LDA(dst, b, h) do { _Pragma("unroll") for (int m = 0; m < 4; ++m) _Pragma("unroll") for (int k = 0; k < 2; ++k) dst[m][k] = *(const LAS bf16x8*)(lds + PG8_SA(b, h) + aoff + m * 2048 + k * 1024); } while (0)
; #define PG8_LDB(dst, b, h) do { _Pragma("unroll") for (int n = 0; n < 2; ++n) _Pragma("unroll") for (int k = 0; k < 2; ++k) dst[n][k] = *(const LAS bf16x8*)(lds + PG8_SB(b, h) + boff + n * 2048 + k * 1024); } while (0)
; #define PG8_MMA(ai, bj, At, Bt) do { __builtin_amdgcn_s_setprio(1); _Pragma("unroll") for (int m = 0; m < 4; ++m) _Pragma("unroll") for (int n = 0; n < 2; ++n) _Pragma("unroll") for (int k = 0; k < 2; ++k) \
;         acc[ai][bj][m][n] = __builtin_amdgcn_mfma_f32_16x16x32_bf16(Bt[n][k], At[m][k], acc[ai][bj][m][n], 0, 0, 0); __builtin_amdgcn_s_setprio(0); } while (0)
; #define PG8_WAIT_V(n) asm volatile("s_waitcnt vmcnt(" #n ")" ::: "memory")
; #define PG8_WAIT_L(n) asm volatile("s_waitcnt lgkmcnt(" #n ")" ::: "memory")
; #define PG8_BAR __builtin_amdgcn_s_barrier()
; #define PG8_SCHED __builtin_amdgcn_sched_barrier(0)
; template <class Epi>
; DI void gemm_phase(LAS unsigned char* lds, const Gemm g, const StaticOrder& S, const Epi& E) {
;     ...
;             PG8_WAIT_V(6); PG8_BAR; PG8_MMA(1, 1, At, B1); PG8_BAR;
;             PG8_LDB(B0, 1, 0); PG8_SCHED; PG8_LDA(At, 1, 0); PG8_STAGE(PG8_SA(0, 1), a2 + hstep);
;             PG8_WAIT_L(8); PG8_BAR; PG8_WAIT_L(0); PG8_MMA(0, 0, At, B0); PG8_BAR; PG8_SCHED;
;             PG8_LDB(B1, 1, 1); PG8_STAGE(PG8_SB(1, 0), b3);
;             PG8_BAR; PG8_WAIT_L(0); PG8_MMA(0, 1, At, B1); PG8_BAR;
;             PG8_LDA(At, 1, 1); PG8_STAGE(PG8_SA(1, 0), a3);
;             PG8_BAR; PG8_WAIT_L(0); PG8_MMA(1, 0, At, B0); PG8_BAR; PG8_SCHED;
	v_mfma_f32_16x16x32_bf16 v[28:31], v[214:217], v[144:147], v[28:31]
	v_mfma_f32_16x16x32_bf16 v[24:27], v[234:237], v[144:147], v[24:27]
	v_mfma_f32_16x16x32_bf16 v[20:23], v[214:217], v[152:155], v[20:23]
	v_mfma_f32_16x16x32_bf16 v[16:19], v[234:237], v[152:155], v[16:19]
	v_mfma_f32_16x16x32_bf16 v[12:15], v[214:217], v[198:201], v[12:15]
	v_mfma_f32_16x16x32_bf16 v[8:11], v[234:237], v[198:201], v[8:11]
	v_mfma_f32_16x16x32_bf16 v[4:7], v[214:217], v[206:209], v[4:7]
	v_mfma_f32_16x16x32_bf16 v[0:3], v[234:237], v[206:209], v[0:3]
	v_mfma_f32_16x16x32_bf16 v[28:31], v[230:233], v[148:151], v[28:31]
	s_add_i32 s43, 0, 0x18000
	v_mfma_f32_16x16x32_bf16 v[24:27], v[238:241], v[148:151], v[24:27]
	v_mfma_f32_16x16x32_bf16 v[20:23], v[230:233], v[194:197], v[20:23]
	v_mfma_f32_16x16x32_bf16 v[16:19], v[238:241], v[194:197], v[16:19]
	v_mfma_f32_16x16x32_bf16 v[12:15], v[230:233], v[202:205], v[12:15]
	v_mfma_f32_16x16x32_bf16 v[8:11], v[238:241], v[202:205], v[8:11]
	v_mfma_f32_16x16x32_bf16 v[4:7], v[230:233], v[210:213], v[4:7]
	s_setprio 0
	v_mfma_f32_16x16x32_bf16 v[0:3], v[238:241], v[210:213], v[0:3]
	s_barrier
	ds_read_b128 v[128:131], v226 offset:32768
	ds_read_b128 v[132:135], v226 offset:33792
	ds_read_b128 v[136:139], v226 offset:34816
	ds_read_b128 v[140:143], v226 offset:35840
	ds_read_b128 v[144:147], v228 offset:32768
	ds_read_b128 v[148:151], v228 offset:33792
	ds_read_b128 v[152:155], v228 offset:34816
	ds_read_b128 v[194:197], v228 offset:35840
	ds_read_b128 v[198:201], v228 offset:36864
	ds_read_b128 v[202:205], v228 offset:37888
	ds_read_b128 v[206:209], v228 offset:38912
	ds_read_b128 v[210:213], v228 offset:39936
	s_add_u32 s20, s26, 0x90000
	s_addc_u32 s21, s27, 0
	s_mov_b32 m0, s36
	s_nop 0
	global_load_lds_dwordx4 v188, s[20:21]
	s_mov_b32 m0, s37
	s_nop 0
	global_load_lds_dwordx4 v186, s[20:21]
	s_waitcnt lgkmcnt(8)
	s_setprio 1
	s_barrier
	s_waitcnt lgkmcnt(0)
	v_mfma_f32_16x16x32_bf16 v[124:127], v[128:131], v[144:147], v[124:127]
	v_mfma_f32_16x16x32_bf16 v[120:123], v[136:139], v[144:147], v[120:123]
	v_mfma_f32_16x16x32_bf16 v[116:119], v[128:131], v[152:155], v[116:119]
	v_mfma_f32_16x16x32_bf16 v[112:115], v[136:139], v[152:155], v[112:115]
	v_mfma_f32_16x16x32_bf16 v[108:111], v[128:131], v[198:201], v[108:111]
	v_mfma_f32_16x16x32_bf16 v[104:107], v[136:139], v[198:201], v[104:107]
	v_mfma_f32_16x16x32_bf16 v[100:103], v[128:131], v[206:209], v[100:103]
	v_mfma_f32_16x16x32_bf16 v[96:99], v[136:139], v[206:209], v[96:99]
	v_mfma_f32_16x16x32_bf16 v[124:127], v[132:135], v[148:151], v[124:127]
	v_mfma_f32_16x16x32_bf16 v[120:123], v[140:143], v[148:151], v[120:123]
	v_mfma_f32_16x16x32_bf16 v[116:119], v[132:135], v[194:197], v[116:119]
	v_mfma_f32_16x16x32_bf16 v[112:115], v[140:143], v[194:197], v[112:115]
	v_mfma_f32_16x16x32_bf16 v[108:111], v[132:135], v[202:205], v[108:111]
	v_mfma_f32_16x16x32_bf16 v[104:107], v[140:143], v[202:205], v[104:107]
	v_mfma_f32_16x16x32_bf16 v[100:103], v[132:135], v[210:213], v[100:103]
	s_setprio 0
	v_mfma_f32_16x16x32_bf16 v[96:99], v[140:143], v[210:213], v[96:99]
	s_barrier
	ds_read_b128 v[214:217], v226 offset:49152
	ds_read_b128 v[230:233], v226 offset:50176
	ds_read_b128 v[234:237], v226 offset:51200
	ds_read_b128 v[238:241], v226 offset:52224
	s_add_i32 s26, 0, 0x1c000
	s_add_i32 s20, s43, s31
	s_add_i32 m0, s20, 0xffffff80
	s_nop 0
	global_load_lds_dwordx4 v188, s[24:25] offset:128
	s_add_i32 m0, s20, 0x1f80
	s_nop 0
	global_load_lds_dwordx4 v186, s[24:25] offset:128
	s_waitcnt lgkmcnt(0)
	s_setprio 1
	s_barrier
	v_mfma_f32_16x16x32_bf16 v[60:63], v[214:217], v[144:147], v[60:63]
	v_mfma_f32_16x16x32_bf16 v[56:59], v[234:237], v[144:147], v[56:59]
	v_mfma_f32_16x16x32_bf16 v[52:55], v[214:217], v[152:155], v[52:55]
	v_mfma_f32_16x16x32_bf16 v[48:51], v[234:237], v[152:155], v[48:51]
	v_mfma_f32_16x16x32_bf16 v[44:47], v[214:217], v[198:201], v[44:47]
	v_mfma_f32_16x16x32_bf16 v[40:43], v[234:237], v[198:201], v[40:43]
	v_mfma_f32_16x16x32_bf16 v[36:39], v[214:217], v[206:209], v[36:39]
	v_mfma_f32_16x16x32_bf16 v[32:35], v[234:237], v[206:209], v[32:35]
	v_mfma_f32_16x16x32_bf16 v[60:63], v[230:233], v[148:151], v[60:63]
	s_add_i32 m0, s38, 0xffffff80
	v_mfma_f32_16x16x32_bf16 v[56:59], v[238:241], v[148:151], v[56:59]
	v_mfma_f32_16x16x32_bf16 v[52:55], v[230:233], v[194:197], v[52:55]
	v_mfma_f32_16x16x32_bf16 v[48:51], v[238:241], v[194:197], v[48:51]
	v_mfma_f32_16x16x32_bf16 v[44:47], v[230:233], v[202:205], v[44:47]
	v_mfma_f32_16x16x32_bf16 v[40:43], v[238:241], v[202:205], v[40:43]
	v_mfma_f32_16x16x32_bf16 v[36:39], v[230:233], v[210:213], v[36:39]
	s_setprio 0
	v_mfma_f32_16x16x32_bf16 v[32:35], v[238:241], v[210:213], v[32:35]
	s_barrier
	ds_read_b128 v[144:147], v228 offset:49152
	ds_read_b128 v[148:151], v228 offset:50176
	ds_read_b128 v[152:155], v228 offset:51200
	ds_read_b128 v[194:197], v228 offset:52224
	ds_read_b128 v[198:201], v228 offset:53248
	ds_read_b128 v[202:205], v228 offset:54272
	ds_read_b128 v[206:209], v228 offset:55296
	ds_read_b128 v[210:213], v228 offset:56320
	global_load_lds_dwordx4 v188, s[100:101] offset:128
	s_add_i32 m0, s39, 0xffffff80
	s_nop 0
	global_load_lds_dwordx4 v186, s[100:101] offset:128
	s_waitcnt lgkmcnt(0)
	s_setprio 1
	s_barrier
; #define PG8_WAIT_V(n) asm volatile("s_waitcnt vmcnt(" #n ")" ::: "memory")
; #define PG8_WAIT_L(n) asm volatile("s_waitcnt lgkmcnt(" #n ")" ::: "memory")
; #define PG8_BAR __builtin_amdgcn_s_barrier()
; template <class Epi>
; DI void gemm_phase(LAS unsigned char* lds, const Gemm g, const StaticOrder& S, const Epi& E) {
;     ...
;             PG8_BAR; PG8_WAIT_L(0); PG8_MMA(1, 0, At, B0); PG8_BAR; PG8_SCHED;
;             PG8_STAGE(PG8_SB(1, 1), b3 + hstep);
;             PG8_WAIT_V(6); PG8_BAR; PG8_MMA(1, 1, At, B1); PG8_BAR;
;     template <bool LN, int BJ, int LO, int HI> DI void batch(const f32x4 (&acc)[2][2][4][2], unsigned row0, unsigned col0, const f32x4 (&gv)[2], const f32x4 (&bv)[2]) const {
;         f32x4 r[HI - LO]; float mean[(HI - LO) / 2], rstd[(HI - LO) / 2];
; #pragma unroll
;         for (int i = LO; i < HI; ++i) { const int ai = i >> 3, m = (i >> 1) & 3, n = i & 1; const unsigned row = row0 + ai * HALF + m * 16;
;             if (n == 0) { mean[(i - LO) >> 1] = 0.f; rstd[(i - LO) >> 1] = 1.f;
;                 if (LN) { const float2 st = *(const float2*)(stats + row * 2u); mean[(i - LO) >> 1] = st.x; rstd[(i - LO) >> 1] = st.y; } }
;             r[i - LO] = *(const f32x4*)(src + (row * (unsigned)DM + col0 + BJ * HALF + n * 16)); }
; #pragma unroll
;         for (int i = LO; i < HI; ++i) { const int ai = i >> 3, m = (i >> 1) & 3, n = i & 1; const unsigned row = row0 + ai * HALF + m * 16;
;             *(f32x4*)(Y + (row * (unsigned)DM + col0 + BJ * HALF + n * 16)) = acc[ai][BJ][m][n] + ((r[i - LO] - mean[(i - LO) >> 1]) * rstd[(i - LO) >> 1]) * gv[n] + bv[n]; }
;         __builtin_amdgcn_sched_barrier(0);
;     }
;     template <bool LN, int BJ> DI void load_gb(unsigned col0, f32x4 (&gv)[2], f32x4 (&bv)[2]) const {
; #pragma unroll
;         for (int n = 0; n < 2; ++n) {
;             if (LN) { gv[n] = *(const f32x4*)(gam + col0 + BJ * HALF + n * 16) * ALPHA; bv[n] = *(const f32x4*)(bet + col0 + BJ * HALF + n * 16) * ALPHA; }
;             else { gv[n] = (f32x4){ALPHA, ALPHA, ALPHA, ALPHA}; bv[n] = (f32x4){0.f, 0.f, 0.f, 0.f}; }
;         }
;     }
;     template <bool LN> DI void run(const f32x4 (&acc)[2][2][4][2], const Unit& u, int wr, int wc, int fr, int fq) const {
;         const unsigned row0 = u.pm * BM + wr * 64 + fr, col0 = u.pn * BM + wc * 32 + 4 * fq;
;         f32x4 gv[2], bv[2];
;         load_gb<LN, 0>(col0, gv, bv);
	v_mfma_f32_16x16x32_bf16 v[92:95], v[128:131], v[144:147], v[92:95]
	v_mfma_f32_16x16x32_bf16 v[88:91], v[136:139], v[144:147], v[88:91]
	v_mfma_f32_16x16x32_bf16 v[84:87], v[128:131], v[152:155], v[84:87]
	v_mfma_f32_16x16x32_bf16 v[80:83], v[136:139], v[152:155], v[80:83]
	v_mfma_f32_16x16x32_bf16 v[76:79], v[128:131], v[198:201], v[76:79]
	v_mfma_f32_16x16x32_bf16 v[72:75], v[136:139], v[198:201], v[72:75]
	v_mfma_f32_16x16x32_bf16 v[68:71], v[128:131], v[206:209], v[68:71]
	v_mfma_f32_16x16x32_bf16 v[64:67], v[136:139], v[206:209], v[64:67]
	v_mfma_f32_16x16x32_bf16 v[92:95], v[132:135], v[148:151], v[92:95]
	v_mfma_f32_16x16x32_bf16 v[88:91], v[140:143], v[148:151], v[88:91]
	v_mfma_f32_16x16x32_bf16 v[84:87], v[132:135], v[194:197], v[84:87]
	v_mfma_f32_16x16x32_bf16 v[80:83], v[140:143], v[194:197], v[80:83]
	v_mfma_f32_16x16x32_bf16 v[76:79], v[132:135], v[202:205], v[76:79]
	v_mfma_f32_16x16x32_bf16 v[72:75], v[140:143], v[202:205], v[72:75]
	v_mfma_f32_16x16x32_bf16 v[68:71], v[132:135], v[210:213], v[68:71]
	s_setprio 0
	v_mfma_f32_16x16x32_bf16 v[64:67], v[140:143], v[210:213], v[64:67]
	s_barrier
	s_add_u32 s20, s24, 0x90080
	s_addc_u32 s21, s25, 0
	s_add_i32 s24, s26, s31
	s_mov_b32 m0, s24
	s_nop 0
	global_load_lds_dwordx4 v188, s[20:21]
	s_add_i32 m0, s24, 0x2000
	s_nop 0
	global_load_lds_dwordx4 v186, s[20:21]
	s_waitcnt vmcnt(6)
	s_setprio 1
	s_barrier
	v_mfma_f32_16x16x32_bf16 v[28:31], v[214:217], v[144:147], v[28:31]
	v_mfma_f32_16x16x32_bf16 v[24:27], v[234:237], v[144:147], v[24:27]
	v_mfma_f32_16x16x32_bf16 v[20:23], v[214:217], v[152:155], v[20:23]
	v_mfma_f32_16x16x32_bf16 v[16:19], v[234:237], v[152:155], v[16:19]
	v_mfma_f32_16x16x32_bf16 v[12:15], v[214:217], v[198:201], v[12:15]
	v_mfma_f32_16x16x32_bf16 v[8:11], v[234:237], v[198:201], v[8:11]
	v_mfma_f32_16x16x32_bf16 v[4:7], v[214:217], v[206:209], v[4:7]
	v_mfma_f32_16x16x32_bf16 v[0:3], v[234:237], v[206:209], v[0:3]
	v_mfma_f32_16x16x32_bf16 v[28:31], v[230:233], v[148:151], v[28:31]
	s_add_i32 s33, s33, 2
	v_mfma_f32_16x16x32_bf16 v[24:27], v[238:241], v[148:151], v[24:27]
	s_add_u32 s4, s4, 0x100
	v_mfma_f32_16x16x32_bf16 v[20:23], v[230:233], v[194:197], v[20:23]
	s_addc_u32 s5, s5, 0
	v_mfma_f32_16x16x32_bf16 v[16:19], v[238:241], v[194:197], v[16:19]
	s_cmp_gt_u32 s33, 33
	v_mfma_f32_16x16x32_bf16 v[12:15], v[230:233], v[202:205], v[12:15]
	s_mov_b64 s[20:21], s[22:23]
	v_mfma_f32_16x16x32_bf16 v[8:11], v[238:241], v[202:205], v[8:11]
	v_mfma_f32_16x16x32_bf16 v[4:7], v[230:233], v[210:213], v[4:7]
	s_setprio 0
	v_mfma_f32_16x16x32_bf16 v[0:3], v[238:241], v[210:213], v[0:3]
	s_barrier
	s_cbranch_scc0 .LBB0_77
	v_lshl_add_u32 v206, s3, 8, v225
	v_lshl_or_b32 v158, s2, 8, v227
	v_lshlrev_b32_e32 v232, 11, v206
	s_andn2_b64 vcc, exec, s[14:15]
	v_or_b32_e32 v231, 16, v158
	v_add_u32_e32 v194, v232, v158
	v_or_b32_e32 v230, 0x80, v158
	v_or_b32_e32 v229, 0x90, v158
	s_cbranch_vccnz .LBB0_80
	v_lshlrev_b64 v[132:133], 2, v[158:159]
	v_lshl_add_u64 v[140:141], s[16:17], 0, v[132:133]
	global_load_dwordx4 v[128:131], v[140:141], off
	v_lshl_add_u64 v[142:143], s[18:19], 0, v[132:133]
	v_readlane_b32 s2, v253, 8
	v_mov_b32_e32 v195, v159
	v_lshlrev_b32_e32 v136, 1, v206
	v_mov_b32_e32 v137, v159
	v_readlane_b32 s3, v253, 9
	v_lshlrev_b64 v[212:213], 2, v[194:195]
	v_add_u32_e32 v146, v232, v231
	v_lshl_add_u64 v[144:145], v[136:137], 2, s[2:3]
	v_lshl_add_u64 v[136:137], s[88:89], 0, v[212:213]
	v_mov_b32_e32 v147, v159
	v_lshl_add_u64 v[146:147], v[146:147], 2, s[88:89]
	v_or_b32_e32 v195, 16, v206
	v_mov_b32_e32 v201, v159
	v_mov_b32_e32 v209, v159
	v_lshl_add_u64 v[212:213], s[90:91], 0, v[212:213]
	s_waitcnt vmcnt(0)
	v_pk_mul_f32 v[152:153], v[130:131], s[78:79] op_sel_hi:[1,0]
	v_pk_mul_f32 v[154:155], v[128:129], s[78:79] op_sel_hi:[1,0]
	global_load_dwordx4 v[132:135], v[142:143], off
	global_load_dwordx4 v[128:131], v[140:141], off offset:64
	global_load_dwordx2 v[204:205], v[144:145], off
	global_load_dwordx4 v[196:199], v[146:147], off
	v_lshlrev_b32_e32 v146, 1, v195
	global_load_dwordx4 v[136:139], v[136:137], off
	v_lshlrev_b32_e32 v195, 11, v195
	v_mov_b32_e32 v147, v159
	v_add_u32_e32 v200, v195, v158
	v_lshl_add_u64 v[146:147], v[146:147], 2, s[2:3]
	v_lshl_add_u64 v[200:201], v[200:201], 2, s[88:89]
	global_load_dwordx2 v[214:215], v[146:147], off
	v_add_u32_e32 v208, v195, v231
	global_load_dwordx4 v[200:203], v[200:201], off
	v_lshl_add_u64 v[208:209], v[208:209], 2, s[88:89]
	global_load_dwordx4 v[208:211], v[208:209], off
	s_waitcnt vmcnt(0)
	v_pk_mul_f32 v[148:149], v[130:131], s[78:79] op_sel_hi:[1,0]
	v_pk_mul_f32 v[150:151], v[128:129], s[78:79] op_sel_hi:[1,0]
	global_load_dwordx4 v[128:131], v[142:143], off offset:64
	v_sub_f32_e32 v137, v137, v204
	v_sub_f32_e32 v136, v136, v204
	v_sub_f32_e32 v139, v139, v204
	v_sub_f32_e32 v138, v138, v204
	v_pk_mul_f32 v[138:139], v[204:205], v[138:139] op_sel:[1,0]
	v_pk_mul_f32 v[136:137], v[204:205], v[136:137] op_sel:[1,0]
	v_pk_fma_f32 v[138:139], v[152:153], v[138:139], v[126:127]
	v_pk_fma_f32 v[136:137], v[154:155], v[136:137], v[124:125]
	v_pk_fma_f32 v[138:139], v[134:135], s[78:79], v[138:139] op_sel_hi:[1,0,1]
	v_pk_fma_f32 v[136:137], v[132:133], s[78:79], v[136:137] op_sel_hi:[1,0,1]
	global_store_dwordx4 v[212:213], v[136:139], off
	s_nop 1
	v_sub_f32_e32 v137, v197, v204
	v_sub_f32_e32 v136, v196, v204
	v_sub_f32_e32 v139, v199, v204
	v_sub_f32_e32 v138, v198, v204
	v_pk_mul_f32 v[138:139], v[204:205], v[138:139] op_sel:[1,0]
	v_pk_mul_f32 v[136:137], v[204:205], v[136:137] op_sel:[1,0]
	v_pk_fma_f32 v[138:139], v[148:149], v[138:139], v[122:123]
	v_pk_fma_f32 v[136:137], v[150:151], v[136:137], v[120:121]
	v_or_b32_e32 v196, 16, v194
	v_mov_b32_e32 v197, v159
	v_lshl_add_u64 v[196:197], v[196:197], 2, s[90:91]
	s_waitcnt vmcnt(0)
;     template <bool LN, int BJ, int LO, int HI> DI void batch(const f32x4 (&acc)[2][2][4][2], unsigned row0, unsigned col0, const f32x4 (&gv)[2], const f32x4 (&bv)[2]) const {
;         f32x4 r[HI - LO]; float mean[(HI - LO) / 2], rstd[(HI - LO) / 2];
; #pragma unroll
;         for (int i = LO; i < HI; ++i) { const int ai = i >> 3, m = (i >> 1) & 3, n = i & 1; const unsigned row = row0 + ai * HALF + m * 16;
;             if (n == 0) { mean[(i - LO) >> 1] = 0.f; rstd[(i - LO) >> 1] = 1.f;
;                 if (LN) { const float2 st = *(const float2*)(stats + row * 2u); mean[(i - LO) >> 1] = st.x; rstd[(i - LO) >> 1] = st.y; } }
;             r[i - LO] = *(const f32x4*)(src + (row * (unsigned)DM + col0 + BJ * HALF + n * 16)); }
; #pragma unroll
;         for (int i = LO; i < HI; ++i) { const int ai = i >> 3, m = (i >> 1) & 3, n = i & 1; const unsigned row = row0 + ai * HALF + m * 16;
;             *(f32x4*)(Y + (row * (unsigned)DM + col0 + BJ * HALF + n * 16)) = acc[ai][BJ][m][n] + ((r[i - LO] - mean[(i - LO) >> 1]) * rstd[(i - LO) >> 1]) * gv[n] + bv[n]; }
;         __builtin_amdgcn_sched_barrier(0);
;     }
	v_pk_fma_f32 v[138:139], v[130:131], s[78:79], v[138:139] op_sel_hi:[1,0,1]
	v_pk_fma_f32 v[136:137], v[128:129], s[78:79], v[136:137] op_sel_hi:[1,0,1]
	global_store_dwordx4 v[196:197], v[136:139], off
	v_add_u32_e32 v196, 0x8000, v194
	v_mov_b32_e32 v197, v159
	v_sub_f32_e32 v137, v201, v214
	v_sub_f32_e32 v136, v200, v214
	v_sub_f32_e32 v139, v203, v214
	v_sub_f32_e32 v138, v202, v214
	v_pk_mul_f32 v[138:139], v[214:215], v[138:139] op_sel:[1,0]
	v_pk_mul_f32 v[136:137], v[214:215], v[136:137] op_sel:[1,0]
	v_pk_fma_f32 v[138:139], v[152:153], v[138:139], v[118:119]
	v_pk_fma_f32 v[136:137], v[154:155], v[136:137], v[116:117]
	v_pk_fma_f32 v[138:139], v[134:135], s[78:79], v[138:139] op_sel_hi:[1,0,1]
	v_pk_fma_f32 v[136:137], v[132:133], s[78:79], v[136:137] op_sel_hi:[1,0,1]
	v_lshl_add_u64 v[196:197], v[196:197], 2, s[90:91]
	global_store_dwordx4 v[196:197], v[136:139], off
	v_add_u32_e32 v196, 0x8010, v194
	v_mov_b32_e32 v197, v159
	v_sub_f32_e32 v137, v209, v214
	v_sub_f32_e32 v136, v208, v214
	v_sub_f32_e32 v139, v211, v214
	v_sub_f32_e32 v138, v210, v214
	v_pk_mul_f32 v[138:139], v[214:215], v[138:139] op_sel:[1,0]
	v_pk_mul_f32 v[136:137], v[214:215], v[136:137] op_sel:[1,0]
	v_pk_fma_f32 v[138:139], v[148:149], v[138:139], v[114:115]
	v_pk_fma_f32 v[136:137], v[150:151], v[136:137], v[112:113]
	v_pk_fma_f32 v[138:139], v[130:131], s[78:79], v[138:139] op_sel_hi:[1,0,1]
	v_pk_fma_f32 v[136:137], v[128:129], s[78:79], v[136:137] op_sel_hi:[1,0,1]
	v_lshl_add_u64 v[196:197], v[196:197], 2, s[90:91]
	global_store_dwordx4 v[196:197], v[136:139], off
	s_nop 1
	v_or_b32_e32 v138, 32, v206
	v_lshlrev_b32_e32 v136, 1, v138
	v_mov_b32_e32 v137, v159
	v_lshlrev_b32_e32 v236, 11, v138
	v_lshl_add_u64 v[200:201], v[136:137], 2, s[2:3]
	v_add_u32_e32 v136, v236, v158
	v_lshl_add_u64 v[136:137], v[136:137], 2, s[88:89]
	global_load_dwordx2 v[204:205], v[200:201], off
	v_add_u32_e32 v196, v236, v231
	global_load_dwordx4 v[136:139], v[136:137], off
	v_mov_b32_e32 v197, v159
	v_lshl_add_u64 v[196:197], v[196:197], 2, s[88:89]
	global_load_dwordx4 v[196:199], v[196:197], off
	v_or_b32_e32 v207, 48, v206
	v_lshlrev_b32_e32 v235, 11, v207
	v_lshlrev_b32_e32 v202, 1, v207
	v_mov_b32_e32 v203, v159
	v_add_u32_e32 v208, v235, v158
	v_mov_b32_e32 v209, v159
	v_lshl_add_u64 v[202:203], v[202:203], 2, s[2:3]
	v_lshl_add_u64 v[208:209], v[208:209], 2, s[88:89]
	global_load_dwordx2 v[216:217], v[202:203], off
	v_add_u32_e32 v212, v235, v231
	global_load_dwordx4 v[208:211], v[208:209], off
	v_mov_b32_e32 v213, v159
	v_lshl_add_u64 v[212:213], v[212:213], 2, s[88:89]
	global_load_dwordx4 v[212:215], v[212:213], off
	v_add_u32_e32 v218, 0x10000, v194
	v_mov_b32_e32 v219, v159
	v_lshl_add_u64 v[218:219], v[218:219], 2, s[90:91]
	s_waitcnt vmcnt(0)
	v_sub_f32_e32 v137, v137, v204
	v_sub_f32_e32 v136, v136, v204
	v_sub_f32_e32 v139, v139, v204
	v_sub_f32_e32 v138, v138, v204
	v_pk_mul_f32 v[138:139], v[204:205], v[138:139] op_sel:[1,0]
	v_pk_mul_f32 v[136:137], v[204:205], v[136:137] op_sel:[1,0]
	v_pk_fma_f32 v[138:139], v[152:153], v[138:139], v[110:111]
	v_pk_fma_f32 v[136:137], v[154:155], v[136:137], v[108:109]
	v_pk_fma_f32 v[138:139], v[134:135], s[78:79], v[138:139] op_sel_hi:[1,0,1]
	v_pk_fma_f32 v[136:137], v[132:133], s[78:79], v[136:137] op_sel_hi:[1,0,1]
	global_store_dwordx4 v[218:219], v[136:139], off
	s_nop 1
	v_sub_f32_e32 v137, v197, v204
	v_sub_f32_e32 v136, v196, v204
	v_sub_f32_e32 v139, v199, v204
	v_sub_f32_e32 v138, v198, v204
	v_pk_mul_f32 v[138:139], v[204:205], v[138:139] op_sel:[1,0]
	v_pk_mul_f32 v[136:137], v[204:205], v[136:137] op_sel:[1,0]
	v_pk_fma_f32 v[138:139], v[148:149], v[138:139], v[106:107]
	v_pk_fma_f32 v[136:137], v[150:151], v[136:137], v[104:105]
	v_add_u32_e32 v196, 0x10010, v194
	v_mov_b32_e32 v197, v159
	v_pk_fma_f32 v[138:139], v[130:131], s[78:79], v[138:139] op_sel_hi:[1,0,1]
	v_pk_fma_f32 v[136:137], v[128:129], s[78:79], v[136:137] op_sel_hi:[1,0,1]
	v_lshl_add_u64 v[196:197], v[196:197], 2, s[90:91]
	global_store_dwordx4 v[196:197], v[136:139], off
	v_add_u32_e32 v196, 0x18000, v194
	v_mov_b32_e32 v197, v159
	v_sub_f32_e32 v137, v209, v216
	v_sub_f32_e32 v136, v208, v216
	v_sub_f32_e32 v139, v211, v216
	v_sub_f32_e32 v138, v210, v216
	v_pk_mul_f32 v[138:139], v[216:217], v[138:139] op_sel:[1,0]
	v_pk_mul_f32 v[136:137], v[216:217], v[136:137] op_sel:[1,0]
	v_pk_fma_f32 v[138:139], v[152:153], v[138:139], v[102:103]
	v_pk_fma_f32 v[136:137], v[154:155], v[136:137], v[100:101]
	v_pk_fma_f32 v[138:139], v[134:135], s[78:79], v[138:139] op_sel_hi:[1,0,1]
	v_pk_fma_f32 v[136:137], v[132:133], s[78:79], v[136:137] op_sel_hi:[1,0,1]
	v_lshl_add_u64 v[196:197], v[196:197], 2, s[90:91]
	global_store_dwordx4 v[196:197], v[136:139], off
	v_add_u32_e32 v196, 0x18010, v194
	v_mov_b32_e32 v197, v159
	v_sub_f32_e32 v137, v213, v216
	v_sub_f32_e32 v136, v212, v216
	v_sub_f32_e32 v139, v215, v216
	v_sub_f32_e32 v138, v214, v216
	v_pk_mul_f32 v[138:139], v[216:217], v[138:139] op_sel:[1,0]
	v_pk_mul_f32 v[136:137], v[216:217], v[136:137] op_sel:[1,0]
	v_pk_fma_f32 v[138:139], v[148:149], v[138:139], v[98:99]
	v_pk_fma_f32 v[136:137], v[150:151], v[136:137], v[96:97]
	v_pk_fma_f32 v[138:139], v[130:131], s[78:79], v[138:139] op_sel_hi:[1,0,1]
	v_pk_fma_f32 v[136:137], v[128:129], s[78:79], v[136:137] op_sel_hi:[1,0,1]
	v_lshl_add_u64 v[196:197], v[196:197], 2, s[90:91]
	global_store_dwordx4 v[196:197], v[136:139], off
	s_nop 1
	v_add_u32_e32 v138, 0x80, v206
	v_lshlrev_b32_e32 v136, 1, v138
	v_mov_b32_e32 v137, v159
	v_lshlrev_b32_e32 v233, 11, v138
	v_lshl_add_u64 v[196:197], v[136:137], 2, s[2:3]
	v_add_u32_e32 v136, v233, v158
	v_lshl_add_u64 v[136:137], v[136:137], 2, s[88:89]
	global_load_dwordx2 v[204:205], v[196:197], off
	v_add_u32_e32 v198, v233, v231
	global_load_dwordx4 v[136:139], v[136:137], off
	v_mov_b32_e32 v199, v159
	v_add_u32_e32 v207, 0x90, v206
	v_lshl_add_u64 v[198:199], v[198:199], 2, s[88:89]
	v_lshlrev_b32_e32 v234, 11, v207
	global_load_dwordx4 v[208:211], v[198:199], off
	v_add_u32_e32 v212, v234, v158
	v_mov_b32_e32 v213, v159
	v_lshl_add_u64 v[212:213], v[212:213], 2, s[88:89]
	global_load_dwordx4 v[212:215], v[212:213], off
	v_lshlrev_b32_e32 v198, 1, v207
	v_mov_b32_e32 v199, v159
	v_lshl_add_u64 v[198:199], v[198:199], 2, s[2:3]
	global_load_dwordx2 v[220:221], v[198:199], off
	v_add_u32_e32 v216, v234, v231
	v_mov_b32_e32 v217, v159
	v_lshl_add_u64 v[216:217], v[216:217], 2, s[88:89]
	global_load_dwordx4 v[216:219], v[216:217], off
	v_add_u32_e32 v238, 0x40000, v194
	v_mov_b32_e32 v239, v159
	v_lshl_add_u64 v[238:239], v[238:239], 2, s[90:91]
	s_waitcnt vmcnt(0)
;     template <bool LN, int BJ, int LO, int HI> DI void batch(const f32x4 (&acc)[2][2][4][2], unsigned row0, unsigned col0, const f32x4 (&gv)[2], const f32x4 (&bv)[2]) const {
;         f32x4 r[HI - LO]; float mean[(HI - LO) / 2], rstd[(HI - LO) / 2];
; #pragma unroll
;         for (int i = LO; i < HI; ++i) { const int ai = i >> 3, m = (i >> 1) & 3, n = i & 1; const unsigned row = row0 + ai * HALF + m * 16;
;             if (n == 0) { mean[(i - LO) >> 1] = 0.f; rstd[(i - LO) >> 1] = 1.f;
;                 if (LN) { const float2 st = *(const float2*)(stats + row * 2u); mean[(i - LO) >> 1] = st.x; rstd[(i - LO) >> 1] = st.y; } }
;             r[i - LO] = *(const f32x4*)(src + (row * (unsigned)DM + col0 + BJ * HALF + n * 16)); }
; #pragma unroll
;         for (int i = LO; i < HI; ++i) { const int ai = i >> 3, m = (i >> 1) & 3, n = i & 1; const unsigned row = row0 + ai * HALF + m * 16;
;             *(f32x4*)(Y + (row * (unsigned)DM + col0 + BJ * HALF + n * 16)) = acc[ai][BJ][m][n] + ((r[i - LO] - mean[(i - LO) >> 1]) * rstd[(i - LO) >> 1]) * gv[n] + bv[n]; }
;         __builtin_amdgcn_sched_barrier(0);
;     }
;     template <bool LN> DI void run(const f32x4 (&acc)[2][2][4][2], const Unit& u, int wr, int wc, int fr, int fq) const {
;     ...
;         load_gb<LN, 1>(col0, gv, bv);
;         batch<LN, 1, 0, 8>(acc, row0, col0, gv, bv);
	v_sub_f32_e32 v137, v137, v204
	v_sub_f32_e32 v136, v136, v204
	v_sub_f32_e32 v139, v139, v204
	v_sub_f32_e32 v138, v138, v204
	v_pk_mul_f32 v[138:139], v[204:205], v[138:139] op_sel:[1,0]
	v_pk_mul_f32 v[136:137], v[204:205], v[136:137] op_sel:[1,0]
	v_pk_fma_f32 v[138:139], v[152:153], v[138:139], v[94:95]
	v_pk_fma_f32 v[136:137], v[154:155], v[136:137], v[92:93]
	v_pk_fma_f32 v[138:139], v[134:135], s[78:79], v[138:139] op_sel_hi:[1,0,1]
	v_pk_fma_f32 v[136:137], v[132:133], s[78:79], v[136:137] op_sel_hi:[1,0,1]
	global_store_dwordx4 v[238:239], v[136:139], off
	s_nop 1
	v_sub_f32_e32 v137, v209, v204
	v_sub_f32_e32 v136, v208, v204
	v_sub_f32_e32 v139, v211, v204
	v_sub_f32_e32 v138, v210, v204
	v_pk_mul_f32 v[138:139], v[204:205], v[138:139] op_sel:[1,0]
	v_pk_mul_f32 v[136:137], v[204:205], v[136:137] op_sel:[1,0]
	v_pk_fma_f32 v[138:139], v[148:149], v[138:139], v[90:91]
	v_pk_fma_f32 v[136:137], v[150:151], v[136:137], v[88:89]
	v_add_u32_e32 v204, 0x40010, v194
	v_mov_b32_e32 v205, v159
	v_pk_fma_f32 v[138:139], v[130:131], s[78:79], v[138:139] op_sel_hi:[1,0,1]
	v_pk_fma_f32 v[136:137], v[128:129], s[78:79], v[136:137] op_sel_hi:[1,0,1]
	v_lshl_add_u64 v[204:205], v[204:205], 2, s[90:91]
	global_store_dwordx4 v[204:205], v[136:139], off
	v_add_u32_e32 v204, 0x48000, v194
	v_mov_b32_e32 v205, v159
	v_sub_f32_e32 v137, v213, v220
	v_sub_f32_e32 v136, v212, v220
	v_sub_f32_e32 v139, v215, v220
	v_sub_f32_e32 v138, v214, v220
	v_pk_mul_f32 v[138:139], v[220:221], v[138:139] op_sel:[1,0]
	v_pk_mul_f32 v[136:137], v[220:221], v[136:137] op_sel:[1,0]
	v_pk_fma_f32 v[138:139], v[152:153], v[138:139], v[86:87]
	v_pk_fma_f32 v[136:137], v[154:155], v[136:137], v[84:85]
	v_pk_fma_f32 v[138:139], v[134:135], s[78:79], v[138:139] op_sel_hi:[1,0,1]
	v_pk_fma_f32 v[136:137], v[132:133], s[78:79], v[136:137] op_sel_hi:[1,0,1]
	v_lshl_add_u64 v[204:205], v[204:205], 2, s[90:91]
	global_store_dwordx4 v[204:205], v[136:139], off
	v_add_u32_e32 v204, 0x48010, v194
	v_mov_b32_e32 v205, v159
	v_sub_f32_e32 v137, v217, v220
	v_sub_f32_e32 v136, v216, v220
	v_sub_f32_e32 v139, v219, v220
	v_sub_f32_e32 v138, v218, v220
	v_pk_mul_f32 v[138:139], v[220:221], v[138:139] op_sel:[1,0]
	v_pk_mul_f32 v[136:137], v[220:221], v[136:137] op_sel:[1,0]
	v_pk_fma_f32 v[138:139], v[148:149], v[138:139], v[82:83]
	v_pk_fma_f32 v[136:137], v[150:151], v[136:137], v[80:81]
	v_pk_fma_f32 v[138:139], v[130:131], s[78:79], v[138:139] op_sel_hi:[1,0,1]
	v_pk_fma_f32 v[136:137], v[128:129], s[78:79], v[136:137] op_sel_hi:[1,0,1]
	v_lshl_add_u64 v[204:205], v[204:205], 2, s[90:91]
	global_store_dwordx4 v[204:205], v[136:139], off
	s_nop 1
	v_add_u32_e32 v138, 0xa0, v206
	v_lshlrev_b32_e32 v136, 1, v138
	v_mov_b32_e32 v137, v159
	v_lshlrev_b32_e32 v237, 11, v138
	v_lshl_add_u64 v[204:205], v[136:137], 2, s[2:3]
	v_add_u32_e32 v136, v237, v158
	v_lshl_add_u64 v[136:137], v[136:137], 2, s[88:89]
	global_load_dwordx2 v[220:221], v[204:205], off
	v_add_u32_e32 v208, v237, v231
	global_load_dwordx4 v[136:139], v[136:137], off
	v_mov_b32_e32 v209, v159
	v_lshl_add_u64 v[208:209], v[208:209], 2, s[88:89]
	global_load_dwordx4 v[212:215], v[208:209], off
	v_add_u32_e32 v208, 0xb0, v206
	v_lshlrev_b32_e32 v206, 1, v208
	v_mov_b32_e32 v207, v159
	v_lshlrev_b32_e32 v238, 11, v208
	v_lshl_add_u64 v[210:211], v[206:207], 2, s[2:3]
	v_add_u32_e32 v206, v238, v158
	v_lshl_add_u64 v[206:207], v[206:207], 2, s[88:89]
	global_load_dwordx2 v[240:241], v[210:211], off
	v_add_u32_e32 v216, v238, v231
	global_load_dwordx4 v[206:209], v[206:207], off
	v_mov_b32_e32 v217, v159
	v_lshl_add_u64 v[216:217], v[216:217], 2, s[88:89]
	global_load_dwordx4 v[216:219], v[216:217], off
	v_add_u32_e32 v242, 0x50000, v194
	v_mov_b32_e32 v243, v159
	v_lshl_add_u64 v[242:243], v[242:243], 2, s[90:91]
	s_waitcnt vmcnt(0)
	v_sub_f32_e32 v137, v137, v220
	v_sub_f32_e32 v136, v136, v220
	v_sub_f32_e32 v139, v139, v220
	v_sub_f32_e32 v138, v138, v220
	v_pk_mul_f32 v[138:139], v[220:221], v[138:139] op_sel:[1,0]
	v_pk_mul_f32 v[136:137], v[220:221], v[136:137] op_sel:[1,0]
	v_pk_fma_f32 v[138:139], v[152:153], v[138:139], v[78:79]
	v_pk_fma_f32 v[136:137], v[154:155], v[136:137], v[76:77]
	v_pk_fma_f32 v[138:139], v[134:135], s[78:79], v[138:139] op_sel_hi:[1,0,1]
	v_pk_fma_f32 v[136:137], v[132:133], s[78:79], v[136:137] op_sel_hi:[1,0,1]
	global_store_dwordx4 v[242:243], v[136:139], off
	s_nop 1
	v_sub_f32_e32 v137, v213, v220
	v_sub_f32_e32 v136, v212, v220
	v_sub_f32_e32 v139, v215, v220
	v_sub_f32_e32 v138, v214, v220
	v_pk_mul_f32 v[138:139], v[220:221], v[138:139] op_sel:[1,0]
	v_pk_mul_f32 v[136:137], v[220:221], v[136:137] op_sel:[1,0]
	v_pk_fma_f32 v[138:139], v[148:149], v[138:139], v[74:75]
	v_pk_fma_f32 v[136:137], v[150:151], v[136:137], v[72:73]
	v_add_u32_e32 v212, 0x50010, v194
	v_mov_b32_e32 v213, v159
	v_pk_fma_f32 v[138:139], v[130:131], s[78:79], v[138:139] op_sel_hi:[1,0,1]
	v_pk_fma_f32 v[136:137], v[128:129], s[78:79], v[136:137] op_sel_hi:[1,0,1]
	v_lshl_add_u64 v[212:213], v[212:213], 2, s[90:91]
	global_store_dwordx4 v[212:213], v[136:139], off
	s_nop 1
	v_sub_f32_e32 v137, v207, v240
	v_sub_f32_e32 v136, v206, v240
	v_sub_f32_e32 v139, v209, v240
	v_sub_f32_e32 v138, v208, v240
	v_pk_mul_f32 v[136:137], v[240:241], v[136:137] op_sel:[1,0]
	v_pk_mul_f32 v[138:139], v[240:241], v[138:139] op_sel:[1,0]
	v_pk_fma_f32 v[136:137], v[154:155], v[136:137], v[68:69]
	v_pk_fma_f32 v[138:139], v[152:153], v[138:139], v[70:71]
	v_pk_fma_f32 v[132:133], v[132:133], s[78:79], v[136:137] op_sel_hi:[1,0,1]
	v_add_u32_e32 v136, 0x58000, v194
	v_mov_b32_e32 v137, v159
	v_pk_fma_f32 v[134:135], v[134:135], s[78:79], v[138:139] op_sel_hi:[1,0,1]
	v_lshl_add_u64 v[136:137], v[136:137], 2, s[90:91]
	global_store_dwordx4 v[136:137], v[132:135], off
	s_nop 1
	v_sub_f32_e32 v133, v217, v240
	v_sub_f32_e32 v132, v216, v240
	v_sub_f32_e32 v135, v219, v240
	v_sub_f32_e32 v134, v218, v240
	v_pk_mul_f32 v[132:133], v[240:241], v[132:133] op_sel:[1,0]
	v_pk_mul_f32 v[134:135], v[240:241], v[134:135] op_sel:[1,0]
	v_pk_fma_f32 v[132:133], v[150:151], v[132:133], v[64:65]
	v_pk_fma_f32 v[134:135], v[148:149], v[134:135], v[66:67]
	v_pk_fma_f32 v[128:129], v[128:129], s[78:79], v[132:133] op_sel_hi:[1,0,1]
	v_add_u32_e32 v132, 0x58010, v194
	v_mov_b32_e32 v133, v159
	v_pk_fma_f32 v[130:131], v[130:131], s[78:79], v[134:135] op_sel_hi:[1,0,1]
	v_lshl_add_u64 v[132:133], v[132:133], 2, s[90:91]
	global_store_dwordx4 v[132:133], v[128:131], off
	global_load_dwordx4 v[128:131], v[140:141], off offset:512
	v_add_u32_e32 v136, v232, v230
	v_mov_b32_e32 v137, v159
	v_lshl_add_u64 v[136:137], v[136:137], 2, s[88:89]
	s_waitcnt vmcnt(0)
;     template <bool LN, int BJ, int LO, int HI> DI void batch(const f32x4 (&acc)[2][2][4][2], unsigned row0, unsigned col0, const f32x4 (&gv)[2], const f32x4 (&bv)[2]) const {
;         f32x4 r[HI - LO]; float mean[(HI - LO) / 2], rstd[(HI - LO) / 2];
; #pragma unroll
;         for (int i = LO; i < HI; ++i) { const int ai = i >> 3, m = (i >> 1) & 3, n = i & 1; const unsigned row = row0 + ai * HALF + m * 16;
;             if (n == 0) { mean[(i - LO) >> 1] = 0.f; rstd[(i - LO) >> 1] = 1.f;
;                 if (LN) { const float2 st = *(const float2*)(stats + row * 2u); mean[(i - LO) >> 1] = st.x; rstd[(i - LO) >> 1] = st.y; } }
;             r[i - LO] = *(const f32x4*)(src + (row * (unsigned)DM + col0 + BJ * HALF + n * 16)); }
; #pragma unroll
;         for (int i = LO; i < HI; ++i) { const int ai = i >> 3, m = (i >> 1) & 3, n = i & 1; const unsigned row = row0 + ai * HALF + m * 16;
;             *(f32x4*)(Y + (row * (unsigned)DM + col0 + BJ * HALF + n * 16)) = acc[ai][BJ][m][n] + ((r[i - LO] - mean[(i - LO) >> 1]) * rstd[(i - LO) >> 1]) * gv[n] + bv[n]; }
;         __builtin_amdgcn_sched_barrier(0);
;     }
;     template <bool LN, int BJ> DI void load_gb(unsigned col0, f32x4 (&gv)[2], f32x4 (&bv)[2]) const {
; #pragma unroll
;         for (int n = 0; n < 2; ++n) {
;             if (LN) { gv[n] = *(const f32x4*)(gam + col0 + BJ * HALF + n * 16) * ALPHA; bv[n] = *(const f32x4*)(bet + col0 + BJ * HALF + n * 16) * ALPHA; }
;             else { gv[n] = (f32x4){ALPHA, ALPHA, ALPHA, ALPHA}; bv[n] = (f32x4){0.f, 0.f, 0.f, 0.f}; }
;         }
;     }
	v_pk_mul_f32 v[212:213], v[130:131], s[78:79] op_sel_hi:[1,0]
	v_pk_mul_f32 v[214:215], v[128:129], s[78:79] op_sel_hi:[1,0]
	global_load_dwordx4 v[132:135], v[142:143], off offset:512
	global_load_dwordx4 v[128:131], v[140:141], off offset:576
	s_waitcnt vmcnt(0)
	v_pk_mul_f32 v[206:207], v[130:131], s[78:79] op_sel_hi:[1,0]
	v_pk_mul_f32 v[208:209], v[128:129], s[78:79] op_sel_hi:[1,0]
	global_load_dwordx4 v[128:131], v[142:143], off offset:576
	global_load_dwordx2 v[220:221], v[144:145], off
	global_load_dwordx4 v[240:243], v[136:137], off
	v_add_u32_e32 v136, v232, v229
	v_mov_b32_e32 v137, v159
	v_lshl_add_u64 v[136:137], v[136:137], 2, s[88:89]
	global_load_dwordx4 v[244:247], v[136:137], off
	global_load_dwordx2 v[218:219], v[146:147], off
	v_add_u32_e32 v136, v195, v230
	v_mov_b32_e32 v137, v159
	v_lshl_add_u64 v[136:137], v[136:137], 2, s[88:89]
	global_load_dwordx4 v[248:251], v[136:137], off
	v_add_u32_e32 v136, v195, v229
	v_mov_b32_e32 v137, v159
	v_lshl_add_u64 v[136:137], v[136:137], 2, s[88:89]
	global_load_dwordx4 v[152:155], v[136:137], off
	global_load_dwordx2 v[216:217], v[200:201], off
	v_add_u32_e32 v136, v236, v230
	v_mov_b32_e32 v137, v159
	v_lshl_add_u64 v[136:137], v[136:137], 2, s[88:89]
	global_load_dwordx4 v[148:151], v[136:137], off
	v_add_u32_e32 v136, v236, v229
	v_mov_b32_e32 v137, v159
	v_lshl_add_u64 v[136:137], v[136:137], 2, s[88:89]
	global_load_dwordx4 v[144:147], v[136:137], off
	global_load_dwordx2 v[200:201], v[202:203], off
	v_add_u32_e32 v136, v235, v230
	v_mov_b32_e32 v137, v159
	v_lshl_add_u64 v[136:137], v[136:137], 2, s[88:89]
	global_load_dwordx4 v[140:143], v[136:137], off
	v_add_u32_e32 v136, v235, v229
	v_mov_b32_e32 v137, v159
	v_lshl_add_u64 v[136:137], v[136:137], 2, s[88:89]
	global_load_dwordx4 v[136:139], v[136:137], off
	v_add_u32_e32 v202, 0x80, v194
	v_mov_b32_e32 v203, v159
	v_lshl_add_u64 v[202:203], v[202:203], 2, s[90:91]
	s_waitcnt vmcnt(0)
	v_sub_f32_e32 v241, v241, v220
	v_sub_f32_e32 v240, v240, v220
	v_sub_f32_e32 v243, v243, v220
	v_sub_f32_e32 v242, v242, v220
	v_pk_mul_f32 v[242:243], v[220:221], v[242:243] op_sel:[1,0]
	v_pk_mul_f32 v[240:241], v[220:221], v[240:241] op_sel:[1,0]
	v_pk_fma_f32 v[242:243], v[212:213], v[242:243], v[62:63]
	v_pk_fma_f32 v[240:241], v[214:215], v[240:241], v[60:61]
	v_pk_fma_f32 v[242:243], v[134:135], s[78:79], v[242:243] op_sel_hi:[1,0,1]
	v_pk_fma_f32 v[240:241], v[132:133], s[78:79], v[240:241] op_sel_hi:[1,0,1]
	global_store_dwordx4 v[202:203], v[240:243], off
	v_sub_f32_e32 v203, v245, v220
	v_sub_f32_e32 v202, v244, v220
	v_sub_f32_e32 v241, v247, v220
	v_sub_f32_e32 v240, v246, v220
	v_pk_mul_f32 v[202:203], v[220:221], v[202:203] op_sel:[1,0]
	v_pk_mul_f32 v[240:241], v[220:221], v[240:241] op_sel:[1,0]
	v_pk_fma_f32 v[202:203], v[208:209], v[202:203], v[56:57]
	v_pk_fma_f32 v[220:221], v[206:207], v[240:241], v[58:59]
	v_pk_fma_f32 v[240:241], v[128:129], s[78:79], v[202:203] op_sel_hi:[1,0,1]
	v_add_u32_e32 v202, 0x90, v194
	v_mov_b32_e32 v203, v159
	v_pk_fma_f32 v[242:243], v[130:131], s[78:79], v[220:221] op_sel_hi:[1,0,1]
	v_lshl_add_u64 v[202:203], v[202:203], 2, s[90:91]
	global_store_dwordx4 v[202:203], v[240:243], off
	v_sub_f32_e32 v203, v249, v218
	v_sub_f32_e32 v202, v248, v218
	v_sub_f32_e32 v221, v251, v218
	v_sub_f32_e32 v220, v250, v218
	v_pk_mul_f32 v[202:203], v[218:219], v[202:203] op_sel:[1,0]
	v_pk_mul_f32 v[220:221], v[218:219], v[220:221] op_sel:[1,0]
	v_pk_fma_f32 v[202:203], v[214:215], v[202:203], v[52:53]
	v_pk_fma_f32 v[220:221], v[212:213], v[220:221], v[54:55]
	v_pk_fma_f32 v[240:241], v[132:133], s[78:79], v[202:203] op_sel_hi:[1,0,1]
	v_add_u32_e32 v202, 0x8080, v194
	v_mov_b32_e32 v203, v159
	v_sub_f32_e32 v153, v153, v218
	v_sub_f32_e32 v152, v152, v218
	v_sub_f32_e32 v155, v155, v218
	v_sub_f32_e32 v154, v154, v218
	v_pk_fma_f32 v[242:243], v[134:135], s[78:79], v[220:221] op_sel_hi:[1,0,1]
	v_lshl_add_u64 v[202:203], v[202:203], 2, s[90:91]
	v_pk_mul_f32 v[154:155], v[218:219], v[154:155] op_sel:[1,0]
	v_pk_mul_f32 v[152:153], v[218:219], v[152:153] op_sel:[1,0]
	global_store_dwordx4 v[202:203], v[240:243], off
	v_pk_fma_f32 v[152:153], v[208:209], v[152:153], v[48:49]
	v_pk_fma_f32 v[154:155], v[206:207], v[154:155], v[50:51]
	v_add_u32_e32 v202, 0x8090, v194
	v_mov_b32_e32 v203, v159
	v_sub_f32_e32 v149, v149, v216
	v_sub_f32_e32 v148, v148, v216
	v_sub_f32_e32 v151, v151, v216
	v_sub_f32_e32 v150, v150, v216
	v_pk_fma_f32 v[154:155], v[130:131], s[78:79], v[154:155] op_sel_hi:[1,0,1]
	v_pk_fma_f32 v[152:153], v[128:129], s[78:79], v[152:153] op_sel_hi:[1,0,1]
	v_lshl_add_u64 v[202:203], v[202:203], 2, s[90:91]
	v_pk_mul_f32 v[150:151], v[216:217], v[150:151] op_sel:[1,0]
	v_pk_mul_f32 v[148:149], v[216:217], v[148:149] op_sel:[1,0]
	global_store_dwordx4 v[202:203], v[152:155], off
	v_pk_fma_f32 v[148:149], v[214:215], v[148:149], v[44:45]
	v_pk_fma_f32 v[150:151], v[212:213], v[150:151], v[46:47]
	v_add_u32_e32 v152, 0x10080, v194
	v_mov_b32_e32 v153, v159
	v_sub_f32_e32 v145, v145, v216
	v_sub_f32_e32 v144, v144, v216
	v_sub_f32_e32 v147, v147, v216
	v_sub_f32_e32 v146, v146, v216
	v_pk_fma_f32 v[150:151], v[134:135], s[78:79], v[150:151] op_sel_hi:[1,0,1]
	v_pk_fma_f32 v[148:149], v[132:133], s[78:79], v[148:149] op_sel_hi:[1,0,1]
	v_lshl_add_u64 v[152:153], v[152:153], 2, s[90:91]
	v_pk_mul_f32 v[146:147], v[216:217], v[146:147] op_sel:[1,0]
	v_pk_mul_f32 v[144:145], v[216:217], v[144:145] op_sel:[1,0]
	global_store_dwordx4 v[152:153], v[148:151], off
	v_pk_fma_f32 v[144:145], v[208:209], v[144:145], v[40:41]
	v_pk_fma_f32 v[146:147], v[206:207], v[146:147], v[42:43]
;     template <bool LN, int BJ, int LO, int HI> DI void batch(const f32x4 (&acc)[2][2][4][2], unsigned row0, unsigned col0, const f32x4 (&gv)[2], const f32x4 (&bv)[2]) const {
;         f32x4 r[HI - LO]; float mean[(HI - LO) / 2], rstd[(HI - LO) / 2];
; #pragma unroll
;         for (int i = LO; i < HI; ++i) { const int ai = i >> 3, m = (i >> 1) & 3, n = i & 1; const unsigned row = row0 + ai * HALF + m * 16;
;             if (n == 0) { mean[(i - LO) >> 1] = 0.f; rstd[(i - LO) >> 1] = 1.f;
;                 if (LN) { const float2 st = *(const float2*)(stats + row * 2u); mean[(i - LO) >> 1] = st.x; rstd[(i - LO) >> 1] = st.y; } }
;             r[i - LO] = *(const f32x4*)(src + (row * (unsigned)DM + col0 + BJ * HALF + n * 16)); }
; #pragma unroll
;         for (int i = LO; i < HI; ++i) { const int ai = i >> 3, m = (i >> 1) & 3, n = i & 1; const unsigned row = row0 + ai * HALF + m * 16;
;             *(f32x4*)(Y + (row * (unsigned)DM + col0 + BJ * HALF + n * 16)) = acc[ai][BJ][m][n] + ((r[i - LO] - mean[(i - LO) >> 1]) * rstd[(i - LO) >> 1]) * gv[n] + bv[n]; }
;         __builtin_amdgcn_sched_barrier(0);
;     }
	v_add_u32_e32 v148, 0x10090, v194
	v_mov_b32_e32 v149, v159
	v_sub_f32_e32 v141, v141, v200
	v_sub_f32_e32 v140, v140, v200
	v_sub_f32_e32 v143, v143, v200
	v_sub_f32_e32 v142, v142, v200
	v_pk_fma_f32 v[146:147], v[130:131], s[78:79], v[146:147] op_sel_hi:[1,0,1]
	v_pk_fma_f32 v[144:145], v[128:129], s[78:79], v[144:145] op_sel_hi:[1,0,1]
	v_lshl_add_u64 v[148:149], v[148:149], 2, s[90:91]
	v_pk_mul_f32 v[142:143], v[200:201], v[142:143] op_sel:[1,0]
	v_pk_mul_f32 v[140:141], v[200:201], v[140:141] op_sel:[1,0]
	global_store_dwordx4 v[148:149], v[144:147], off
	v_pk_fma_f32 v[140:141], v[214:215], v[140:141], v[36:37]
	v_pk_fma_f32 v[142:143], v[212:213], v[142:143], v[38:39]
	v_add_u32_e32 v144, 0x18080, v194
	v_mov_b32_e32 v145, v159
	v_sub_f32_e32 v137, v137, v200
	v_sub_f32_e32 v136, v136, v200
	v_sub_f32_e32 v139, v139, v200
	v_sub_f32_e32 v138, v138, v200
	v_pk_fma_f32 v[142:143], v[134:135], s[78:79], v[142:143] op_sel_hi:[1,0,1]
	v_pk_fma_f32 v[140:141], v[132:133], s[78:79], v[140:141] op_sel_hi:[1,0,1]
	v_lshl_add_u64 v[144:145], v[144:145], 2, s[90:91]
	v_pk_mul_f32 v[138:139], v[200:201], v[138:139] op_sel:[1,0]
	v_pk_mul_f32 v[136:137], v[200:201], v[136:137] op_sel:[1,0]
	global_store_dwordx4 v[144:145], v[140:143], off
	v_pk_fma_f32 v[136:137], v[208:209], v[136:137], v[32:33]
	v_pk_fma_f32 v[138:139], v[206:207], v[138:139], v[34:35]
	v_add_u32_e32 v140, 0x18090, v194
	v_mov_b32_e32 v141, v159
	v_pk_fma_f32 v[138:139], v[130:131], s[78:79], v[138:139] op_sel_hi:[1,0,1]
	v_pk_fma_f32 v[136:137], v[128:129], s[78:79], v[136:137] op_sel_hi:[1,0,1]
	v_lshl_add_u64 v[140:141], v[140:141], 2, s[90:91]
	global_store_dwordx4 v[140:141], v[136:139], off
	s_nop 1
	v_add_u32_e32 v136, v233, v230
	v_mov_b32_e32 v137, v159
	v_lshl_add_u64 v[136:137], v[136:137], 2, s[88:89]
	global_load_dwordx2 v[220:221], v[196:197], off
	global_load_dwordx4 v[216:219], v[136:137], off
	v_add_u32_e32 v136, v233, v229
	v_mov_b32_e32 v137, v159
	v_lshl_add_u64 v[136:137], v[136:137], 2, s[88:89]
	global_load_dwordx4 v[240:243], v[136:137], off
	global_load_dwordx2 v[200:201], v[198:199], off
	v_add_u32_e32 v136, v234, v230
	v_mov_b32_e32 v137, v159
	v_lshl_add_u64 v[136:137], v[136:137], 2, s[88:89]
	global_load_dwordx4 v[244:247], v[136:137], off
	v_add_u32_e32 v136, v234, v229
	v_mov_b32_e32 v137, v159
	v_lshl_add_u64 v[136:137], v[136:137], 2, s[88:89]
	global_load_dwordx4 v[152:155], v[136:137], off
	global_load_dwordx2 v[198:199], v[204:205], off
	v_add_u32_e32 v136, v237, v230
	v_mov_b32_e32 v137, v159
	v_lshl_add_u64 v[136:137], v[136:137], 2, s[88:89]
	global_load_dwordx4 v[148:151], v[136:137], off
	v_add_u32_e32 v136, v237, v229
	v_mov_b32_e32 v137, v159
	v_lshl_add_u64 v[136:137], v[136:137], 2, s[88:89]
	global_load_dwordx4 v[144:147], v[136:137], off
	global_load_dwordx2 v[196:197], v[210:211], off
	v_add_u32_e32 v136, v238, v230
	v_mov_b32_e32 v137, v159
	v_lshl_add_u64 v[136:137], v[136:137], 2, s[88:89]
	global_load_dwordx4 v[140:143], v[136:137], off
	v_add_u32_e32 v136, v238, v229
	v_mov_b32_e32 v137, v159
	v_lshl_add_u64 v[136:137], v[136:137], 2, s[88:89]
	global_load_dwordx4 v[136:139], v[136:137], off
	v_add_u32_e32 v210, 0x40080, v194
	v_mov_b32_e32 v211, v159
	v_lshl_add_u64 v[210:211], v[210:211], 2, s[90:91]
	s_waitcnt vmcnt(0)
;     template <bool LN, int BJ, int LO, int HI> DI void batch(const f32x4 (&acc)[2][2][4][2], unsigned row0, unsigned col0, const f32x4 (&gv)[2], const f32x4 (&bv)[2]) const {
;         f32x4 r[HI - LO]; float mean[(HI - LO) / 2], rstd[(HI - LO) / 2];
; #pragma unroll
;         for (int i = LO; i < HI; ++i) { const int ai = i >> 3, m = (i >> 1) & 3, n = i & 1; const unsigned row = row0 + ai * HALF + m * 16;
;             if (n == 0) { mean[(i - LO) >> 1] = 0.f; rstd[(i - LO) >> 1] = 1.f;
;                 if (LN) { const float2 st = *(const float2*)(stats + row * 2u); mean[(i - LO) >> 1] = st.x; rstd[(i - LO) >> 1] = st.y; } }
;             r[i - LO] = *(const f32x4*)(src + (row * (unsigned)DM + col0 + BJ * HALF + n * 16)); }
; #pragma unroll
;         for (int i = LO; i < HI; ++i) { const int ai = i >> 3, m = (i >> 1) & 3, n = i & 1; const unsigned row = row0 + ai * HALF + m * 16;
;             *(f32x4*)(Y + (row * (unsigned)DM + col0 + BJ * HALF + n * 16)) = acc[ai][BJ][m][n] + ((r[i - LO] - mean[(i - LO) >> 1]) * rstd[(i - LO) >> 1]) * gv[n] + bv[n]; }
;         __builtin_amdgcn_sched_barrier(0);
;     }
	v_sub_f32_e32 v203, v217, v220
	v_sub_f32_e32 v202, v216, v220
	v_sub_f32_e32 v205, v219, v220
	v_sub_f32_e32 v204, v218, v220
	v_pk_mul_f32 v[204:205], v[220:221], v[204:205] op_sel:[1,0]
	v_pk_mul_f32 v[202:203], v[220:221], v[202:203] op_sel:[1,0]
	v_pk_fma_f32 v[204:205], v[212:213], v[204:205], v[30:31]
	v_pk_fma_f32 v[202:203], v[214:215], v[202:203], v[28:29]
	v_pk_fma_f32 v[204:205], v[134:135], s[78:79], v[204:205] op_sel_hi:[1,0,1]
	v_pk_fma_f32 v[202:203], v[132:133], s[78:79], v[202:203] op_sel_hi:[1,0,1]
	global_store_dwordx4 v[210:211], v[202:205], off
	v_add_u32_e32 v210, 0x40090, v194
	v_mov_b32_e32 v211, v159
	v_sub_f32_e32 v203, v241, v220
	v_sub_f32_e32 v202, v240, v220
	v_sub_f32_e32 v205, v243, v220
	v_sub_f32_e32 v204, v242, v220
	v_pk_mul_f32 v[204:205], v[220:221], v[204:205] op_sel:[1,0]
	v_pk_mul_f32 v[202:203], v[220:221], v[202:203] op_sel:[1,0]
	v_pk_fma_f32 v[204:205], v[206:207], v[204:205], v[26:27]
	v_pk_fma_f32 v[202:203], v[208:209], v[202:203], v[24:25]
	v_pk_fma_f32 v[204:205], v[130:131], s[78:79], v[204:205] op_sel_hi:[1,0,1]
	v_pk_fma_f32 v[202:203], v[128:129], s[78:79], v[202:203] op_sel_hi:[1,0,1]
	v_lshl_add_u64 v[210:211], v[210:211], 2, s[90:91]
	global_store_dwordx4 v[210:211], v[202:205], off
	v_sub_f32_e32 v149, v149, v198
	v_sub_f32_e32 v148, v148, v198
	v_sub_f32_e32 v203, v245, v200
	v_sub_f32_e32 v202, v244, v200
	v_sub_f32_e32 v141, v141, v196
	v_sub_f32_e32 v140, v140, v196
	v_sub_f32_e32 v205, v247, v200
	v_sub_f32_e32 v204, v246, v200
	v_pk_mul_f32 v[202:203], v[200:201], v[202:203] op_sel:[1,0]
	v_sub_f32_e32 v151, v151, v198
	v_sub_f32_e32 v150, v150, v198
	v_pk_mul_f32 v[148:149], v[198:199], v[148:149] op_sel:[1,0]
	v_sub_f32_e32 v143, v143, v196
	v_sub_f32_e32 v142, v142, v196
	v_pk_mul_f32 v[140:141], v[196:197], v[140:141] op_sel:[1,0]
	v_pk_mul_f32 v[204:205], v[200:201], v[204:205] op_sel:[1,0]
	v_pk_fma_f32 v[202:203], v[214:215], v[202:203], v[20:21]
	v_sub_f32_e32 v153, v153, v200
	v_sub_f32_e32 v152, v152, v200
	v_sub_f32_e32 v155, v155, v200
	v_sub_f32_e32 v154, v154, v200
	v_pk_mul_f32 v[150:151], v[198:199], v[150:151] op_sel:[1,0]
	v_pk_fma_f32 v[148:149], v[214:215], v[148:149], v[12:13]
	v_pk_mul_f32 v[142:143], v[196:197], v[142:143] op_sel:[1,0]
	v_pk_fma_f32 v[140:141], v[214:215], v[140:141], v[4:5]
	v_pk_fma_f32 v[204:205], v[212:213], v[204:205], v[22:23]
	v_pk_fma_f32 v[202:203], v[132:133], s[78:79], v[202:203] op_sel_hi:[1,0,1]
	v_pk_mul_f32 v[154:155], v[200:201], v[154:155] op_sel:[1,0]
	v_pk_mul_f32 v[152:153], v[200:201], v[152:153] op_sel:[1,0]
	v_pk_fma_f32 v[150:151], v[212:213], v[150:151], v[14:15]
	v_pk_fma_f32 v[148:149], v[132:133], s[78:79], v[148:149] op_sel_hi:[1,0,1]
	v_pk_fma_f32 v[142:143], v[212:213], v[142:143], v[6:7]
	v_pk_fma_f32 v[132:133], v[132:133], s[78:79], v[140:141] op_sel_hi:[1,0,1]
	v_add_u32_e32 v140, 0x58080, v194
	v_mov_b32_e32 v141, v159
	v_pk_fma_f32 v[204:205], v[134:135], s[78:79], v[204:205] op_sel_hi:[1,0,1]
	v_pk_fma_f32 v[152:153], v[208:209], v[152:153], v[16:17]
	v_pk_fma_f32 v[154:155], v[206:207], v[154:155], v[18:19]
	v_add_u32_e32 v200, 0x48090, v194
	v_mov_b32_e32 v201, v159
	v_pk_fma_f32 v[150:151], v[134:135], s[78:79], v[150:151] op_sel_hi:[1,0,1]
	v_pk_fma_f32 v[134:135], v[134:135], s[78:79], v[142:143] op_sel_hi:[1,0,1]
	v_lshl_add_u64 v[140:141], v[140:141], 2, s[90:91]
	v_pk_fma_f32 v[154:155], v[130:131], s[78:79], v[154:155] op_sel_hi:[1,0,1]
	v_pk_fma_f32 v[152:153], v[128:129], s[78:79], v[152:153] op_sel_hi:[1,0,1]
	v_lshl_add_u64 v[200:201], v[200:201], 2, s[90:91]
	v_sub_f32_e32 v145, v145, v198
	v_sub_f32_e32 v144, v144, v198
	global_store_dwordx4 v[140:141], v[132:135], off
	global_store_dwordx4 v[200:201], v[152:155], off
	v_sub_f32_e32 v147, v147, v198
	v_sub_f32_e32 v133, v137, v196
	v_sub_f32_e32 v132, v136, v196
	v_add_u32_e32 v152, 0x50080, v194
	v_mov_b32_e32 v153, v159
	v_sub_f32_e32 v146, v146, v198
	v_pk_mul_f32 v[144:145], v[198:199], v[144:145] op_sel:[1,0]
	v_sub_f32_e32 v135, v139, v196
	v_sub_f32_e32 v134, v138, v196
	v_pk_mul_f32 v[132:133], v[196:197], v[132:133] op_sel:[1,0]
	v_lshl_add_u64 v[152:153], v[152:153], 2, s[90:91]
	v_pk_mul_f32 v[146:147], v[198:199], v[146:147] op_sel:[1,0]
	v_pk_fma_f32 v[144:145], v[208:209], v[144:145], v[8:9]
	v_pk_mul_f32 v[134:135], v[196:197], v[134:135] op_sel:[1,0]
	v_pk_fma_f32 v[132:133], v[208:209], v[132:133], v[0:1]
	v_add_u32_e32 v210, 0x48080, v194
	v_mov_b32_e32 v211, v159
	global_store_dwordx4 v[152:153], v[148:151], off
	v_pk_fma_f32 v[146:147], v[206:207], v[146:147], v[10:11]
	v_pk_fma_f32 v[144:145], v[128:129], s[78:79], v[144:145] op_sel_hi:[1,0,1]
	v_add_u32_e32 v148, 0x50090, v194
	v_mov_b32_e32 v149, v159
	v_pk_fma_f32 v[134:135], v[206:207], v[134:135], v[2:3]
	v_pk_fma_f32 v[128:129], v[128:129], s[78:79], v[132:133] op_sel_hi:[1,0,1]
	v_add_u32_e32 v132, 0x58090, v194
	v_mov_b32_e32 v133, v159
	v_lshl_add_u64 v[210:211], v[210:211], 2, s[90:91]
	v_pk_fma_f32 v[146:147], v[130:131], s[78:79], v[146:147] op_sel_hi:[1,0,1]
	v_lshl_add_u64 v[148:149], v[148:149], 2, s[90:91]
	v_pk_fma_f32 v[130:131], v[130:131], s[78:79], v[134:135] op_sel_hi:[1,0,1]
	v_lshl_add_u64 v[132:133], v[132:133], 2, s[90:91]
	global_store_dwordx4 v[210:211], v[202:205], off
	global_store_dwordx4 v[148:149], v[144:147], off
	global_store_dwordx4 v[132:133], v[128:131], off
	s_mov_b64 s[20:21], 0
	s_branch .LBB0_81

; #define PG8_STAGE(bufoff, gbase) do { _Pragma("unroll") for (int _i = 0; _i < 2; ++_i) \
;         __builtin_amdgcn_global_load_lds((const unsigned*)((const char*)(gbase) + voff[_i]), (LAS unsigned*)(lds + (bufoff) + ldsw + _i * 8192), 16, 0, 0); } while (0)
; #define PG8_LDA(dst, b, h) do { _Pragma("unroll") for (int m = 0; m < 4; ++m) _Pragma("unroll") for (int k = 0; k < 2; ++k) dst[m][k] = *(const LAS bf16x8*)(lds + PG8_SA(b, h) + aoff + m * 2048 + k * 1024); } while (0)
; #define PG8_LDB(dst, b, h) do { _Pragma("unroll") for (int n = 0; n < 2; ++n) _Pragma("unroll") for (int k = 0; k < 2; ++k) dst[n][k] = *(const LAS bf16x8*)(lds + PG8_SB(b, h) + boff + n * 2048 + k * 1024); } while (0)
; #define PG8_MMA(ai, bj, At, Bt) do { __builtin_amdgcn_s_setprio(1); _Pragma("unroll") for (int m = 0; m < 4; ++m) _Pragma("unroll") for (int n = 0; n < 2; ++n) _Pragma("unroll") for (int k = 0; k < 2; ++k) \
;         acc[ai][bj][m][n] = __builtin_amdgcn_mfma_f32_16x16x32_bf16(Bt[n][k], At[m][k], acc[ai][bj][m][n], 0, 0, 0); __builtin_amdgcn_s_setprio(0); } while (0)
; #define PG8_WAIT_L(n) asm volatile("s_waitcnt lgkmcnt(" #n ")" ::: "memory")
; #define PG8_BAR __builtin_amdgcn_s_barrier()
; #define PG8_SCHED __builtin_amdgcn_sched_barrier(0)
; template <class Epi>
; DI void gemm_phase(LAS unsigned char* lds, const Gemm g, const StaticOrder& S, const Epi& E) {
;     ...
;         for (int t = 0; t < nt; t += 2) {
;             const bool last = (t == nt - 2);
;             const char* a1 = cA + (size_t)(t + 1) * kstep;
;             const char* a2 = last ? nA : cA + (size_t)(t + 2) * kstep; const char* b2 = last ? nB : cB + (size_t)(t + 2) * kstep;
;             const char* a3 = a2 + kstep; const char* b3 = b2 + kstep;
;             PG8_LDB(B0, 0, 0); PG8_SCHED; PG8_LDA(At, 0, 0); PG8_STAGE(PG8_SA(1, 1), a1 + hstep);
;             PG8_WAIT_L(8); PG8_BAR; PG8_WAIT_L(0); PG8_MMA(0, 0, At, B0); PG8_BAR; PG8_SCHED;
;             PG8_LDB(B1, 0, 1); PG8_STAGE(PG8_SB(0, 0), b2);
;             PG8_BAR; PG8_WAIT_L(0); PG8_MMA(0, 1, At, B1); PG8_BAR;
;             PG8_LDA(At, 0, 1); PG8_STAGE(PG8_SA(0, 0), a2);
;             PG8_BAR; PG8_WAIT_L(0); PG8_MMA(1, 0, At, B0); PG8_BAR; PG8_SCHED;
.LBB0_134:
	ds_read_b128 v[96:99], v199
	ds_read_b128 v[100:103], v199 offset:1024
	ds_read_b128 v[136:139], v199 offset:2048
	ds_read_b128 v[148:151], v199 offset:3072
	ds_read_b128 v[152:155], v201
	ds_read_b128 v[186:189], v201 offset:1024
	ds_read_b128 v[190:193], v201 offset:2048
	ds_read_b128 v[194:197], v201 offset:3072
	ds_read_b128 v[202:205], v201 offset:4096
	ds_read_b128 v[206:209], v201 offset:5120
	ds_read_b128 v[210:213], v201 offset:6144
	ds_read_b128 v[214:217], v201 offset:7168
	s_add_u32 s18, s16, 0x100
	s_addc_u32 s19, s17, 0
	s_add_i32 s39, 0, 0x10000
	s_cmpk_eq_i32 s33, 0x54
	s_cselect_b32 s23, s9, s19
	s_cselect_b32 s22, s8, s18
	s_cselect_b32 s21, s11, s5
	s_cselect_b32 s20, s10, s4
	s_add_i32 m0, s28, 0xc000
	s_nop 0
	global_load_lds_dwordx4 v144, s[16:17]
	s_add_i32 m0, s28, 0xe000
	s_nop 0
	global_load_lds_dwordx4 v146, s[16:17]
	s_waitcnt lgkmcnt(8)
	s_setprio 1
	s_barrier
	s_waitcnt lgkmcnt(0)
	v_mfma_f32_16x16x32_bf16 v[132:135], v[96:99], v[152:155], v[132:135]
	v_mfma_f32_16x16x32_bf16 v[128:131], v[136:139], v[152:155], v[128:131]
	v_mfma_f32_16x16x32_bf16 v[124:127], v[96:99], v[190:193], v[124:127]
	v_mfma_f32_16x16x32_bf16 v[120:123], v[136:139], v[190:193], v[120:123]
	v_mfma_f32_16x16x32_bf16 v[116:119], v[96:99], v[202:205], v[116:119]
	v_mfma_f32_16x16x32_bf16 v[112:115], v[136:139], v[202:205], v[112:115]
	v_mfma_f32_16x16x32_bf16 v[108:111], v[96:99], v[210:213], v[108:111]
	v_mfma_f32_16x16x32_bf16 v[104:107], v[136:139], v[210:213], v[104:107]
	v_mfma_f32_16x16x32_bf16 v[132:135], v[100:103], v[186:189], v[132:135]
	v_mfma_f32_16x16x32_bf16 v[128:131], v[148:151], v[186:189], v[128:131]
	v_mfma_f32_16x16x32_bf16 v[124:127], v[100:103], v[194:197], v[124:127]
	v_mfma_f32_16x16x32_bf16 v[120:123], v[148:151], v[194:197], v[120:123]
	v_mfma_f32_16x16x32_bf16 v[116:119], v[100:103], v[206:209], v[116:119]
	v_mfma_f32_16x16x32_bf16 v[112:115], v[148:151], v[206:209], v[112:115]
	v_mfma_f32_16x16x32_bf16 v[108:111], v[100:103], v[214:217], v[108:111]
	s_setprio 0
	v_mfma_f32_16x16x32_bf16 v[104:107], v[148:151], v[214:217], v[104:107]
	s_barrier
	ds_read_b128 v[226:229], v199 offset:16384
	ds_read_b128 v[230:233], v199 offset:17408
	ds_read_b128 v[234:237], v199 offset:18432
	ds_read_b128 v[238:241], v199 offset:19456
	s_add_i32 s40, 0, 0x14000
	s_add_i32 s16, s39, s27
	s_mov_b32 m0, s16
	s_nop 0
	global_load_lds_dwordx4 v142, s[20:21]
	s_add_i32 m0, s16, 0x2000
	s_nop 0
	global_load_lds_dwordx4 v140, s[20:21]
	s_waitcnt lgkmcnt(0)
	s_setprio 1
	s_barrier
	v_mfma_f32_16x16x32_bf16 v[60:63], v[226:229], v[152:155], v[60:63]
	v_mfma_f32_16x16x32_bf16 v[56:59], v[234:237], v[152:155], v[56:59]
	v_mfma_f32_16x16x32_bf16 v[52:55], v[226:229], v[190:193], v[52:55]
	v_mfma_f32_16x16x32_bf16 v[48:51], v[234:237], v[190:193], v[48:51]
	v_mfma_f32_16x16x32_bf16 v[44:47], v[226:229], v[202:205], v[44:47]
	v_mfma_f32_16x16x32_bf16 v[40:43], v[234:237], v[202:205], v[40:43]
	v_mfma_f32_16x16x32_bf16 v[36:39], v[226:229], v[210:213], v[36:39]
	v_mfma_f32_16x16x32_bf16 v[32:35], v[234:237], v[210:213], v[32:35]
	v_mfma_f32_16x16x32_bf16 v[60:63], v[230:233], v[186:189], v[60:63]
	s_mov_b32 m0, s28
	v_mfma_f32_16x16x32_bf16 v[56:59], v[238:241], v[186:189], v[56:59]
	v_mfma_f32_16x16x32_bf16 v[52:55], v[230:233], v[194:197], v[52:55]
	v_mfma_f32_16x16x32_bf16 v[48:51], v[238:241], v[194:197], v[48:51]
	v_mfma_f32_16x16x32_bf16 v[44:47], v[230:233], v[206:209], v[44:47]
	v_mfma_f32_16x16x32_bf16 v[40:43], v[238:241], v[206:209], v[40:43]
	v_mfma_f32_16x16x32_bf16 v[36:39], v[230:233], v[214:217], v[36:39]
	s_setprio 0
	v_mfma_f32_16x16x32_bf16 v[32:35], v[238:241], v[214:217], v[32:35]
	s_barrier
	ds_read_b128 v[152:155], v201 offset:16384
	ds_read_b128 v[186:189], v201 offset:17408
	ds_read_b128 v[190:193], v201 offset:18432
	ds_read_b128 v[194:197], v201 offset:19456
	ds_read_b128 v[202:205], v201 offset:20480
	ds_read_b128 v[206:209], v201 offset:21504
	ds_read_b128 v[210:213], v201 offset:22528
	ds_read_b128 v[214:217], v201 offset:23552
	global_load_lds_dwordx4 v142, s[22:23]
	s_mov_b64 s[100:101], s[22:23]
	s_mov_b32 m0, s29
	s_nop 0
	global_load_lds_dwordx4 v140, s[22:23]
	s_waitcnt lgkmcnt(0)
	s_setprio 1
	s_barrier
	v_mfma_f32_16x16x32_bf16 v[92:95], v[96:99], v[152:155], v[92:95]
	v_mfma_f32_16x16x32_bf16 v[88:91], v[136:139], v[152:155], v[88:91]
	v_mfma_f32_16x16x32_bf16 v[84:87], v[96:99], v[190:193], v[84:87]
	v_mfma_f32_16x16x32_bf16 v[80:83], v[136:139], v[190:193], v[80:83]
	v_mfma_f32_16x16x32_bf16 v[76:79], v[96:99], v[202:205], v[76:79]
	v_mfma_f32_16x16x32_bf16 v[72:75], v[136:139], v[202:205], v[72:75]
	v_mfma_f32_16x16x32_bf16 v[68:71], v[96:99], v[210:213], v[68:71]
	v_mfma_f32_16x16x32_bf16 v[64:67], v[136:139], v[210:213], v[64:67]
	v_mfma_f32_16x16x32_bf16 v[92:95], v[100:103], v[186:189], v[92:95]
	v_mfma_f32_16x16x32_bf16 v[88:91], v[148:151], v[186:189], v[88:91]
	v_mfma_f32_16x16x32_bf16 v[84:87], v[100:103], v[194:197], v[84:87]
	v_mfma_f32_16x16x32_bf16 v[80:83], v[148:151], v[194:197], v[80:83]
	v_mfma_f32_16x16x32_bf16 v[76:79], v[100:103], v[206:209], v[76:79]
	v_mfma_f32_16x16x32_bf16 v[72:75], v[148:151], v[206:209], v[72:75]
	v_mfma_f32_16x16x32_bf16 v[68:71], v[100:103], v[214:217], v[68:71]
	s_setprio 0
	v_mfma_f32_16x16x32_bf16 v[64:67], v[148:151], v[214:217], v[64:67]
	s_barrier
	s_add_u32 s16, s20, 0x160000
	s_addc_u32 s17, s21, 0
	s_add_i32 s39, s40, s27
	s_mov_b32 m0, s39
	s_nop 0
	global_load_lds_dwordx4 v142, s[16:17]
	s_add_i32 m0, s39, 0x2000
	s_nop 0
	global_load_lds_dwordx4 v140, s[16:17]
	s_waitcnt vmcnt(6)
	s_setprio 1
	s_barrier
; #define PG8_STAGE(bufoff, gbase) do { _Pragma("unroll") for (int _i = 0; _i < 2; ++_i) \
;         __builtin_amdgcn_global_load_lds((const unsigned*)((const char*)(gbase) + voff[_i]), (LAS unsigned*)(lds + (bufoff) + ldsw + _i * 8192), 16, 0, 0); } while (0)
; #define PG8_LDA(dst, b, h) do { _Pragma("unroll") for (int m = 0; m < 4; ++m) _Pragma("unroll") for (int k = 0; k < 2; ++k) dst[m][k] = *(const LAS bf16x8*)(lds + PG8_SA(b, h) + aoff + m * 2048 + k * 1024); } while (0)
; #define PG8_LDB(dst, b, h) do { _Pragma("unroll") for (int n = 0; n < 2; ++n) _Pragma("unroll") for (int k = 0; k < 2; ++k) dst[n][k] = *(const LAS bf16x8*)(lds + PG8_SB(b, h) + boff + n * 2048 + k * 1024); } while (0)
; #define PG8_MMA(ai, bj, At, Bt) do { __builtin_amdgcn_s_setprio(1); _Pragma("unroll") for (int m = 0; m < 4; ++m) _Pragma("unroll") for (int n = 0; n < 2; ++n) _Pragma("unroll") for (int k = 0; k < 2; ++k) \
;         acc[ai][bj][m][n] = __builtin_amdgcn_mfma_f32_16x16x32_bf16(Bt[n][k], At[m][k], acc[ai][bj][m][n], 0, 0, 0); __builtin_amdgcn_s_setprio(0); } while (0)
; #define PG8_WAIT_V(n) asm volatile("s_waitcnt vmcnt(" #n ")" ::: "memory")
; #define PG8_WAIT_L(n) asm volatile("s_waitcnt lgkmcnt(" #n ")" ::: "memory")
; #define PG8_BAR __builtin_amdgcn_s_barrier()
; #define PG8_SCHED __builtin_amdgcn_sched_barrier(0)
; template <class Epi>
; DI void gemm_phase(LAS unsigned char* lds, const Gemm g, const StaticOrder& S, const Epi& E) {
;     ...
;             PG8_LDA(At, 0, 1); PG8_STAGE(PG8_SA(0, 0), a2);
;             PG8_BAR; PG8_WAIT_L(0); PG8_MMA(1, 0, At, B0); PG8_BAR; PG8_SCHED;
;             PG8_STAGE(PG8_SB(0, 1), b2 + hstep);
;             PG8_WAIT_V(6); PG8_BAR; PG8_MMA(1, 1, At, B1); PG8_BAR;
;             PG8_LDB(B0, 1, 0); PG8_SCHED; PG8_LDA(At, 1, 0); PG8_STAGE(PG8_SA(0, 1), a2 + hstep);
;             PG8_WAIT_L(8); PG8_BAR; PG8_WAIT_L(0); PG8_MMA(0, 0, At, B0); PG8_BAR; PG8_SCHED;
;             PG8_LDB(B1, 1, 1); PG8_STAGE(PG8_SB(1, 0), b3);
;             PG8_BAR; PG8_WAIT_L(0); PG8_MMA(0, 1, At, B1); PG8_BAR;
;             PG8_LDA(At, 1, 1); PG8_STAGE(PG8_SA(1, 0), a3);
;             PG8_BAR; PG8_WAIT_L(0); PG8_MMA(1, 0, At, B0); PG8_BAR; PG8_SCHED;
;             PG8_STAGE(PG8_SB(1, 1), b3 + hstep);
	v_mfma_f32_16x16x32_bf16 v[28:31], v[226:229], v[152:155], v[28:31]
	v_mfma_f32_16x16x32_bf16 v[24:27], v[234:237], v[152:155], v[24:27]
	v_mfma_f32_16x16x32_bf16 v[20:23], v[226:229], v[190:193], v[20:23]
	v_mfma_f32_16x16x32_bf16 v[16:19], v[234:237], v[190:193], v[16:19]
	v_mfma_f32_16x16x32_bf16 v[12:15], v[226:229], v[202:205], v[12:15]
	v_mfma_f32_16x16x32_bf16 v[8:11], v[234:237], v[202:205], v[8:11]
	v_mfma_f32_16x16x32_bf16 v[4:7], v[226:229], v[210:213], v[4:7]
	v_mfma_f32_16x16x32_bf16 v[0:3], v[234:237], v[210:213], v[0:3]
	v_mfma_f32_16x16x32_bf16 v[28:31], v[230:233], v[186:189], v[28:31]
	s_add_i32 s39, 0, 0x18000
	v_mfma_f32_16x16x32_bf16 v[24:27], v[238:241], v[186:189], v[24:27]
	v_mfma_f32_16x16x32_bf16 v[20:23], v[230:233], v[194:197], v[20:23]
	v_mfma_f32_16x16x32_bf16 v[16:19], v[238:241], v[194:197], v[16:19]
	v_mfma_f32_16x16x32_bf16 v[12:15], v[230:233], v[206:209], v[12:15]
	v_mfma_f32_16x16x32_bf16 v[8:11], v[238:241], v[206:209], v[8:11]
	v_mfma_f32_16x16x32_bf16 v[4:7], v[230:233], v[214:217], v[4:7]
	s_setprio 0
	v_mfma_f32_16x16x32_bf16 v[0:3], v[238:241], v[214:217], v[0:3]
	s_barrier
	ds_read_b128 v[96:99], v199 offset:32768
	ds_read_b128 v[100:103], v199 offset:33792
	ds_read_b128 v[136:139], v199 offset:34816
	ds_read_b128 v[148:151], v199 offset:35840
	ds_read_b128 v[152:155], v201 offset:32768
	ds_read_b128 v[186:189], v201 offset:33792
	ds_read_b128 v[190:193], v201 offset:34816
	ds_read_b128 v[194:197], v201 offset:35840
	ds_read_b128 v[202:205], v201 offset:36864
	ds_read_b128 v[206:209], v201 offset:37888
	ds_read_b128 v[210:213], v201 offset:38912
	ds_read_b128 v[214:217], v201 offset:39936
	s_add_u32 s16, s22, 0x160000
	s_addc_u32 s17, s23, 0
	s_mov_b32 m0, s30
	s_nop 0
	global_load_lds_dwordx4 v142, s[16:17]
	s_mov_b32 m0, s31
	s_nop 0
	global_load_lds_dwordx4 v140, s[16:17]
	s_waitcnt lgkmcnt(8)
	s_setprio 1
	s_barrier
	s_waitcnt lgkmcnt(0)
	v_mfma_f32_16x16x32_bf16 v[132:135], v[96:99], v[152:155], v[132:135]
	v_mfma_f32_16x16x32_bf16 v[128:131], v[136:139], v[152:155], v[128:131]
	v_mfma_f32_16x16x32_bf16 v[124:127], v[96:99], v[190:193], v[124:127]
	v_mfma_f32_16x16x32_bf16 v[120:123], v[136:139], v[190:193], v[120:123]
	v_mfma_f32_16x16x32_bf16 v[116:119], v[96:99], v[202:205], v[116:119]
	v_mfma_f32_16x16x32_bf16 v[112:115], v[136:139], v[202:205], v[112:115]
	v_mfma_f32_16x16x32_bf16 v[108:111], v[96:99], v[210:213], v[108:111]
	v_mfma_f32_16x16x32_bf16 v[104:107], v[136:139], v[210:213], v[104:107]
	v_mfma_f32_16x16x32_bf16 v[132:135], v[100:103], v[186:189], v[132:135]
	v_mfma_f32_16x16x32_bf16 v[128:131], v[148:151], v[186:189], v[128:131]
	v_mfma_f32_16x16x32_bf16 v[124:127], v[100:103], v[194:197], v[124:127]
	v_mfma_f32_16x16x32_bf16 v[120:123], v[148:151], v[194:197], v[120:123]
	v_mfma_f32_16x16x32_bf16 v[116:119], v[100:103], v[206:209], v[116:119]
	v_mfma_f32_16x16x32_bf16 v[112:115], v[148:151], v[206:209], v[112:115]
	v_mfma_f32_16x16x32_bf16 v[108:111], v[100:103], v[214:217], v[108:111]
	s_setprio 0
	v_mfma_f32_16x16x32_bf16 v[104:107], v[148:151], v[214:217], v[104:107]
	s_barrier
	ds_read_b128 v[226:229], v199 offset:49152
	ds_read_b128 v[230:233], v199 offset:50176
	ds_read_b128 v[234:237], v199 offset:51200
	ds_read_b128 v[238:241], v199 offset:52224
	s_add_i32 s22, 0, 0x1c000
	s_add_i32 s16, s39, s27
	s_add_i32 m0, s16, 0xffffff80
	s_nop 0
	global_load_lds_dwordx4 v142, s[20:21] offset:128
	s_add_i32 m0, s16, 0x1f80
	s_nop 0
	global_load_lds_dwordx4 v140, s[20:21] offset:128
	s_waitcnt lgkmcnt(0)
	s_setprio 1
	s_barrier
	v_mfma_f32_16x16x32_bf16 v[60:63], v[226:229], v[152:155], v[60:63]
	v_mfma_f32_16x16x32_bf16 v[56:59], v[234:237], v[152:155], v[56:59]
	v_mfma_f32_16x16x32_bf16 v[52:55], v[226:229], v[190:193], v[52:55]
	v_mfma_f32_16x16x32_bf16 v[48:51], v[234:237], v[190:193], v[48:51]
	v_mfma_f32_16x16x32_bf16 v[44:47], v[226:229], v[202:205], v[44:47]
	v_mfma_f32_16x16x32_bf16 v[40:43], v[234:237], v[202:205], v[40:43]
	v_mfma_f32_16x16x32_bf16 v[36:39], v[226:229], v[210:213], v[36:39]
	v_mfma_f32_16x16x32_bf16 v[32:35], v[234:237], v[210:213], v[32:35]
	v_mfma_f32_16x16x32_bf16 v[60:63], v[230:233], v[186:189], v[60:63]
	s_add_i32 m0, s34, 0xffffff80
	v_mfma_f32_16x16x32_bf16 v[56:59], v[238:241], v[186:189], v[56:59]
	v_mfma_f32_16x16x32_bf16 v[52:55], v[230:233], v[194:197], v[52:55]
	v_mfma_f32_16x16x32_bf16 v[48:51], v[238:241], v[194:197], v[48:51]
	v_mfma_f32_16x16x32_bf16 v[44:47], v[230:233], v[206:209], v[44:47]
	v_mfma_f32_16x16x32_bf16 v[40:43], v[238:241], v[206:209], v[40:43]
	v_mfma_f32_16x16x32_bf16 v[36:39], v[230:233], v[214:217], v[36:39]
	s_setprio 0
	v_mfma_f32_16x16x32_bf16 v[32:35], v[238:241], v[214:217], v[32:35]
	s_barrier
	ds_read_b128 v[152:155], v201 offset:49152
	ds_read_b128 v[186:189], v201 offset:50176
	ds_read_b128 v[190:193], v201 offset:51200
	ds_read_b128 v[194:197], v201 offset:52224
	ds_read_b128 v[202:205], v201 offset:53248
	ds_read_b128 v[206:209], v201 offset:54272
	ds_read_b128 v[210:213], v201 offset:55296
	ds_read_b128 v[214:217], v201 offset:56320
	global_load_lds_dwordx4 v142, s[100:101] offset:128
	s_add_i32 m0, s35, 0xffffff80
	s_nop 0
	global_load_lds_dwordx4 v140, s[100:101] offset:128
	s_waitcnt lgkmcnt(0)
	s_setprio 1
	s_barrier
; #define PG8_STAGE(bufoff, gbase) do { _Pragma("unroll") for (int _i = 0; _i < 2; ++_i) \
;         __builtin_amdgcn_global_load_lds((const unsigned*)((const char*)(gbase) + voff[_i]), (LAS unsigned*)(lds + (bufoff) + ldsw + _i * 8192), 16, 0, 0); } while (0)
; #define PG8_MMA(ai, bj, At, Bt) do { __builtin_amdgcn_s_setprio(1); _Pragma("unroll") for (int m = 0; m < 4; ++m) _Pragma("unroll") for (int n = 0; n < 2; ++n) _Pragma("unroll") for (int k = 0; k < 2; ++k) \
;         acc[ai][bj][m][n] = __builtin_amdgcn_mfma_f32_16x16x32_bf16(Bt[n][k], At[m][k], acc[ai][bj][m][n], 0, 0, 0); __builtin_amdgcn_s_setprio(0); } while (0)
; #define PG8_WAIT_V(n) asm volatile("s_waitcnt vmcnt(" #n ")" ::: "memory")
; #define PG8_BAR __builtin_amdgcn_s_barrier()
; template <class Epi>
; DI void gemm_phase(LAS unsigned char* lds, const Gemm g, const StaticOrder& S, const Epi& E) {
;     ...
;             PG8_STAGE(PG8_SB(1, 1), b3 + hstep);
;             PG8_WAIT_V(6); PG8_BAR; PG8_MMA(1, 1, At, B1); PG8_BAR;
;         }
;         E(acc, cur, wr, wc, fr, fq);
;         if (!has_next) break;
;     template <bool LN, int BJ> DI void load_gb(unsigned col0, f32x4 (&gv)[2], f32x4 (&bv)[2]) const {
; #pragma unroll
;         for (int n = 0; n < 2; ++n) {
;             if (LN) { gv[n] = *(const f32x4*)(gam + col0 + BJ * HALF + n * 16) * ALPHA; bv[n] = *(const f32x4*)(bet + col0 + BJ * HALF + n * 16) * ALPHA; }
;             else { gv[n] = (f32x4){ALPHA, ALPHA, ALPHA, ALPHA}; bv[n] = (f32x4){0.f, 0.f, 0.f, 0.f}; }
;         }
;     }
;     template <bool LN> DI void run(const f32x4 (&acc)[2][2][4][2], const Unit& u, int wr, int wc, int fr, int fq) const {
;         const unsigned row0 = u.pm * BM + wr * 64 + fr, col0 = u.pn * BM + wc * 32 + 4 * fq;
;         f32x4 gv[2], bv[2];
;         load_gb<LN, 0>(col0, gv, bv);
;         batch<LN, 0, 0, 4>(acc, row0, col0, gv, bv);
	v_mfma_f32_16x16x32_bf16 v[92:95], v[96:99], v[152:155], v[92:95]
	v_mfma_f32_16x16x32_bf16 v[88:91], v[136:139], v[152:155], v[88:91]
	v_mfma_f32_16x16x32_bf16 v[84:87], v[96:99], v[190:193], v[84:87]
	v_mfma_f32_16x16x32_bf16 v[80:83], v[136:139], v[190:193], v[80:83]
	v_mfma_f32_16x16x32_bf16 v[76:79], v[96:99], v[202:205], v[76:79]
	v_mfma_f32_16x16x32_bf16 v[72:75], v[136:139], v[202:205], v[72:75]
	v_mfma_f32_16x16x32_bf16 v[68:71], v[96:99], v[210:213], v[68:71]
	v_mfma_f32_16x16x32_bf16 v[64:67], v[136:139], v[210:213], v[64:67]
	v_mfma_f32_16x16x32_bf16 v[92:95], v[100:103], v[186:189], v[92:95]
	v_mfma_f32_16x16x32_bf16 v[88:91], v[148:151], v[186:189], v[88:91]
	v_mfma_f32_16x16x32_bf16 v[84:87], v[100:103], v[194:197], v[84:87]
	v_mfma_f32_16x16x32_bf16 v[80:83], v[148:151], v[194:197], v[80:83]
	v_mfma_f32_16x16x32_bf16 v[76:79], v[100:103], v[206:209], v[76:79]
	v_mfma_f32_16x16x32_bf16 v[72:75], v[148:151], v[206:209], v[72:75]
	v_mfma_f32_16x16x32_bf16 v[68:71], v[100:103], v[214:217], v[68:71]
	s_setprio 0
	v_mfma_f32_16x16x32_bf16 v[64:67], v[148:151], v[214:217], v[64:67]
	s_barrier
	s_add_u32 s16, s20, 0x160080
	s_addc_u32 s17, s21, 0
	s_add_i32 s20, s22, s27
	s_mov_b32 m0, s20
	s_nop 0
	global_load_lds_dwordx4 v142, s[16:17]
	s_add_i32 m0, s20, 0x2000
	s_nop 0
	global_load_lds_dwordx4 v140, s[16:17]
	s_waitcnt vmcnt(6)
	s_setprio 1
	s_barrier
	v_mfma_f32_16x16x32_bf16 v[28:31], v[226:229], v[152:155], v[28:31]
	v_mfma_f32_16x16x32_bf16 v[24:27], v[234:237], v[152:155], v[24:27]
	v_mfma_f32_16x16x32_bf16 v[20:23], v[226:229], v[190:193], v[20:23]
	v_mfma_f32_16x16x32_bf16 v[16:19], v[234:237], v[190:193], v[16:19]
	v_mfma_f32_16x16x32_bf16 v[12:15], v[226:229], v[202:205], v[12:15]
	v_mfma_f32_16x16x32_bf16 v[8:11], v[234:237], v[202:205], v[8:11]
	v_mfma_f32_16x16x32_bf16 v[4:7], v[226:229], v[210:213], v[4:7]
	v_mfma_f32_16x16x32_bf16 v[0:3], v[234:237], v[210:213], v[0:3]
	v_mfma_f32_16x16x32_bf16 v[28:31], v[230:233], v[186:189], v[28:31]
	s_add_i32 s33, s33, 2
	v_mfma_f32_16x16x32_bf16 v[24:27], v[238:241], v[186:189], v[24:27]
	s_add_u32 s4, s4, 0x100
	v_mfma_f32_16x16x32_bf16 v[20:23], v[230:233], v[194:197], v[20:23]
	s_addc_u32 s5, s5, 0
	v_mfma_f32_16x16x32_bf16 v[16:19], v[238:241], v[194:197], v[16:19]
	s_cmpk_gt_u32 s33, 0x55
	v_mfma_f32_16x16x32_bf16 v[12:15], v[230:233], v[206:209], v[12:15]
	s_mov_b64 s[16:17], s[18:19]
	v_mfma_f32_16x16x32_bf16 v[8:11], v[238:241], v[206:209], v[8:11]
	v_mfma_f32_16x16x32_bf16 v[4:7], v[230:233], v[214:217], v[4:7]
	s_setprio 0
	v_mfma_f32_16x16x32_bf16 v[0:3], v[238:241], v[214:217], v[0:3]
	s_barrier
	s_cbranch_scc0 .LBB0_134
	v_lshl_or_b32 v158, s2, 8, v200
	v_lshlrev_b64 v[100:101], 2, v[158:159]
	v_lshl_add_u64 v[150:151], s[12:13], 0, v[100:101]
	global_load_dwordx4 v[96:99], v[150:151], off
	v_lshl_add_u64 v[152:153], s[14:15], 0, v[100:101]
	v_lshl_add_u32 v203, s3, 8, v198
	v_lshlrev_b32_e32 v202, 11, v203
	v_add_u32_e32 v148, v202, v158
	v_mov_b32_e32 v149, v159
	v_lshlrev_b32_e32 v136, 1, v203
	v_mov_b32_e32 v137, v159
	v_lshlrev_b64 v[220:221], 2, v[148:149]
	v_lshl_add_u64 v[154:155], v[136:137], 2, s[96:97]
	v_lshl_add_u64 v[136:137], s[90:91], 0, v[220:221]
	v_or_b32_e32 v204, 16, v158
	v_or_b32_e32 v138, 16, v203
	v_lshlrev_b32_e32 v149, 11, v138
	s_waitcnt vmcnt(0)
	v_pk_mul_f32 v[192:193], v[98:99], s[78:79] op_sel_hi:[1,0]
	v_pk_mul_f32 v[194:195], v[96:97], s[78:79] op_sel_hi:[1,0]
	global_load_dwordx4 v[100:103], v[152:153], off
	global_load_dwordx4 v[96:99], v[150:151], off offset:64
	global_load_dwordx2 v[218:219], v[154:155], off
	global_load_dwordx4 v[206:209], v[136:137], off
	v_add_u32_e32 v136, v202, v204
	v_mov_b32_e32 v137, v159
	v_lshl_add_u64 v[136:137], v[136:137], 2, s[90:91]
	global_load_dwordx4 v[210:213], v[136:137], off
	v_lshlrev_b32_e32 v136, 1, v138
	v_mov_b32_e32 v137, v159
	v_lshl_add_u64 v[186:187], v[136:137], 2, s[96:97]
	v_add_u32_e32 v136, v149, v158
	v_lshl_add_u64 v[136:137], v[136:137], 2, s[90:91]
	global_load_dwordx2 v[196:197], v[186:187], off
	global_load_dwordx4 v[214:217], v[136:137], off
	v_add_u32_e32 v136, v149, v204
	v_mov_b32_e32 v137, v159
	v_lshl_add_u64 v[136:137], v[136:137], 2, s[90:91]
	global_load_dwordx4 v[136:139], v[136:137], off
	s_waitcnt vmcnt(0)
	v_pk_mul_f32 v[188:189], v[98:99], s[78:79] op_sel_hi:[1,0]
	v_pk_mul_f32 v[190:191], v[96:97], s[78:79] op_sel_hi:[1,0]
	global_load_dwordx4 v[96:99], v[152:153], off offset:64
	v_sub_f32_e32 v207, v207, v218
	v_sub_f32_e32 v206, v206, v218
	v_sub_f32_e32 v209, v209, v218
	v_sub_f32_e32 v208, v208, v218
	v_pk_mul_f32 v[208:209], v[218:219], v[208:209] op_sel:[1,0]
	v_pk_mul_f32 v[206:207], v[218:219], v[206:207] op_sel:[1,0]
	v_pk_fma_f32 v[134:135], v[192:193], v[208:209], v[134:135]
	v_pk_fma_f32 v[132:133], v[194:195], v[206:207], v[132:133]
	v_pk_fma_f32 v[134:135], v[102:103], s[78:79], v[134:135] op_sel_hi:[1,0,1]
	v_pk_fma_f32 v[132:133], v[100:101], s[78:79], v[132:133] op_sel_hi:[1,0,1]
	v_lshl_add_u64 v[206:207], s[88:89], 0, v[220:221]
	global_store_dwordx4 v[206:207], v[132:135], off
	s_nop 1
	v_sub_f32_e32 v133, v211, v218
	v_sub_f32_e32 v132, v210, v218
	v_sub_f32_e32 v135, v213, v218
	v_sub_f32_e32 v134, v212, v218
	v_pk_mul_f32 v[134:135], v[218:219], v[134:135] op_sel:[1,0]
	v_pk_mul_f32 v[132:133], v[218:219], v[132:133] op_sel:[1,0]
	v_pk_fma_f32 v[130:131], v[188:189], v[134:135], v[130:131]
	v_pk_fma_f32 v[128:129], v[190:191], v[132:133], v[128:129]
	v_or_b32_e32 v132, 16, v148
	v_mov_b32_e32 v133, v159
	v_lshl_add_u64 v[132:133], v[132:133], 2, s[88:89]
	s_waitcnt vmcnt(0)
;     template <bool LN, int BJ, int LO, int HI> DI void batch(const f32x4 (&acc)[2][2][4][2], unsigned row0, unsigned col0, const f32x4 (&gv)[2], const f32x4 (&bv)[2]) const {
;         f32x4 r[HI - LO]; float mean[(HI - LO) / 2], rstd[(HI - LO) / 2];
; #pragma unroll
;         for (int i = LO; i < HI; ++i) { const int ai = i >> 3, m = (i >> 1) & 3, n = i & 1; const unsigned row = row0 + ai * HALF + m * 16;
;             if (n == 0) { mean[(i - LO) >> 1] = 0.f; rstd[(i - LO) >> 1] = 1.f;
;                 if (LN) { const float2 st = *(const float2*)(stats + row * 2u); mean[(i - LO) >> 1] = st.x; rstd[(i - LO) >> 1] = st.y; } }
;             r[i - LO] = *(const f32x4*)(src + (row * (unsigned)DM + col0 + BJ * HALF + n * 16)); }
; #pragma unroll
;         for (int i = LO; i < HI; ++i) { const int ai = i >> 3, m = (i >> 1) & 3, n = i & 1; const unsigned row = row0 + ai * HALF + m * 16;
;             *(f32x4*)(Y + (row * (unsigned)DM + col0 + BJ * HALF + n * 16)) = acc[ai][BJ][m][n] + ((r[i - LO] - mean[(i - LO) >> 1]) * rstd[(i - LO) >> 1]) * gv[n] + bv[n]; }
	v_pk_fma_f32 v[130:131], v[98:99], s[78:79], v[130:131] op_sel_hi:[1,0,1]
	v_pk_fma_f32 v[128:129], v[96:97], s[78:79], v[128:129] op_sel_hi:[1,0,1]
	global_store_dwordx4 v[132:133], v[128:131], off
	s_nop 1
	v_sub_f32_e32 v129, v215, v196
	v_sub_f32_e32 v128, v214, v196
	v_sub_f32_e32 v131, v217, v196
	v_sub_f32_e32 v130, v216, v196
	v_pk_mul_f32 v[130:131], v[196:197], v[130:131] op_sel:[1,0]
	v_pk_mul_f32 v[128:129], v[196:197], v[128:129] op_sel:[1,0]
	v_pk_fma_f32 v[126:127], v[192:193], v[130:131], v[126:127]
	v_pk_fma_f32 v[124:125], v[194:195], v[128:129], v[124:125]
	v_add_u32_e32 v128, 0x8000, v148
	v_mov_b32_e32 v129, v159
	v_pk_fma_f32 v[126:127], v[102:103], s[78:79], v[126:127] op_sel_hi:[1,0,1]
	v_pk_fma_f32 v[124:125], v[100:101], s[78:79], v[124:125] op_sel_hi:[1,0,1]
	v_lshl_add_u64 v[128:129], v[128:129], 2, s[88:89]
	global_store_dwordx4 v[128:129], v[124:127], off
	s_nop 1
	v_sub_f32_e32 v125, v137, v196
	v_sub_f32_e32 v124, v136, v196
	v_sub_f32_e32 v127, v139, v196
	v_sub_f32_e32 v126, v138, v196
	v_pk_mul_f32 v[126:127], v[196:197], v[126:127] op_sel:[1,0]
	v_pk_mul_f32 v[124:125], v[196:197], v[124:125] op_sel:[1,0]
	v_pk_fma_f32 v[122:123], v[188:189], v[126:127], v[122:123]
	v_pk_fma_f32 v[120:121], v[190:191], v[124:125], v[120:121]
	v_add_u32_e32 v124, 0x8010, v148
	v_mov_b32_e32 v125, v159
	v_pk_fma_f32 v[122:123], v[98:99], s[78:79], v[122:123] op_sel_hi:[1,0,1]
	v_pk_fma_f32 v[120:121], v[96:97], s[78:79], v[120:121] op_sel_hi:[1,0,1]
	v_lshl_add_u64 v[124:125], v[124:125], 2, s[88:89]
	global_store_dwordx4 v[124:125], v[120:123], off
	s_nop 1
	v_or_b32_e32 v122, 32, v203
	v_lshlrev_b32_e32 v124, 11, v122
	v_lshlrev_b32_e32 v120, 1, v122
	v_mov_b32_e32 v121, v159
	v_add_u32_e32 v122, v124, v158
	v_mov_b32_e32 v123, v159
	v_lshl_add_u64 v[120:121], v[120:121], 2, s[96:97]
	v_lshl_add_u64 v[122:123], v[122:123], 2, s[90:91]
	global_load_dwordx2 v[138:139], v[120:121], off
	global_load_dwordx4 v[126:129], v[122:123], off
	v_add_u32_e32 v122, v124, v204
	v_mov_b32_e32 v123, v159
	v_lshl_add_u64 v[122:123], v[122:123], 2, s[90:91]
	global_load_dwordx4 v[130:133], v[122:123], off
	v_or_b32_e32 v125, 48, v203
	v_lshlrev_b32_e32 v122, 1, v125
	v_lshlrev_b32_e32 v125, 11, v125
	v_mov_b32_e32 v123, v159
	v_add_u32_e32 v134, v125, v158
	v_mov_b32_e32 v135, v159
	v_lshl_add_u64 v[122:123], v[122:123], 2, s[96:97]
	v_lshl_add_u64 v[134:135], v[134:135], 2, s[90:91]
	global_load_dwordx2 v[196:197], v[122:123], off
	v_add_u32_e32 v206, v125, v204
	global_load_dwordx4 v[134:137], v[134:135], off
	v_mov_b32_e32 v207, v159
	v_lshl_add_u64 v[206:207], v[206:207], 2, s[90:91]
	global_load_dwordx4 v[206:209], v[206:207], off
	s_waitcnt vmcnt(0)
	v_sub_f32_e32 v127, v127, v138
	v_sub_f32_e32 v126, v126, v138
	v_sub_f32_e32 v129, v129, v138
	v_sub_f32_e32 v128, v128, v138
	v_pk_mul_f32 v[128:129], v[138:139], v[128:129] op_sel:[1,0]
	v_pk_mul_f32 v[126:127], v[138:139], v[126:127] op_sel:[1,0]
	v_pk_fma_f32 v[118:119], v[192:193], v[128:129], v[118:119]
	v_pk_fma_f32 v[116:117], v[194:195], v[126:127], v[116:117]
	v_add_u32_e32 v126, 0x10000, v148
	v_mov_b32_e32 v127, v159
	v_pk_fma_f32 v[118:119], v[102:103], s[78:79], v[118:119] op_sel_hi:[1,0,1]
	v_pk_fma_f32 v[116:117], v[100:101], s[78:79], v[116:117] op_sel_hi:[1,0,1]
	v_lshl_add_u64 v[126:127], v[126:127], 2, s[88:89]
	global_store_dwordx4 v[126:127], v[116:119], off
	s_nop 1
	v_sub_f32_e32 v117, v131, v138
	v_sub_f32_e32 v116, v130, v138
	v_sub_f32_e32 v119, v133, v138
	v_sub_f32_e32 v118, v132, v138
	v_pk_mul_f32 v[118:119], v[138:139], v[118:119] op_sel:[1,0]
	v_pk_mul_f32 v[116:117], v[138:139], v[116:117] op_sel:[1,0]
	v_pk_fma_f32 v[114:115], v[188:189], v[118:119], v[114:115]
	v_pk_fma_f32 v[112:113], v[190:191], v[116:117], v[112:113]
	v_add_u32_e32 v116, 0x10010, v148
	v_mov_b32_e32 v117, v159
	v_pk_fma_f32 v[114:115], v[98:99], s[78:79], v[114:115] op_sel_hi:[1,0,1]
	v_pk_fma_f32 v[112:113], v[96:97], s[78:79], v[112:113] op_sel_hi:[1,0,1]
	v_lshl_add_u64 v[116:117], v[116:117], 2, s[88:89]
	global_store_dwordx4 v[116:117], v[112:115], off
	s_nop 1
	v_sub_f32_e32 v113, v135, v196
	v_sub_f32_e32 v112, v134, v196
	v_sub_f32_e32 v115, v137, v196
	v_sub_f32_e32 v114, v136, v196
	v_pk_mul_f32 v[114:115], v[196:197], v[114:115] op_sel:[1,0]
	v_pk_mul_f32 v[112:113], v[196:197], v[112:113] op_sel:[1,0]
	v_pk_fma_f32 v[110:111], v[192:193], v[114:115], v[110:111]
	v_pk_fma_f32 v[108:109], v[194:195], v[112:113], v[108:109]
	v_add_u32_e32 v112, 0x18000, v148
	v_mov_b32_e32 v113, v159
	v_pk_fma_f32 v[110:111], v[102:103], s[78:79], v[110:111] op_sel_hi:[1,0,1]
	v_pk_fma_f32 v[108:109], v[100:101], s[78:79], v[108:109] op_sel_hi:[1,0,1]
	v_lshl_add_u64 v[112:113], v[112:113], 2, s[88:89]
	global_store_dwordx4 v[112:113], v[108:111], off
	s_nop 1
	v_sub_f32_e32 v109, v207, v196
	v_sub_f32_e32 v108, v206, v196
	v_sub_f32_e32 v111, v209, v196
	v_sub_f32_e32 v110, v208, v196
	v_pk_mul_f32 v[110:111], v[196:197], v[110:111] op_sel:[1,0]
	v_pk_mul_f32 v[108:109], v[196:197], v[108:109] op_sel:[1,0]
	v_pk_fma_f32 v[106:107], v[188:189], v[110:111], v[106:107]
	v_pk_fma_f32 v[104:105], v[190:191], v[108:109], v[104:105]
	v_add_u32_e32 v108, 0x18010, v148
	v_mov_b32_e32 v109, v159
	v_pk_fma_f32 v[106:107], v[98:99], s[78:79], v[106:107] op_sel_hi:[1,0,1]
	v_pk_fma_f32 v[104:105], v[96:97], s[78:79], v[104:105] op_sel_hi:[1,0,1]
	v_lshl_add_u64 v[108:109], v[108:109], 2, s[88:89]
	global_store_dwordx4 v[108:109], v[104:107], off
	s_nop 1
	v_add_u32_e32 v106, 0x80, v203
	v_lshlrev_b32_e32 v114, 11, v106
	v_lshlrev_b32_e32 v104, 1, v106
	v_mov_b32_e32 v105, v159
	v_add_u32_e32 v106, v114, v158
	v_mov_b32_e32 v107, v159
	v_lshl_add_u64 v[104:105], v[104:105], 2, s[96:97]
	v_lshl_add_u64 v[106:107], v[106:107], 2, s[90:91]
	global_load_dwordx2 v[112:113], v[104:105], off
	global_load_dwordx4 v[108:111], v[106:107], off
	v_add_u32_e32 v106, v114, v204
	v_mov_b32_e32 v107, v159
	v_lshl_add_u64 v[106:107], v[106:107], 2, s[90:91]
	global_load_dwordx4 v[116:119], v[106:107], off
	v_add_u32_e32 v115, 0x90, v203
	v_lshlrev_b32_e32 v106, 1, v115
	v_lshlrev_b32_e32 v115, 11, v115
	v_mov_b32_e32 v107, v159
	v_add_u32_e32 v126, v115, v158
	v_mov_b32_e32 v127, v159
	v_lshl_add_u64 v[106:107], v[106:107], 2, s[96:97]
	v_lshl_add_u64 v[126:127], v[126:127], 2, s[90:91]
	global_load_dwordx2 v[134:135], v[106:107], off
	v_add_u32_e32 v130, v115, v204
	global_load_dwordx4 v[126:129], v[126:127], off
	v_mov_b32_e32 v131, v159
	v_lshl_add_u64 v[130:131], v[130:131], 2, s[90:91]
	global_load_dwordx4 v[130:133], v[130:131], off
	s_waitcnt vmcnt(0)
;     template <bool LN, int BJ, int LO, int HI> DI void batch(const f32x4 (&acc)[2][2][4][2], unsigned row0, unsigned col0, const f32x4 (&gv)[2], const f32x4 (&bv)[2]) const {
;         f32x4 r[HI - LO]; float mean[(HI - LO) / 2], rstd[(HI - LO) / 2];
; #pragma unroll
;         for (int i = LO; i < HI; ++i) { const int ai = i >> 3, m = (i >> 1) & 3, n = i & 1; const unsigned row = row0 + ai * HALF + m * 16;
;             if (n == 0) { mean[(i - LO) >> 1] = 0.f; rstd[(i - LO) >> 1] = 1.f;
;                 if (LN) { const float2 st = *(const float2*)(stats + row * 2u); mean[(i - LO) >> 1] = st.x; rstd[(i - LO) >> 1] = st.y; } }
;             r[i - LO] = *(const f32x4*)(src + (row * (unsigned)DM + col0 + BJ * HALF + n * 16)); }
; #pragma unroll
;         for (int i = LO; i < HI; ++i) { const int ai = i >> 3, m = (i >> 1) & 3, n = i & 1; const unsigned row = row0 + ai * HALF + m * 16;
;             *(f32x4*)(Y + (row * (unsigned)DM + col0 + BJ * HALF + n * 16)) = acc[ai][BJ][m][n] + ((r[i - LO] - mean[(i - LO) >> 1]) * rstd[(i - LO) >> 1]) * gv[n] + bv[n]; }
;         __builtin_amdgcn_sched_barrier(0);
;     }
;     template <bool LN, int BJ> DI void load_gb(unsigned col0, f32x4 (&gv)[2], f32x4 (&bv)[2]) const {
; #pragma unroll
;         for (int n = 0; n < 2; ++n) {
;             if (LN) { gv[n] = *(const f32x4*)(gam + col0 + BJ * HALF + n * 16) * ALPHA; bv[n] = *(const f32x4*)(bet + col0 + BJ * HALF + n * 16) * ALPHA; }
	v_sub_f32_e32 v109, v109, v112
	v_sub_f32_e32 v108, v108, v112
	v_sub_f32_e32 v111, v111, v112
	v_sub_f32_e32 v110, v110, v112
	v_pk_mul_f32 v[110:111], v[112:113], v[110:111] op_sel:[1,0]
	v_pk_mul_f32 v[108:109], v[112:113], v[108:109] op_sel:[1,0]
	v_pk_fma_f32 v[94:95], v[192:193], v[110:111], v[94:95]
	v_pk_fma_f32 v[92:93], v[194:195], v[108:109], v[92:93]
	v_add_u32_e32 v108, 0x40000, v148
	v_mov_b32_e32 v109, v159
	v_pk_fma_f32 v[94:95], v[102:103], s[78:79], v[94:95] op_sel_hi:[1,0,1]
	v_pk_fma_f32 v[92:93], v[100:101], s[78:79], v[92:93] op_sel_hi:[1,0,1]
	v_lshl_add_u64 v[108:109], v[108:109], 2, s[88:89]
	global_store_dwordx4 v[108:109], v[92:95], off
	s_nop 1
	v_sub_f32_e32 v93, v117, v112
	v_sub_f32_e32 v92, v116, v112
	v_sub_f32_e32 v95, v119, v112
	v_sub_f32_e32 v94, v118, v112
	v_pk_mul_f32 v[94:95], v[112:113], v[94:95] op_sel:[1,0]
	v_pk_mul_f32 v[92:93], v[112:113], v[92:93] op_sel:[1,0]
	v_pk_fma_f32 v[90:91], v[188:189], v[94:95], v[90:91]
	v_pk_fma_f32 v[88:89], v[190:191], v[92:93], v[88:89]
	v_add_u32_e32 v92, 0x40010, v148
	v_mov_b32_e32 v93, v159
	v_pk_fma_f32 v[90:91], v[98:99], s[78:79], v[90:91] op_sel_hi:[1,0,1]
	v_pk_fma_f32 v[88:89], v[96:97], s[78:79], v[88:89] op_sel_hi:[1,0,1]
	v_lshl_add_u64 v[92:93], v[92:93], 2, s[88:89]
	global_store_dwordx4 v[92:93], v[88:91], off
	s_nop 1
	v_sub_f32_e32 v89, v127, v134
	v_sub_f32_e32 v88, v126, v134
	v_sub_f32_e32 v91, v129, v134
	v_sub_f32_e32 v90, v128, v134
	v_pk_mul_f32 v[90:91], v[134:135], v[90:91] op_sel:[1,0]
	v_pk_mul_f32 v[88:89], v[134:135], v[88:89] op_sel:[1,0]
	v_pk_fma_f32 v[86:87], v[192:193], v[90:91], v[86:87]
	v_pk_fma_f32 v[84:85], v[194:195], v[88:89], v[84:85]
	v_add_u32_e32 v88, 0x48000, v148
	v_mov_b32_e32 v89, v159
	v_pk_fma_f32 v[86:87], v[102:103], s[78:79], v[86:87] op_sel_hi:[1,0,1]
	v_pk_fma_f32 v[84:85], v[100:101], s[78:79], v[84:85] op_sel_hi:[1,0,1]
	v_lshl_add_u64 v[88:89], v[88:89], 2, s[88:89]
	global_store_dwordx4 v[88:89], v[84:87], off
	s_nop 1
	v_sub_f32_e32 v85, v131, v134
	v_sub_f32_e32 v84, v130, v134
	v_sub_f32_e32 v87, v133, v134
	v_sub_f32_e32 v86, v132, v134
	v_pk_mul_f32 v[86:87], v[134:135], v[86:87] op_sel:[1,0]
	v_pk_mul_f32 v[84:85], v[134:135], v[84:85] op_sel:[1,0]
	v_pk_fma_f32 v[82:83], v[188:189], v[86:87], v[82:83]
	v_pk_fma_f32 v[80:81], v[190:191], v[84:85], v[80:81]
	v_add_u32_e32 v84, 0x48010, v148
	v_mov_b32_e32 v85, v159
	v_pk_fma_f32 v[82:83], v[98:99], s[78:79], v[82:83] op_sel_hi:[1,0,1]
	v_pk_fma_f32 v[80:81], v[96:97], s[78:79], v[80:81] op_sel_hi:[1,0,1]
	v_lshl_add_u64 v[84:85], v[84:85], 2, s[88:89]
	global_store_dwordx4 v[84:85], v[80:83], off
	s_nop 1
	v_add_u32_e32 v82, 0xa0, v203
	v_lshlrev_b32_e32 v80, 1, v82
	v_mov_b32_e32 v81, v159
	v_lshlrev_b32_e32 v116, 11, v82
	v_lshl_add_u64 v[108:109], v[80:81], 2, s[96:97]
	v_add_u32_e32 v80, v116, v158
	v_lshl_add_u64 v[80:81], v[80:81], 2, s[90:91]
	global_load_dwordx2 v[112:113], v[108:109], off
	v_add_u32_e32 v84, v116, v204
	global_load_dwordx4 v[80:83], v[80:81], off
	v_mov_b32_e32 v85, v159
	v_lshl_add_u64 v[84:85], v[84:85], 2, s[90:91]
	global_load_dwordx4 v[84:87], v[84:85], off
	v_add_u32_e32 v90, 0xb0, v203
	v_lshlrev_b32_e32 v88, 1, v90
	v_mov_b32_e32 v89, v159
	v_lshlrev_b32_e32 v117, 11, v90
	v_lshl_add_u64 v[110:111], v[88:89], 2, s[96:97]
	v_add_u32_e32 v88, v117, v158
	v_lshl_add_u64 v[88:89], v[88:89], 2, s[90:91]
	global_load_dwordx2 v[118:119], v[110:111], off
	v_add_u32_e32 v92, v117, v204
	global_load_dwordx4 v[88:91], v[88:89], off
	v_mov_b32_e32 v93, v159
	v_lshl_add_u64 v[92:93], v[92:93], 2, s[90:91]
	global_load_dwordx4 v[92:95], v[92:93], off
	s_waitcnt vmcnt(0)
	v_sub_f32_e32 v81, v81, v112
	v_sub_f32_e32 v80, v80, v112
	v_sub_f32_e32 v83, v83, v112
	v_sub_f32_e32 v82, v82, v112
	v_pk_mul_f32 v[82:83], v[112:113], v[82:83] op_sel:[1,0]
	v_pk_mul_f32 v[80:81], v[112:113], v[80:81] op_sel:[1,0]
	v_pk_fma_f32 v[78:79], v[192:193], v[82:83], v[78:79]
	v_pk_fma_f32 v[76:77], v[194:195], v[80:81], v[76:77]
	v_add_u32_e32 v80, 0x50000, v148
	v_mov_b32_e32 v81, v159
	v_pk_fma_f32 v[78:79], v[102:103], s[78:79], v[78:79] op_sel_hi:[1,0,1]
	v_pk_fma_f32 v[76:77], v[100:101], s[78:79], v[76:77] op_sel_hi:[1,0,1]
	v_lshl_add_u64 v[80:81], v[80:81], 2, s[88:89]
	global_store_dwordx4 v[80:81], v[76:79], off
	s_nop 1
	v_sub_f32_e32 v77, v85, v112
	v_sub_f32_e32 v76, v84, v112
	v_sub_f32_e32 v79, v87, v112
	v_sub_f32_e32 v78, v86, v112
	v_pk_mul_f32 v[78:79], v[112:113], v[78:79] op_sel:[1,0]
	v_pk_mul_f32 v[76:77], v[112:113], v[76:77] op_sel:[1,0]
	v_pk_fma_f32 v[74:75], v[188:189], v[78:79], v[74:75]
	v_pk_fma_f32 v[72:73], v[190:191], v[76:77], v[72:73]
	v_add_u32_e32 v76, 0x50010, v148
	v_mov_b32_e32 v77, v159
	v_pk_fma_f32 v[74:75], v[98:99], s[78:79], v[74:75] op_sel_hi:[1,0,1]
	v_pk_fma_f32 v[72:73], v[96:97], s[78:79], v[72:73] op_sel_hi:[1,0,1]
	v_lshl_add_u64 v[76:77], v[76:77], 2, s[88:89]
	global_store_dwordx4 v[76:77], v[72:75], off
	s_nop 1
	v_sub_f32_e32 v73, v89, v118
	v_sub_f32_e32 v72, v88, v118
	v_sub_f32_e32 v75, v91, v118
	v_sub_f32_e32 v74, v90, v118
	v_pk_mul_f32 v[74:75], v[118:119], v[74:75] op_sel:[1,0]
	v_pk_mul_f32 v[72:73], v[118:119], v[72:73] op_sel:[1,0]
	v_pk_fma_f32 v[70:71], v[192:193], v[74:75], v[70:71]
	v_pk_fma_f32 v[68:69], v[194:195], v[72:73], v[68:69]
	v_add_u32_e32 v72, 0x58000, v148
	v_mov_b32_e32 v73, v159
	v_pk_fma_f32 v[70:71], v[102:103], s[78:79], v[70:71] op_sel_hi:[1,0,1]
	v_pk_fma_f32 v[68:69], v[100:101], s[78:79], v[68:69] op_sel_hi:[1,0,1]
	v_lshl_add_u64 v[72:73], v[72:73], 2, s[88:89]
	global_store_dwordx4 v[72:73], v[68:71], off
	s_nop 1
	v_sub_f32_e32 v69, v93, v118
	v_sub_f32_e32 v68, v92, v118
	v_sub_f32_e32 v71, v95, v118
	v_sub_f32_e32 v70, v94, v118
	v_pk_mul_f32 v[70:71], v[118:119], v[70:71] op_sel:[1,0]
	v_pk_mul_f32 v[68:69], v[118:119], v[68:69] op_sel:[1,0]
	v_pk_fma_f32 v[66:67], v[188:189], v[70:71], v[66:67]
	v_pk_fma_f32 v[64:65], v[190:191], v[68:69], v[64:65]
	v_add_u32_e32 v68, 0x58010, v148
	v_mov_b32_e32 v69, v159
	v_pk_fma_f32 v[66:67], v[98:99], s[78:79], v[66:67] op_sel_hi:[1,0,1]
	v_pk_fma_f32 v[64:65], v[96:97], s[78:79], v[64:65] op_sel_hi:[1,0,1]
	v_lshl_add_u64 v[68:69], v[68:69], 2, s[88:89]
	global_store_dwordx4 v[68:69], v[64:67], off
	global_load_dwordx4 v[64:67], v[150:151], off offset:512
	v_or_b32_e32 v119, 0x80, v158
	v_add_u32_e32 v72, v202, v119
	v_mov_b32_e32 v73, v159
	v_lshl_add_u64 v[72:73], v[72:73], 2, s[90:91]
	v_or_b32_e32 v118, 0x90, v158
	v_add_u32_e32 v158, v202, v118
	s_waitcnt vmcnt(0)
;     template <bool LN, int BJ, int LO, int HI> DI void batch(const f32x4 (&acc)[2][2][4][2], unsigned row0, unsigned col0, const f32x4 (&gv)[2], const f32x4 (&bv)[2]) const {
;         f32x4 r[HI - LO]; float mean[(HI - LO) / 2], rstd[(HI - LO) / 2];
; #pragma unroll
;         for (int i = LO; i < HI; ++i) { const int ai = i >> 3, m = (i >> 1) & 3, n = i & 1; const unsigned row = row0 + ai * HALF + m * 16;
;             if (n == 0) { mean[(i - LO) >> 1] = 0.f; rstd[(i - LO) >> 1] = 1.f;
;                 if (LN) { const float2 st = *(const float2*)(stats + row * 2u); mean[(i - LO) >> 1] = st.x; rstd[(i - LO) >> 1] = st.y; } }
;             r[i - LO] = *(const f32x4*)(src + (row * (unsigned)DM + col0 + BJ * HALF + n * 16)); }
; #pragma unroll
;         for (int i = LO; i < HI; ++i) { const int ai = i >> 3, m = (i >> 1) & 3, n = i & 1; const unsigned row = row0 + ai * HALF + m * 16;
;             *(f32x4*)(Y + (row * (unsigned)DM + col0 + BJ * HALF + n * 16)) = acc[ai][BJ][m][n] + ((r[i - LO] - mean[(i - LO) >> 1]) * rstd[(i - LO) >> 1]) * gv[n] + bv[n]; }
;     template <bool LN> DI void run(const f32x4 (&acc)[2][2][4][2], const Unit& u, int wr, int wc, int fr, int fq) const {
;     ...
;         load_gb<LN, 1>(col0, gv, bv);
;         batch<LN, 1, 0, 8>(acc, row0, col0, gv, bv);
	v_pk_mul_f32 v[96:97], v[66:67], s[78:79] op_sel_hi:[1,0]
	v_pk_mul_f32 v[98:99], v[64:65], s[78:79] op_sel_hi:[1,0]
	global_load_dwordx4 v[68:71], v[152:153], off offset:512
	global_load_dwordx4 v[64:67], v[150:151], off offset:576
	global_load_dwordx2 v[138:139], v[154:155], off
	global_load_dwordx4 v[126:129], v[72:73], off
	v_lshl_add_u64 v[72:73], v[158:159], 2, s[90:91]
	v_add_u32_e32 v158, v149, v119
	s_waitcnt vmcnt(0)
	v_pk_mul_f32 v[92:93], v[66:67], s[78:79] op_sel_hi:[1,0]
	v_pk_mul_f32 v[94:95], v[64:65], s[78:79] op_sel_hi:[1,0]
	global_load_dwordx4 v[64:67], v[152:153], off offset:576
	global_load_dwordx4 v[130:133], v[72:73], off
	global_load_dwordx2 v[112:113], v[186:187], off
	v_lshl_add_u64 v[72:73], v[158:159], 2, s[90:91]
	global_load_dwordx4 v[134:137], v[72:73], off
	v_add_u32_e32 v158, v149, v118
	v_lshl_add_u64 v[72:73], v[158:159], 2, s[90:91]
	global_load_dwordx4 v[88:91], v[72:73], off
	global_load_dwordx2 v[102:103], v[120:121], off
	v_add_u32_e32 v158, v124, v119
	v_lshl_add_u64 v[72:73], v[158:159], 2, s[90:91]
	global_load_dwordx4 v[84:87], v[72:73], off
	v_add_u32_e32 v158, v124, v118
	v_lshl_add_u64 v[72:73], v[158:159], 2, s[90:91]
	global_load_dwordx4 v[80:83], v[72:73], off
	global_load_dwordx2 v[100:101], v[122:123], off
	v_add_u32_e32 v158, v125, v119
	v_lshl_add_u64 v[72:73], v[158:159], 2, s[90:91]
	global_load_dwordx4 v[76:79], v[72:73], off
	v_add_u32_e32 v158, v125, v118
	v_lshl_add_u64 v[72:73], v[158:159], 2, s[90:91]
	global_load_dwordx4 v[72:75], v[72:73], off
	v_sub_f32_e32 v121, v127, v138
	v_sub_f32_e32 v120, v126, v138
	v_sub_f32_e32 v123, v129, v138
	v_sub_f32_e32 v122, v128, v138
	v_pk_mul_f32 v[122:123], v[138:139], v[122:123] op_sel:[1,0]
	v_pk_mul_f32 v[120:121], v[138:139], v[120:121] op_sel:[1,0]
	v_or_b32_e32 v158, 0x80, v148
	v_pk_fma_f32 v[60:61], v[98:99], v[120:121], v[60:61]
	v_pk_fma_f32 v[62:63], v[96:97], v[122:123], v[62:63]
	v_pk_fma_f32 v[60:61], v[68:69], s[78:79], v[60:61] op_sel_hi:[1,0,1]
	v_pk_fma_f32 v[62:63], v[70:71], s[78:79], v[62:63] op_sel_hi:[1,0,1]
	v_lshl_add_u64 v[120:121], v[158:159], 2, s[88:89]
	global_store_dwordx4 v[120:121], v[60:63], off
	v_or_b32_e32 v158, 0x90, v148
	s_waitcnt vmcnt(0)
	v_sub_f32_e32 v61, v131, v138
	v_sub_f32_e32 v60, v130, v138
	v_sub_f32_e32 v63, v133, v138
	v_sub_f32_e32 v62, v132, v138
	v_pk_mul_f32 v[62:63], v[138:139], v[62:63] op_sel:[1,0]
	v_pk_mul_f32 v[60:61], v[138:139], v[60:61] op_sel:[1,0]
	v_pk_fma_f32 v[58:59], v[92:93], v[62:63], v[58:59]
	v_pk_fma_f32 v[56:57], v[94:95], v[60:61], v[56:57]
	v_pk_fma_f32 v[58:59], v[66:67], s[78:79], v[58:59] op_sel_hi:[1,0,1]
	v_pk_fma_f32 v[56:57], v[64:65], s[78:79], v[56:57] op_sel_hi:[1,0,1]
	v_lshl_add_u64 v[60:61], v[158:159], 2, s[88:89]
	global_store_dwordx4 v[60:61], v[56:59], off
	v_add_u32_e32 v158, 0x8080, v148
	s_nop 0
	v_sub_f32_e32 v57, v135, v112
	v_sub_f32_e32 v56, v134, v112
	v_sub_f32_e32 v59, v137, v112
	v_sub_f32_e32 v58, v136, v112
	v_pk_mul_f32 v[58:59], v[112:113], v[58:59] op_sel:[1,0]
	v_pk_mul_f32 v[56:57], v[112:113], v[56:57] op_sel:[1,0]
	v_pk_fma_f32 v[54:55], v[96:97], v[58:59], v[54:55]
	v_pk_fma_f32 v[52:53], v[98:99], v[56:57], v[52:53]
	v_pk_fma_f32 v[54:55], v[70:71], s[78:79], v[54:55] op_sel_hi:[1,0,1]
	v_pk_fma_f32 v[52:53], v[68:69], s[78:79], v[52:53] op_sel_hi:[1,0,1]
	v_lshl_add_u64 v[56:57], v[158:159], 2, s[88:89]
	global_store_dwordx4 v[56:57], v[52:55], off
	v_add_u32_e32 v158, 0x8090, v148
	s_nop 0
	v_sub_f32_e32 v53, v89, v112
	v_sub_f32_e32 v52, v88, v112
	v_sub_f32_e32 v55, v91, v112
	v_sub_f32_e32 v54, v90, v112
	v_pk_mul_f32 v[54:55], v[112:113], v[54:55] op_sel:[1,0]
	v_pk_mul_f32 v[52:53], v[112:113], v[52:53] op_sel:[1,0]
	v_pk_fma_f32 v[50:51], v[92:93], v[54:55], v[50:51]
	v_pk_fma_f32 v[48:49], v[94:95], v[52:53], v[48:49]
	v_pk_fma_f32 v[50:51], v[66:67], s[78:79], v[50:51] op_sel_hi:[1,0,1]
	v_pk_fma_f32 v[48:49], v[64:65], s[78:79], v[48:49] op_sel_hi:[1,0,1]
	v_lshl_add_u64 v[52:53], v[158:159], 2, s[88:89]
	global_store_dwordx4 v[52:53], v[48:51], off
	v_add_u32_e32 v158, 0x10080, v148
	s_nop 0
	v_sub_f32_e32 v49, v85, v102
	v_sub_f32_e32 v48, v84, v102
	v_sub_f32_e32 v51, v87, v102
	v_sub_f32_e32 v50, v86, v102
	v_pk_mul_f32 v[50:51], v[102:103], v[50:51] op_sel:[1,0]
	v_pk_mul_f32 v[48:49], v[102:103], v[48:49] op_sel:[1,0]
	v_pk_fma_f32 v[46:47], v[96:97], v[50:51], v[46:47]
	v_pk_fma_f32 v[44:45], v[98:99], v[48:49], v[44:45]
	v_pk_fma_f32 v[46:47], v[70:71], s[78:79], v[46:47] op_sel_hi:[1,0,1]
	v_pk_fma_f32 v[44:45], v[68:69], s[78:79], v[44:45] op_sel_hi:[1,0,1]
	v_lshl_add_u64 v[48:49], v[158:159], 2, s[88:89]
	global_store_dwordx4 v[48:49], v[44:47], off
	v_add_u32_e32 v158, 0x10090, v148
	s_nop 0
	v_sub_f32_e32 v45, v81, v102
	v_sub_f32_e32 v44, v80, v102
	v_sub_f32_e32 v47, v83, v102
	v_sub_f32_e32 v46, v82, v102
	v_pk_mul_f32 v[46:47], v[102:103], v[46:47] op_sel:[1,0]
	v_pk_mul_f32 v[44:45], v[102:103], v[44:45] op_sel:[1,0]
	v_pk_fma_f32 v[42:43], v[92:93], v[46:47], v[42:43]
	v_pk_fma_f32 v[40:41], v[94:95], v[44:45], v[40:41]
	v_pk_fma_f32 v[42:43], v[66:67], s[78:79], v[42:43] op_sel_hi:[1,0,1]
	v_pk_fma_f32 v[40:41], v[64:65], s[78:79], v[40:41] op_sel_hi:[1,0,1]
	v_lshl_add_u64 v[44:45], v[158:159], 2, s[88:89]
	global_store_dwordx4 v[44:45], v[40:43], off
	v_add_u32_e32 v158, 0x18080, v148
	s_nop 0
	v_sub_f32_e32 v41, v77, v100
	v_sub_f32_e32 v40, v76, v100
	v_sub_f32_e32 v43, v79, v100
	v_sub_f32_e32 v42, v78, v100
	v_pk_mul_f32 v[42:43], v[100:101], v[42:43] op_sel:[1,0]
	v_pk_mul_f32 v[40:41], v[100:101], v[40:41] op_sel:[1,0]
	v_pk_fma_f32 v[38:39], v[96:97], v[42:43], v[38:39]
;     template <bool LN, int BJ, int LO, int HI> DI void batch(const f32x4 (&acc)[2][2][4][2], unsigned row0, unsigned col0, const f32x4 (&gv)[2], const f32x4 (&bv)[2]) const {
;         f32x4 r[HI - LO]; float mean[(HI - LO) / 2], rstd[(HI - LO) / 2];
; #pragma unroll
;         for (int i = LO; i < HI; ++i) { const int ai = i >> 3, m = (i >> 1) & 3, n = i & 1; const unsigned row = row0 + ai * HALF + m * 16;
;             if (n == 0) { mean[(i - LO) >> 1] = 0.f; rstd[(i - LO) >> 1] = 1.f;
;                 if (LN) { const float2 st = *(const float2*)(stats + row * 2u); mean[(i - LO) >> 1] = st.x; rstd[(i - LO) >> 1] = st.y; } }
;             r[i - LO] = *(const f32x4*)(src + (row * (unsigned)DM + col0 + BJ * HALF + n * 16)); }
; #pragma unroll
;         for (int i = LO; i < HI; ++i) { const int ai = i >> 3, m = (i >> 1) & 3, n = i & 1; const unsigned row = row0 + ai * HALF + m * 16;
;             *(f32x4*)(Y + (row * (unsigned)DM + col0 + BJ * HALF + n * 16)) = acc[ai][BJ][m][n] + ((r[i - LO] - mean[(i - LO) >> 1]) * rstd[(i - LO) >> 1]) * gv[n] + bv[n]; }
;     template <bool LN> DI void run(const f32x4 (&acc)[2][2][4][2], const Unit& u, int wr, int wc, int fr, int fq) const {
;     ...
;         batch<LN, 1, 8, 16>(acc, row0, col0, gv, bv);
	v_pk_fma_f32 v[36:37], v[98:99], v[40:41], v[36:37]
	v_pk_fma_f32 v[38:39], v[70:71], s[78:79], v[38:39] op_sel_hi:[1,0,1]
	v_pk_fma_f32 v[36:37], v[68:69], s[78:79], v[36:37] op_sel_hi:[1,0,1]
	v_lshl_add_u64 v[40:41], v[158:159], 2, s[88:89]
	global_store_dwordx4 v[40:41], v[36:39], off
	v_add_u32_e32 v158, 0x18090, v148
	s_nop 0
	v_sub_f32_e32 v37, v73, v100
	v_sub_f32_e32 v36, v72, v100
	v_sub_f32_e32 v39, v75, v100
	v_sub_f32_e32 v38, v74, v100
	v_pk_mul_f32 v[38:39], v[100:101], v[38:39] op_sel:[1,0]
	v_pk_mul_f32 v[36:37], v[100:101], v[36:37] op_sel:[1,0]
	v_pk_fma_f32 v[34:35], v[92:93], v[38:39], v[34:35]
	v_pk_fma_f32 v[32:33], v[94:95], v[36:37], v[32:33]
	v_pk_fma_f32 v[34:35], v[66:67], s[78:79], v[34:35] op_sel_hi:[1,0,1]
	v_pk_fma_f32 v[32:33], v[64:65], s[78:79], v[32:33] op_sel_hi:[1,0,1]
	v_lshl_add_u64 v[36:37], v[158:159], 2, s[88:89]
	global_store_dwordx4 v[36:37], v[32:35], off
	v_add_u32_e32 v158, v114, v119
	s_nop 0
	v_lshl_add_u64 v[32:33], v[158:159], 2, s[90:91]
	global_load_dwordx2 v[62:63], v[104:105], off
	global_load_dwordx4 v[54:57], v[32:33], off
	v_add_u32_e32 v158, v114, v118
	v_lshl_add_u64 v[32:33], v[158:159], 2, s[90:91]
	global_load_dwordx4 v[58:61], v[32:33], off
	global_load_dwordx2 v[52:53], v[106:107], off
	v_add_u32_e32 v158, v115, v119
	v_lshl_add_u64 v[32:33], v[158:159], 2, s[90:91]
	global_load_dwordx4 v[72:75], v[32:33], off
	v_add_u32_e32 v158, v115, v118
	v_lshl_add_u64 v[32:33], v[158:159], 2, s[90:91]
	global_load_dwordx4 v[76:79], v[32:33], off
	global_load_dwordx2 v[50:51], v[108:109], off
	v_add_u32_e32 v158, v116, v119
	v_lshl_add_u64 v[32:33], v[158:159], 2, s[90:91]
	global_load_dwordx4 v[44:47], v[32:33], off
	v_add_u32_e32 v158, v116, v118
	v_lshl_add_u64 v[32:33], v[158:159], 2, s[90:91]
	global_load_dwordx4 v[40:43], v[32:33], off
	global_load_dwordx2 v[48:49], v[110:111], off
	v_add_u32_e32 v158, v117, v119
	v_lshl_add_u64 v[32:33], v[158:159], 2, s[90:91]
	global_load_dwordx4 v[36:39], v[32:33], off
	v_add_u32_e32 v158, v117, v118
	v_lshl_add_u64 v[32:33], v[158:159], 2, s[90:91]
	global_load_dwordx4 v[32:35], v[32:33], off
	v_add_u32_e32 v158, 0x40080, v148
	s_waitcnt vmcnt(0)
; #define PG8_WAIT_V(n) asm volatile("s_waitcnt vmcnt(" #n ")" ::: "memory")
; #define PG8_BAR __builtin_amdgcn_s_barrier()
; template <class Epi>
; DI void gemm_phase(LAS unsigned char* lds, const Gemm g, const StaticOrder& S, const Epi& E) {
;     ...
;         E(acc, cur, wr, wc, fr, fq);
;         if (!has_next) break;
; #pragma unroll
;         for (int a = 0; a < 2; ++a)
; #pragma unroll
;             for (int b = 0; b < 2; ++b)
; #pragma unroll
;                 for (int m = 0; m < 4; ++m)
; #pragma unroll
;                     for (int n = 0; n < 2; ++n) acc[a][b][m][n] = (f32x4){0.f, 0.f, 0.f, 0.f};
;         cur = nxt; cA = nA; cB = nB; ++ui;
;     }
;     PG8_WAIT_V(0);
;     if (wr == 0) PG8_BAR;
;     PG8_BAR;
;     template <bool LN, int BJ, int LO, int HI> DI void batch(const f32x4 (&acc)[2][2][4][2], unsigned row0, unsigned col0, const f32x4 (&gv)[2], const f32x4 (&bv)[2]) const {
;     ...
;         for (int i = LO; i < HI; ++i) { const int ai = i >> 3, m = (i >> 1) & 3, n = i & 1; const unsigned row = row0 + ai * HALF + m * 16;
;             if (n == 0) { mean[(i - LO) >> 1] = 0.f; rstd[(i - LO) >> 1] = 1.f;
;                 if (LN) { const float2 st = *(const float2*)(stats + row * 2u); mean[(i - LO) >> 1] = st.x; rstd[(i - LO) >> 1] = st.y; } }
;             r[i - LO] = *(const f32x4*)(src + (row * (unsigned)DM + col0 + BJ * HALF + n * 16)); }
; #pragma unroll
;         for (int i = LO; i < HI; ++i) { const int ai = i >> 3, m = (i >> 1) & 3, n = i & 1; const unsigned row = row0 + ai * HALF + m * 16;
;             *(f32x4*)(Y + (row * (unsigned)DM + col0 + BJ * HALF + n * 16)) = acc[ai][BJ][m][n] + ((r[i - LO] - mean[(i - LO) >> 1]) * rstd[(i - LO) >> 1]) * gv[n] + bv[n]; }
	v_sub_f32_e32 v55, v55, v62
	v_sub_f32_e32 v54, v54, v62
	v_sub_f32_e32 v57, v57, v62
	v_sub_f32_e32 v56, v56, v62
	v_pk_mul_f32 v[56:57], v[62:63], v[56:57] op_sel:[1,0]
	v_pk_mul_f32 v[54:55], v[62:63], v[54:55] op_sel:[1,0]
	v_pk_fma_f32 v[30:31], v[96:97], v[56:57], v[30:31]
	v_pk_fma_f32 v[28:29], v[98:99], v[54:55], v[28:29]
	v_pk_fma_f32 v[30:31], v[70:71], s[78:79], v[30:31] op_sel_hi:[1,0,1]
	v_pk_fma_f32 v[28:29], v[68:69], s[78:79], v[28:29] op_sel_hi:[1,0,1]
	v_lshl_add_u64 v[54:55], v[158:159], 2, s[88:89]
	global_store_dwordx4 v[54:55], v[28:31], off
	v_add_u32_e32 v158, 0x40090, v148
	s_nop 0
	v_sub_f32_e32 v29, v59, v62
	v_sub_f32_e32 v28, v58, v62
	v_sub_f32_e32 v31, v61, v62
	v_sub_f32_e32 v30, v60, v62
	v_pk_mul_f32 v[30:31], v[62:63], v[30:31] op_sel:[1,0]
	v_pk_mul_f32 v[28:29], v[62:63], v[28:29] op_sel:[1,0]
	v_pk_fma_f32 v[26:27], v[92:93], v[30:31], v[26:27]
	v_pk_fma_f32 v[24:25], v[94:95], v[28:29], v[24:25]
	v_pk_fma_f32 v[26:27], v[66:67], s[78:79], v[26:27] op_sel_hi:[1,0,1]
	v_pk_fma_f32 v[24:25], v[64:65], s[78:79], v[24:25] op_sel_hi:[1,0,1]
	v_lshl_add_u64 v[28:29], v[158:159], 2, s[88:89]
	global_store_dwordx4 v[28:29], v[24:27], off
	v_add_u32_e32 v158, 0x48080, v148
	s_nop 0
	v_sub_f32_e32 v25, v73, v52
	v_sub_f32_e32 v24, v72, v52
	v_sub_f32_e32 v27, v75, v52
	v_sub_f32_e32 v26, v74, v52
	v_pk_mul_f32 v[26:27], v[52:53], v[26:27] op_sel:[1,0]
	v_pk_mul_f32 v[24:25], v[52:53], v[24:25] op_sel:[1,0]
	v_pk_fma_f32 v[22:23], v[96:97], v[26:27], v[22:23]
	v_pk_fma_f32 v[20:21], v[98:99], v[24:25], v[20:21]
	v_pk_fma_f32 v[22:23], v[70:71], s[78:79], v[22:23] op_sel_hi:[1,0,1]
	v_pk_fma_f32 v[20:21], v[68:69], s[78:79], v[20:21] op_sel_hi:[1,0,1]
	v_lshl_add_u64 v[24:25], v[158:159], 2, s[88:89]
	global_store_dwordx4 v[24:25], v[20:23], off
	v_add_u32_e32 v158, 0x48090, v148
	s_nop 0
	v_sub_f32_e32 v21, v77, v52
	v_sub_f32_e32 v20, v76, v52
	v_sub_f32_e32 v23, v79, v52
	v_sub_f32_e32 v22, v78, v52
	v_pk_mul_f32 v[22:23], v[52:53], v[22:23] op_sel:[1,0]
	v_pk_mul_f32 v[20:21], v[52:53], v[20:21] op_sel:[1,0]
	v_pk_fma_f32 v[18:19], v[92:93], v[22:23], v[18:19]
	v_pk_fma_f32 v[16:17], v[94:95], v[20:21], v[16:17]
	v_pk_fma_f32 v[18:19], v[66:67], s[78:79], v[18:19] op_sel_hi:[1,0,1]
	v_pk_fma_f32 v[16:17], v[64:65], s[78:79], v[16:17] op_sel_hi:[1,0,1]
	v_lshl_add_u64 v[20:21], v[158:159], 2, s[88:89]
	global_store_dwordx4 v[20:21], v[16:19], off
	v_add_u32_e32 v158, 0x50080, v148
	s_nop 0
	v_sub_f32_e32 v17, v45, v50
	v_sub_f32_e32 v16, v44, v50
	v_sub_f32_e32 v19, v47, v50
	v_sub_f32_e32 v18, v46, v50
	v_pk_mul_f32 v[18:19], v[50:51], v[18:19] op_sel:[1,0]
	v_pk_mul_f32 v[16:17], v[50:51], v[16:17] op_sel:[1,0]
	v_pk_fma_f32 v[14:15], v[96:97], v[18:19], v[14:15]
	v_pk_fma_f32 v[12:13], v[98:99], v[16:17], v[12:13]
	v_pk_fma_f32 v[14:15], v[70:71], s[78:79], v[14:15] op_sel_hi:[1,0,1]
	v_pk_fma_f32 v[12:13], v[68:69], s[78:79], v[12:13] op_sel_hi:[1,0,1]
	v_lshl_add_u64 v[16:17], v[158:159], 2, s[88:89]
	global_store_dwordx4 v[16:17], v[12:15], off
	v_add_u32_e32 v158, 0x50090, v148
	s_nop 0
	v_sub_f32_e32 v13, v41, v50
	v_sub_f32_e32 v12, v40, v50
	v_sub_f32_e32 v15, v43, v50
	v_sub_f32_e32 v14, v42, v50
	v_pk_mul_f32 v[14:15], v[50:51], v[14:15] op_sel:[1,0]
	v_pk_mul_f32 v[12:13], v[50:51], v[12:13] op_sel:[1,0]
	v_pk_fma_f32 v[10:11], v[92:93], v[14:15], v[10:11]
	v_pk_fma_f32 v[8:9], v[94:95], v[12:13], v[8:9]
	v_pk_fma_f32 v[10:11], v[66:67], s[78:79], v[10:11] op_sel_hi:[1,0,1]
	v_pk_fma_f32 v[8:9], v[64:65], s[78:79], v[8:9] op_sel_hi:[1,0,1]
	v_lshl_add_u64 v[12:13], v[158:159], 2, s[88:89]
	global_store_dwordx4 v[12:13], v[8:11], off
	v_add_u32_e32 v158, 0x58080, v148
	s_nop 0
	v_sub_f32_e32 v9, v37, v48
	v_sub_f32_e32 v8, v36, v48
	v_sub_f32_e32 v11, v39, v48
	v_sub_f32_e32 v10, v38, v48
	v_pk_mul_f32 v[10:11], v[48:49], v[10:11] op_sel:[1,0]
	v_pk_mul_f32 v[8:9], v[48:49], v[8:9] op_sel:[1,0]
	v_pk_fma_f32 v[6:7], v[96:97], v[10:11], v[6:7]
	v_pk_fma_f32 v[4:5], v[98:99], v[8:9], v[4:5]
	v_pk_fma_f32 v[6:7], v[70:71], s[78:79], v[6:7] op_sel_hi:[1,0,1]
	v_pk_fma_f32 v[4:5], v[68:69], s[78:79], v[4:5] op_sel_hi:[1,0,1]
	v_lshl_add_u64 v[8:9], v[158:159], 2, s[88:89]
	global_store_dwordx4 v[8:9], v[4:7], off
	v_add_u32_e32 v158, 0x58090, v148
	s_nop 0
	v_sub_f32_e32 v5, v33, v48
	v_sub_f32_e32 v4, v32, v48
	v_sub_f32_e32 v7, v35, v48
	v_sub_f32_e32 v6, v34, v48
	v_pk_mul_f32 v[6:7], v[48:49], v[6:7] op_sel:[1,0]
	v_pk_mul_f32 v[4:5], v[48:49], v[4:5] op_sel:[1,0]
	v_pk_fma_f32 v[2:3], v[92:93], v[6:7], v[2:3]
	v_pk_fma_f32 v[0:1], v[94:95], v[4:5], v[0:1]
	v_pk_fma_f32 v[2:3], v[66:67], s[78:79], v[2:3] op_sel_hi:[1,0,1]
	v_pk_fma_f32 v[0:1], v[64:65], s[78:79], v[0:1] op_sel_hi:[1,0,1]
	v_lshl_add_u64 v[4:5], v[158:159], 2, s[88:89]
	global_store_dwordx4 v[4:5], v[0:3], off
	s_and_b64 vcc, exec, s[6:7]
	s_mov_b32 s2, s37
	s_mov_b32 s3, s38
	s_mov_b64 s[18:19], s[10:11]
	s_mov_b64 s[16:17], s[8:9]
	v_readlane_b32 s33, v255, 39
	s_cbranch_vccz .LBB0_123
	s_waitcnt vmcnt(0)
	s_cmpk_gt_u32 s24, 0xff
	s_cbranch_scc1 .LBB0_138
	s_barrier

; #define PG8_STAGE(bufoff, gbase) do { _Pragma("unroll") for (int _i = 0; _i < 2; ++_i) \
;         __builtin_amdgcn_global_load_lds((const unsigned*)((const char*)(gbase) + voff[_i]), (LAS unsigned*)(lds + (bufoff) + ldsw + _i * 8192), 16, 0, 0); } while (0)
; #define PG8_LDA(dst, b, h) do { _Pragma("unroll") for (int m = 0; m < 4; ++m) _Pragma("unroll") for (int k = 0; k < 2; ++k) dst[m][k] = *(const LAS bf16x8*)(lds + PG8_SA(b, h) + aoff + m * 2048 + k * 1024); } while (0)
; #define PG8_LDB(dst, b, h) do { _Pragma("unroll") for (int n = 0; n < 2; ++n) _Pragma("unroll") for (int k = 0; k < 2; ++k) dst[n][k] = *(const LAS bf16x8*)(lds + PG8_SB(b, h) + boff + n * 2048 + k * 1024); } while (0)
; #define PG8_MMA(ai, bj, At, Bt) do { __builtin_amdgcn_s_setprio(1); _Pragma("unroll") for (int m = 0; m < 4; ++m) _Pragma("unroll") for (int n = 0; n < 2; ++n) _Pragma("unroll") for (int k = 0; k < 2; ++k) \
;         acc[ai][bj][m][n] = __builtin_amdgcn_mfma_f32_16x16x32_bf16(Bt[n][k], At[m][k], acc[ai][bj][m][n], 0, 0, 0); __builtin_amdgcn_s_setprio(0); } while (0)
; #define PG8_WAIT_L(n) asm volatile("s_waitcnt lgkmcnt(" #n ")" ::: "memory")
; #define PG8_BAR __builtin_amdgcn_s_barrier()
; template <class Epi>
; DI void gemm_phase(LAS unsigned char* lds, const Gemm g, const StaticOrder& S, const Epi& E) {
;     ...
;         const bool has_next = S.next(ui + 1, nxt);
;         const char* nA = has_next ? (const char*)g.A + (size_t)nxt.pm * tstep : cA; const char* nB = has_next ? (const char*)g.Bt + (size_t)nxt.pn * tstep : cB;
;         for (int t = 0; t < nt; t += 2) {
;             const bool last = (t == nt - 2);
;             const char* a1 = cA + (size_t)(t + 1) * kstep;
;             const char* a2 = last ? nA : cA + (size_t)(t + 2) * kstep; const char* b2 = last ? nB : cB + (size_t)(t + 2) * kstep;
;             const char* a3 = a2 + kstep; const char* b3 = b2 + kstep;
;             PG8_LDB(B0, 0, 0); PG8_SCHED; PG8_LDA(At, 0, 0); PG8_STAGE(PG8_SA(1, 1), a1 + hstep);
;             PG8_WAIT_L(8); PG8_BAR; PG8_WAIT_L(0); PG8_MMA(0, 0, At, B0); PG8_BAR; PG8_SCHED;
;     ...
; #pragma unroll
;         for (int a = 0; a < 2; ++a)
; #pragma unroll
;             for (int b = 0; b < 2; ++b)
; #pragma unroll
;                 for (int m = 0; m < 4; ++m)
; #pragma unroll
;                     for (int n = 0; n < 2; ++n) acc[a][b][m][n] = (f32x4){0.f, 0.f, 0.f, 0.f};
.LBB0_201:
	s_ashr_i32 s13, s12, 31
	v_mov_b64_e32 v[0:1], 0x6c0
	s_lshl_b64 s[4:5], s[12:13], 20
	v_cmp_lt_i64_e32 vcc, s[14:15], v[0:1]
	s_add_u32 s14, s92, s4
	s_addc_u32 s15, s93, s5
	s_and_b64 s[4:5], vcc, exec
	s_cselect_b32 s4, s15, s9
	s_cselect_b32 s5, s14, s8
	s_ashr_i32 s11, s10, 31
	s_lshl_b64 s[16:17], s[10:11], 20
	s_add_u32 s16, s23, s16
	s_addc_u32 s17, s24, s17
	s_and_b64 s[20:21], vcc, exec
	s_cselect_b32 s11, s17, s19
	s_cselect_b32 s13, s16, s18
	s_add_u32 s8, s8, 0x80080
	s_addc_u32 s9, s9, 0
	s_add_u32 s33, s18, 0x100
	v_mov_b32_e32 v0, 0
	v_mov_b32_e32 v1, 0
	s_addc_u32 s35, s19, 0
	s_mov_b32 s36, -2
	v_mov_b64_e32 v[2:3], v[0:1]
	v_mov_b64_e32 v[4:5], v[0:1]
	v_mov_b64_e32 v[6:7], v[0:1]
	v_mov_b64_e32 v[8:9], v[0:1]
	v_mov_b64_e32 v[10:11], v[0:1]
	v_mov_b64_e32 v[12:13], v[0:1]
	v_mov_b64_e32 v[14:15], v[0:1]
	v_mov_b64_e32 v[16:17], v[0:1]
	v_mov_b64_e32 v[18:19], v[0:1]
	v_mov_b64_e32 v[20:21], v[0:1]
	v_mov_b64_e32 v[22:23], v[0:1]
	v_mov_b64_e32 v[24:25], v[0:1]
	v_mov_b64_e32 v[26:27], v[0:1]
	v_mov_b64_e32 v[28:29], v[0:1]
	v_mov_b64_e32 v[30:31], v[0:1]
	v_mov_b64_e32 v[32:33], v[0:1]
	v_mov_b64_e32 v[34:35], v[0:1]
	v_mov_b64_e32 v[36:37], v[0:1]
	v_mov_b64_e32 v[38:39], v[0:1]
	v_mov_b64_e32 v[40:41], v[0:1]
	v_mov_b64_e32 v[42:43], v[0:1]
	v_mov_b64_e32 v[44:45], v[0:1]
	v_mov_b64_e32 v[46:47], v[0:1]
	v_mov_b64_e32 v[48:49], v[0:1]
	v_mov_b64_e32 v[50:51], v[0:1]
	v_mov_b64_e32 v[52:53], v[0:1]
	v_mov_b64_e32 v[54:55], v[0:1]
	v_mov_b64_e32 v[56:57], v[0:1]
	v_mov_b64_e32 v[58:59], v[0:1]
	v_mov_b64_e32 v[60:61], v[0:1]
	v_mov_b64_e32 v[62:63], v[0:1]
	v_mov_b64_e32 v[64:65], v[0:1]
	v_mov_b64_e32 v[66:67], v[0:1]
	v_mov_b64_e32 v[68:69], v[0:1]
	v_mov_b64_e32 v[70:71], v[0:1]
	v_mov_b64_e32 v[72:73], v[0:1]
	v_mov_b64_e32 v[74:75], v[0:1]
	v_mov_b64_e32 v[76:77], v[0:1]
	v_mov_b64_e32 v[78:79], v[0:1]
	v_mov_b64_e32 v[80:81], v[0:1]
	v_mov_b64_e32 v[82:83], v[0:1]
	v_mov_b64_e32 v[84:85], v[0:1]
	v_mov_b64_e32 v[86:87], v[0:1]
	v_mov_b64_e32 v[88:89], v[0:1]
	v_mov_b64_e32 v[90:91], v[0:1]
	v_mov_b64_e32 v[92:93], v[0:1]
	v_mov_b64_e32 v[94:95], v[0:1]
	v_mov_b64_e32 v[96:97], v[0:1]
	v_mov_b64_e32 v[98:99], v[0:1]
	v_mov_b64_e32 v[100:101], v[0:1]
	v_mov_b64_e32 v[102:103], v[0:1]
	v_mov_b64_e32 v[104:105], v[0:1]
	v_mov_b64_e32 v[106:107], v[0:1]
	v_mov_b64_e32 v[108:109], v[0:1]
	v_mov_b64_e32 v[110:111], v[0:1]
	v_mov_b64_e32 v[112:113], v[0:1]
	v_mov_b64_e32 v[114:115], v[0:1]
	v_mov_b64_e32 v[116:117], v[0:1]
	v_mov_b64_e32 v[118:119], v[0:1]
	v_mov_b64_e32 v[120:121], v[0:1]
	v_mov_b64_e32 v[122:123], v[0:1]
	v_mov_b64_e32 v[124:125], v[0:1]
	v_mov_b64_e32 v[126:127], v[0:1]
.LBB0_202:
	s_add_u32 s18, s8, 0xfff80080
	s_addc_u32 s19, s9, -1
	s_add_i32 s37, 0, 0x10000
	s_waitcnt lgkmcnt(0)
	ds_read_b128 v[128:131], v187
	ds_read_b128 v[132:135], v187 offset:1024
	ds_read_b128 v[136:139], v187 offset:2048
	ds_read_b128 v[190:193], v187 offset:3072
	s_cmp_eq_u32 s36, 28
	s_cselect_b32 s21, s4, s19
	s_cselect_b32 s20, s5, s18
	s_cselect_b32 s19, s11, s35
	s_cselect_b32 s18, s13, s33
	s_add_i32 m0, s26, 0xc000
	ds_read_b128 v[194:197], v189
	ds_read_b128 v[198:201], v189 offset:1024
	ds_read_b128 v[202:205], v189 offset:2048
	ds_read_b128 v[206:209], v189 offset:3072
	ds_read_b128 v[210:213], v189 offset:4096
	ds_read_b128 v[214:217], v189 offset:5120
	ds_read_b128 v[226:229], v189 offset:6144
	ds_read_b128 v[230:233], v189 offset:7168
	global_load_lds_dwordx4 v150, s[8:9]
	s_add_i32 m0, s26, 0xe000
	s_nop 0
	global_load_lds_dwordx4 v152, s[8:9]
	s_waitcnt lgkmcnt(8)
	s_setprio 1
	s_barrier
	s_waitcnt lgkmcnt(0)
	v_mfma_f32_16x16x32_bf16 v[124:127], v[128:131], v[194:197], v[124:127]
	v_mfma_f32_16x16x32_bf16 v[120:123], v[136:139], v[194:197], v[120:123]
	v_mfma_f32_16x16x32_bf16 v[108:111], v[128:131], v[202:205], v[108:111]
	v_mfma_f32_16x16x32_bf16 v[104:107], v[136:139], v[202:205], v[104:107]
	v_mfma_f32_16x16x32_bf16 v[92:95], v[128:131], v[210:213], v[92:95]
	v_mfma_f32_16x16x32_bf16 v[88:91], v[136:139], v[210:213], v[88:91]
	v_mfma_f32_16x16x32_bf16 v[76:79], v[128:131], v[226:229], v[76:79]
	v_mfma_f32_16x16x32_bf16 v[72:75], v[136:139], v[226:229], v[72:75]
	v_mfma_f32_16x16x32_bf16 v[124:127], v[132:135], v[198:201], v[124:127]
	v_mfma_f32_16x16x32_bf16 v[120:123], v[190:193], v[198:201], v[120:123]
	v_mfma_f32_16x16x32_bf16 v[108:111], v[132:135], v[206:209], v[108:111]
	v_mfma_f32_16x16x32_bf16 v[104:107], v[190:193], v[206:209], v[104:107]
	v_mfma_f32_16x16x32_bf16 v[92:95], v[132:135], v[214:217], v[92:95]
	v_mfma_f32_16x16x32_bf16 v[88:91], v[190:193], v[214:217], v[88:91]
	v_mfma_f32_16x16x32_bf16 v[76:79], v[132:135], v[230:233], v[76:79]
	s_setprio 0
	v_mfma_f32_16x16x32_bf16 v[72:75], v[190:193], v[230:233], v[72:75]
	s_barrier
	ds_read_b128 v[234:237], v187 offset:16384
	ds_read_b128 v[238:241], v187 offset:17408
	ds_read_b128 v[242:245], v187 offset:18432
	ds_read_b128 v[246:249], v187 offset:19456
	s_add_i32 s40, 0, 0x14000
	s_add_i32 s37, s37, s25
	s_mov_b32 m0, s37
	s_nop 0
	global_load_lds_dwordx4 v144, s[18:19]
	s_add_i32 m0, s37, 0x2000
	s_nop 0
	global_load_lds_dwordx4 v142, s[18:19]
	s_waitcnt lgkmcnt(0)
	s_setprio 1
	s_barrier
; #define PG8_STAGE(bufoff, gbase) do { _Pragma("unroll") for (int _i = 0; _i < 2; ++_i) \
;         __builtin_amdgcn_global_load_lds((const unsigned*)((const char*)(gbase) + voff[_i]), (LAS unsigned*)(lds + (bufoff) + ldsw + _i * 8192), 16, 0, 0); } while (0)
; #define PG8_LDA(dst, b, h) do { _Pragma("unroll") for (int m = 0; m < 4; ++m) _Pragma("unroll") for (int k = 0; k < 2; ++k) dst[m][k] = *(const LAS bf16x8*)(lds + PG8_SA(b, h) + aoff + m * 2048 + k * 1024); } while (0)
; #define PG8_LDB(dst, b, h) do { _Pragma("unroll") for (int n = 0; n < 2; ++n) _Pragma("unroll") for (int k = 0; k < 2; ++k) dst[n][k] = *(const LAS bf16x8*)(lds + PG8_SB(b, h) + boff + n * 2048 + k * 1024); } while (0)
; #define PG8_MMA(ai, bj, At, Bt) do { __builtin_amdgcn_s_setprio(1); _Pragma("unroll") for (int m = 0; m < 4; ++m) _Pragma("unroll") for (int n = 0; n < 2; ++n) _Pragma("unroll") for (int k = 0; k < 2; ++k) \
;         acc[ai][bj][m][n] = __builtin_amdgcn_mfma_f32_16x16x32_bf16(Bt[n][k], At[m][k], acc[ai][bj][m][n], 0, 0, 0); __builtin_amdgcn_s_setprio(0); } while (0)
; #define PG8_WAIT_V(n) asm volatile("s_waitcnt vmcnt(" #n ")" ::: "memory")
; #define PG8_WAIT_L(n) asm volatile("s_waitcnt lgkmcnt(" #n ")" ::: "memory")
; #define PG8_BAR __builtin_amdgcn_s_barrier()
; #define PG8_SCHED __builtin_amdgcn_sched_barrier(0)
; template <class Epi>
; DI void gemm_phase(LAS unsigned char* lds, const Gemm g, const StaticOrder& S, const Epi& E) {
;     ...
;             PG8_LDB(B0, 0, 0); PG8_SCHED; PG8_LDA(At, 0, 0); PG8_STAGE(PG8_SA(1, 1), a1 + hstep);
;             PG8_WAIT_L(8); PG8_BAR; PG8_WAIT_L(0); PG8_MMA(0, 0, At, B0); PG8_BAR; PG8_SCHED;
;             PG8_LDB(B1, 0, 1); PG8_STAGE(PG8_SB(0, 0), b2);
;             PG8_BAR; PG8_WAIT_L(0); PG8_MMA(0, 1, At, B1); PG8_BAR;
;             PG8_LDA(At, 0, 1); PG8_STAGE(PG8_SA(0, 0), a2);
;             PG8_BAR; PG8_WAIT_L(0); PG8_MMA(1, 0, At, B0); PG8_BAR; PG8_SCHED;
;             PG8_STAGE(PG8_SB(0, 1), b2 + hstep);
;             PG8_WAIT_V(6); PG8_BAR; PG8_MMA(1, 1, At, B1); PG8_BAR;
;             PG8_LDB(B0, 1, 0); PG8_SCHED; PG8_LDA(At, 1, 0); PG8_STAGE(PG8_SA(0, 1), a2 + hstep);
;             PG8_WAIT_L(8); PG8_BAR; PG8_WAIT_L(0); PG8_MMA(0, 0, At, B0); PG8_BAR; PG8_SCHED;
	v_mfma_f32_16x16x32_bf16 v[116:119], v[234:237], v[194:197], v[116:119]
	v_mfma_f32_16x16x32_bf16 v[112:115], v[242:245], v[194:197], v[112:115]
	v_mfma_f32_16x16x32_bf16 v[100:103], v[234:237], v[202:205], v[100:103]
	v_mfma_f32_16x16x32_bf16 v[96:99], v[242:245], v[202:205], v[96:99]
	v_mfma_f32_16x16x32_bf16 v[84:87], v[234:237], v[210:213], v[84:87]
	v_mfma_f32_16x16x32_bf16 v[80:83], v[242:245], v[210:213], v[80:83]
	v_mfma_f32_16x16x32_bf16 v[68:71], v[234:237], v[226:229], v[68:71]
	v_mfma_f32_16x16x32_bf16 v[64:67], v[242:245], v[226:229], v[64:67]
	v_mfma_f32_16x16x32_bf16 v[116:119], v[238:241], v[198:201], v[116:119]
	s_mov_b32 m0, s26
	v_mfma_f32_16x16x32_bf16 v[112:115], v[246:249], v[198:201], v[112:115]
	v_mfma_f32_16x16x32_bf16 v[100:103], v[238:241], v[206:209], v[100:103]
	v_mfma_f32_16x16x32_bf16 v[96:99], v[246:249], v[206:209], v[96:99]
	v_mfma_f32_16x16x32_bf16 v[84:87], v[238:241], v[214:217], v[84:87]
	v_mfma_f32_16x16x32_bf16 v[80:83], v[246:249], v[214:217], v[80:83]
	v_mfma_f32_16x16x32_bf16 v[68:71], v[238:241], v[230:233], v[68:71]
	s_setprio 0
	v_mfma_f32_16x16x32_bf16 v[64:67], v[246:249], v[230:233], v[64:67]
	s_barrier
	ds_read_b128 v[194:197], v189 offset:16384
	ds_read_b128 v[198:201], v189 offset:17408
	ds_read_b128 v[202:205], v189 offset:18432
	ds_read_b128 v[206:209], v189 offset:19456
	ds_read_b128 v[210:213], v189 offset:20480
	ds_read_b128 v[214:217], v189 offset:21504
	ds_read_b128 v[226:229], v189 offset:22528
	ds_read_b128 v[230:233], v189 offset:23552
	global_load_lds_dwordx4 v144, s[20:21]
	s_mov_b64 s[100:101], s[20:21]
	s_mov_b32 m0, s27
	s_nop 0
	global_load_lds_dwordx4 v142, s[20:21]
	s_waitcnt lgkmcnt(0)
	s_setprio 1
	s_barrier
	v_mfma_f32_16x16x32_bf16 v[60:63], v[128:131], v[194:197], v[60:63]
	v_mfma_f32_16x16x32_bf16 v[56:59], v[136:139], v[194:197], v[56:59]
	v_mfma_f32_16x16x32_bf16 v[44:47], v[128:131], v[202:205], v[44:47]
	v_mfma_f32_16x16x32_bf16 v[40:43], v[136:139], v[202:205], v[40:43]
	v_mfma_f32_16x16x32_bf16 v[28:31], v[128:131], v[210:213], v[28:31]
	v_mfma_f32_16x16x32_bf16 v[24:27], v[136:139], v[210:213], v[24:27]
	v_mfma_f32_16x16x32_bf16 v[12:15], v[128:131], v[226:229], v[12:15]
	v_mfma_f32_16x16x32_bf16 v[8:11], v[136:139], v[226:229], v[8:11]
	v_mfma_f32_16x16x32_bf16 v[60:63], v[132:135], v[198:201], v[60:63]
	v_mfma_f32_16x16x32_bf16 v[56:59], v[190:193], v[198:201], v[56:59]
	v_mfma_f32_16x16x32_bf16 v[44:47], v[132:135], v[206:209], v[44:47]
	v_mfma_f32_16x16x32_bf16 v[40:43], v[190:193], v[206:209], v[40:43]
	v_mfma_f32_16x16x32_bf16 v[28:31], v[132:135], v[214:217], v[28:31]
	v_mfma_f32_16x16x32_bf16 v[24:27], v[190:193], v[214:217], v[24:27]
	v_mfma_f32_16x16x32_bf16 v[12:15], v[132:135], v[230:233], v[12:15]
	s_setprio 0
	v_mfma_f32_16x16x32_bf16 v[8:11], v[190:193], v[230:233], v[8:11]
	s_barrier
	s_add_u32 s38, s18, 0x80000
	s_addc_u32 s39, s19, 0
	s_add_i32 s37, s40, s25
	s_mov_b32 m0, s37
	s_nop 0
	global_load_lds_dwordx4 v144, s[38:39]
	s_add_i32 m0, s37, 0x2000
	s_nop 0
	global_load_lds_dwordx4 v142, s[38:39]
	s_waitcnt vmcnt(6)
	s_setprio 1
	s_barrier
	v_mfma_f32_16x16x32_bf16 v[52:55], v[234:237], v[194:197], v[52:55]
	v_mfma_f32_16x16x32_bf16 v[48:51], v[242:245], v[194:197], v[48:51]
	v_mfma_f32_16x16x32_bf16 v[36:39], v[234:237], v[202:205], v[36:39]
	v_mfma_f32_16x16x32_bf16 v[32:35], v[242:245], v[202:205], v[32:35]
	v_mfma_f32_16x16x32_bf16 v[20:23], v[234:237], v[210:213], v[20:23]
	v_mfma_f32_16x16x32_bf16 v[16:19], v[242:245], v[210:213], v[16:19]
	v_mfma_f32_16x16x32_bf16 v[4:7], v[234:237], v[226:229], v[4:7]
	v_mfma_f32_16x16x32_bf16 v[0:3], v[242:245], v[226:229], v[0:3]
	v_mfma_f32_16x16x32_bf16 v[52:55], v[238:241], v[198:201], v[52:55]
	s_add_i32 s37, 0, 0x18000
	v_mfma_f32_16x16x32_bf16 v[48:51], v[246:249], v[198:201], v[48:51]
	v_mfma_f32_16x16x32_bf16 v[36:39], v[238:241], v[206:209], v[36:39]
	v_mfma_f32_16x16x32_bf16 v[32:35], v[246:249], v[206:209], v[32:35]
	v_mfma_f32_16x16x32_bf16 v[20:23], v[238:241], v[214:217], v[20:23]
	v_mfma_f32_16x16x32_bf16 v[16:19], v[246:249], v[214:217], v[16:19]
	v_mfma_f32_16x16x32_bf16 v[4:7], v[238:241], v[230:233], v[4:7]
	s_setprio 0
	v_mfma_f32_16x16x32_bf16 v[0:3], v[246:249], v[230:233], v[0:3]
	s_barrier
	ds_read_b128 v[128:131], v187 offset:32768
	ds_read_b128 v[132:135], v187 offset:33792
	ds_read_b128 v[136:139], v187 offset:34816
	ds_read_b128 v[190:193], v187 offset:35840
	ds_read_b128 v[194:197], v189 offset:32768
	ds_read_b128 v[198:201], v189 offset:33792
	ds_read_b128 v[202:205], v189 offset:34816
	ds_read_b128 v[206:209], v189 offset:35840
	ds_read_b128 v[210:213], v189 offset:36864
	ds_read_b128 v[214:217], v189 offset:37888
	ds_read_b128 v[226:229], v189 offset:38912
	ds_read_b128 v[230:233], v189 offset:39936
	s_add_u32 s20, s20, 0x80000
	s_addc_u32 s21, s21, 0
	s_mov_b32 m0, s28
	s_nop 0
	global_load_lds_dwordx4 v144, s[20:21]
	s_mov_b32 m0, s29
	s_nop 0
	global_load_lds_dwordx4 v142, s[20:21]
	s_waitcnt lgkmcnt(8)
	s_setprio 1
	s_barrier
	s_waitcnt lgkmcnt(0)
	v_mfma_f32_16x16x32_bf16 v[124:127], v[128:131], v[194:197], v[124:127]
	v_mfma_f32_16x16x32_bf16 v[120:123], v[136:139], v[194:197], v[120:123]
	v_mfma_f32_16x16x32_bf16 v[108:111], v[128:131], v[202:205], v[108:111]
	v_mfma_f32_16x16x32_bf16 v[104:107], v[136:139], v[202:205], v[104:107]
	v_mfma_f32_16x16x32_bf16 v[92:95], v[128:131], v[210:213], v[92:95]
	v_mfma_f32_16x16x32_bf16 v[88:91], v[136:139], v[210:213], v[88:91]
	v_mfma_f32_16x16x32_bf16 v[76:79], v[128:131], v[226:229], v[76:79]
	v_mfma_f32_16x16x32_bf16 v[72:75], v[136:139], v[226:229], v[72:75]
	v_mfma_f32_16x16x32_bf16 v[124:127], v[132:135], v[198:201], v[124:127]
	v_mfma_f32_16x16x32_bf16 v[120:123], v[190:193], v[198:201], v[120:123]
	v_mfma_f32_16x16x32_bf16 v[108:111], v[132:135], v[206:209], v[108:111]
	v_mfma_f32_16x16x32_bf16 v[104:107], v[190:193], v[206:209], v[104:107]
	v_mfma_f32_16x16x32_bf16 v[92:95], v[132:135], v[214:217], v[92:95]
	v_mfma_f32_16x16x32_bf16 v[88:91], v[190:193], v[214:217], v[88:91]
	v_mfma_f32_16x16x32_bf16 v[76:79], v[132:135], v[230:233], v[76:79]
	s_setprio 0
	v_mfma_f32_16x16x32_bf16 v[72:75], v[190:193], v[230:233], v[72:75]
	s_barrier
; #define PG8_STAGE(bufoff, gbase) do { _Pragma("unroll") for (int _i = 0; _i < 2; ++_i) \
;         __builtin_amdgcn_global_load_lds((const unsigned*)((const char*)(gbase) + voff[_i]), (LAS unsigned*)(lds + (bufoff) + ldsw + _i * 8192), 16, 0, 0); } while (0)
; #define PG8_LDA(dst, b, h) do { _Pragma("unroll") for (int m = 0; m < 4; ++m) _Pragma("unroll") for (int k = 0; k < 2; ++k) dst[m][k] = *(const LAS bf16x8*)(lds + PG8_SA(b, h) + aoff + m * 2048 + k * 1024); } while (0)
; #define PG8_MMA(ai, bj, At, Bt) do { __builtin_amdgcn_s_setprio(1); _Pragma("unroll") for (int m = 0; m < 4; ++m) _Pragma("unroll") for (int n = 0; n < 2; ++n) _Pragma("unroll") for (int k = 0; k < 2; ++k) \
;         acc[ai][bj][m][n] = __builtin_amdgcn_mfma_f32_16x16x32_bf16(Bt[n][k], At[m][k], acc[ai][bj][m][n], 0, 0, 0); __builtin_amdgcn_s_setprio(0); } while (0)
; #define PG8_WAIT_V(n) asm volatile("s_waitcnt vmcnt(" #n ")" ::: "memory")
; #define PG8_WAIT_L(n) asm volatile("s_waitcnt lgkmcnt(" #n ")" ::: "memory")
; #define PG8_BAR __builtin_amdgcn_s_barrier()
; #define PG8_SCHED __builtin_amdgcn_sched_barrier(0)
; template <class Epi>
; DI void gemm_phase(LAS unsigned char* lds, const Gemm g, const StaticOrder& S, const Epi& E) {
;     ...
;             PG8_LDA(At, 1, 1); PG8_STAGE(PG8_SA(1, 0), a3);
;             PG8_BAR; PG8_WAIT_L(0); PG8_MMA(1, 0, At, B0); PG8_BAR; PG8_SCHED;
;             PG8_STAGE(PG8_SB(1, 1), b3 + hstep);
;             PG8_WAIT_V(6); PG8_BAR; PG8_MMA(1, 1, At, B1); PG8_BAR;
;         }
;         E(acc, cur, wr, wc, fr, fq);
;         if (!has_next) break;
;     DI void operator()(const f32x4 (&acc)[2][2][4][2], const Unit& u, int wr, int wc, int fr, int fq) const {
;         const int row0 = u.pm * BM + wr * 64 + fr, col0 = u.pn * BM + wc * 16 + 4 * fq;
;         const bool rot = u.pn < 18;
; #pragma unroll
;         for (int ai = 0; ai < 2; ++ai)
; #pragma unroll
;             for (int m = 0; m < 4; ++m) { const int row = row0 + ai * HALF + m * 16; u16* rowp = O + (size_t)row * NQKV_DIL + col0;
;                 f32x4 c4 = (f32x4){1.f, 1.f, 1.f, 1.f}, s4 = (f32x4){0.f, 0.f, 0.f, 0.f};
;                 if (rot) { const int pos = row & (SEQ - 1); c4 = *(const f32x4*)(cs + pos * 64 + wc * 16 + 4 * fq); s4 = *(const f32x4*)(sn + pos * 64 + wc * 16 + 4 * fq); }
	ds_read_b128 v[234:237], v187 offset:49152
	ds_read_b128 v[238:241], v187 offset:50176
	ds_read_b128 v[242:245], v187 offset:51200
	ds_read_b128 v[246:249], v187 offset:52224
	s_add_i32 s20, 0, 0x1c000
	s_add_i32 s21, s37, s25
	s_add_i32 m0, s21, 0xffffff80
	s_nop 0
	global_load_lds_dwordx4 v144, s[18:19] offset:128
	s_add_i32 m0, s21, 0x1f80
	s_nop 0
	global_load_lds_dwordx4 v142, s[18:19] offset:128
	s_waitcnt lgkmcnt(0)
	s_setprio 1
	s_barrier
	v_mfma_f32_16x16x32_bf16 v[116:119], v[234:237], v[194:197], v[116:119]
	v_mfma_f32_16x16x32_bf16 v[112:115], v[242:245], v[194:197], v[112:115]
	v_mfma_f32_16x16x32_bf16 v[100:103], v[234:237], v[202:205], v[100:103]
	v_mfma_f32_16x16x32_bf16 v[96:99], v[242:245], v[202:205], v[96:99]
	v_mfma_f32_16x16x32_bf16 v[84:87], v[234:237], v[210:213], v[84:87]
	v_mfma_f32_16x16x32_bf16 v[80:83], v[242:245], v[210:213], v[80:83]
	v_mfma_f32_16x16x32_bf16 v[68:71], v[234:237], v[226:229], v[68:71]
	v_mfma_f32_16x16x32_bf16 v[64:67], v[242:245], v[226:229], v[64:67]
	v_mfma_f32_16x16x32_bf16 v[116:119], v[238:241], v[198:201], v[116:119]
	s_add_i32 m0, s30, 0xffffff80
	v_mfma_f32_16x16x32_bf16 v[112:115], v[246:249], v[198:201], v[112:115]
	v_mfma_f32_16x16x32_bf16 v[100:103], v[238:241], v[206:209], v[100:103]
	v_mfma_f32_16x16x32_bf16 v[96:99], v[246:249], v[206:209], v[96:99]
	v_mfma_f32_16x16x32_bf16 v[84:87], v[238:241], v[214:217], v[84:87]
	v_mfma_f32_16x16x32_bf16 v[80:83], v[246:249], v[214:217], v[80:83]
	v_mfma_f32_16x16x32_bf16 v[68:71], v[238:241], v[230:233], v[68:71]
	s_setprio 0
	v_mfma_f32_16x16x32_bf16 v[64:67], v[246:249], v[230:233], v[64:67]
	s_barrier
	ds_read_b128 v[194:197], v189 offset:49152
	ds_read_b128 v[198:201], v189 offset:50176
	ds_read_b128 v[202:205], v189 offset:51200
	ds_read_b128 v[206:209], v189 offset:52224
	ds_read_b128 v[210:213], v189 offset:53248
	ds_read_b128 v[214:217], v189 offset:54272
	ds_read_b128 v[226:229], v189 offset:55296
	ds_read_b128 v[230:233], v189 offset:56320
	global_load_lds_dwordx4 v144, s[100:101] offset:128
	s_add_i32 m0, s31, 0xffffff80
	s_nop 0
	global_load_lds_dwordx4 v142, s[100:101] offset:128
	s_waitcnt lgkmcnt(0)
	s_setprio 1
	s_barrier
	v_mfma_f32_16x16x32_bf16 v[60:63], v[128:131], v[194:197], v[60:63]
	v_mfma_f32_16x16x32_bf16 v[56:59], v[136:139], v[194:197], v[56:59]
	v_mfma_f32_16x16x32_bf16 v[44:47], v[128:131], v[202:205], v[44:47]
	v_mfma_f32_16x16x32_bf16 v[40:43], v[136:139], v[202:205], v[40:43]
	v_mfma_f32_16x16x32_bf16 v[28:31], v[128:131], v[210:213], v[28:31]
	v_mfma_f32_16x16x32_bf16 v[24:27], v[136:139], v[210:213], v[24:27]
	v_mfma_f32_16x16x32_bf16 v[12:15], v[128:131], v[226:229], v[12:15]
	v_mfma_f32_16x16x32_bf16 v[8:11], v[136:139], v[226:229], v[8:11]
	v_mfma_f32_16x16x32_bf16 v[60:63], v[132:135], v[198:201], v[60:63]
	v_mfma_f32_16x16x32_bf16 v[56:59], v[190:193], v[198:201], v[56:59]
	v_mfma_f32_16x16x32_bf16 v[44:47], v[132:135], v[206:209], v[44:47]
	v_mfma_f32_16x16x32_bf16 v[40:43], v[190:193], v[206:209], v[40:43]
	v_mfma_f32_16x16x32_bf16 v[28:31], v[132:135], v[214:217], v[28:31]
	v_mfma_f32_16x16x32_bf16 v[24:27], v[190:193], v[214:217], v[24:27]
	v_mfma_f32_16x16x32_bf16 v[12:15], v[132:135], v[230:233], v[12:15]
	s_setprio 0
	v_mfma_f32_16x16x32_bf16 v[8:11], v[190:193], v[230:233], v[8:11]
	s_barrier
	s_add_u32 s18, s18, 0x80080
	s_addc_u32 s19, s19, 0
	s_add_i32 s20, s20, s25
	s_mov_b32 m0, s20
	s_nop 0
	global_load_lds_dwordx4 v144, s[18:19]
	s_add_i32 m0, s20, 0x2000
	s_nop 0
	global_load_lds_dwordx4 v142, s[18:19]
	s_waitcnt vmcnt(6)
	s_setprio 1
	s_barrier
	v_mfma_f32_16x16x32_bf16 v[52:55], v[234:237], v[194:197], v[52:55]
	v_mfma_f32_16x16x32_bf16 v[48:51], v[242:245], v[194:197], v[48:51]
	v_mfma_f32_16x16x32_bf16 v[36:39], v[234:237], v[202:205], v[36:39]
	v_mfma_f32_16x16x32_bf16 v[32:35], v[242:245], v[202:205], v[32:35]
	v_mfma_f32_16x16x32_bf16 v[20:23], v[234:237], v[210:213], v[20:23]
	v_mfma_f32_16x16x32_bf16 v[16:19], v[242:245], v[210:213], v[16:19]
	v_mfma_f32_16x16x32_bf16 v[4:7], v[234:237], v[226:229], v[4:7]
	v_mfma_f32_16x16x32_bf16 v[0:3], v[242:245], v[226:229], v[0:3]
	v_mfma_f32_16x16x32_bf16 v[52:55], v[238:241], v[198:201], v[52:55]
	s_add_i32 s36, s36, 2
	v_mfma_f32_16x16x32_bf16 v[48:51], v[246:249], v[198:201], v[48:51]
	s_add_u32 s8, s8, 0x100
	v_mfma_f32_16x16x32_bf16 v[36:39], v[238:241], v[206:209], v[36:39]
	s_addc_u32 s9, s9, 0
	v_mfma_f32_16x16x32_bf16 v[32:35], v[246:249], v[206:209], v[32:35]
	s_add_u32 s33, s33, 0x100
	v_mfma_f32_16x16x32_bf16 v[20:23], v[238:241], v[214:217], v[20:23]
	s_addc_u32 s35, s35, 0
	v_mfma_f32_16x16x32_bf16 v[16:19], v[246:249], v[214:217], v[16:19]
	s_cmp_gt_u32 s36, 29
	v_mfma_f32_16x16x32_bf16 v[4:7], v[238:241], v[230:233], v[4:7]
	s_setprio 0
	v_mfma_f32_16x16x32_bf16 v[0:3], v[246:249], v[230:233], v[0:3]
	s_barrier
	s_cbranch_scc0 .LBB0_202
	s_cmp_lt_i32 s2, 18
	v_lshl_add_u32 v190, s3, 8, v186
	v_mov_b32_e32 v128, 1.0
	v_mov_b32_e32 v132, 0
	s_cselect_b64 s[18:19], -1, 0
	s_cmp_gt_i32 s2, 17
	v_mov_b32_e32 v134, 0
	v_mov_b32_e32 v135, 0
	v_mov_b32_e32 v136, 0
	v_mov_b32_e32 v137, 0
	v_mov_b32_e32 v138, 1.0
	v_mov_b32_e32 v139, 1.0
	v_mov_b32_e32 v140, 1.0
	v_mov_b32_e32 v141, 1.0
	s_cbranch_scc1 .LBB0_205
	v_lshlrev_b32_e32 v129, 8, v190
	v_and_b32_e32 v158, 0xfcf00, v129
	v_lshl_add_u64 v[130:131], v[146:147], 0, v[158:159]
	v_lshl_add_u64 v[134:135], v[148:149], 0, v[158:159]
	global_load_dwordx4 v[138:141], v[130:131], off
	s_nop 0
	global_load_dwordx4 v[134:137], v[134:135], off

; #define PG8_STAGE(bufoff, gbase) do { _Pragma("unroll") for (int _i = 0; _i < 2; ++_i) \
;         __builtin_amdgcn_global_load_lds((const unsigned*)((const char*)(gbase) + voff[_i]), (LAS unsigned*)(lds + (bufoff) + ldsw + _i * 8192), 16, 0, 0); } while (0)
; #define PG8_LDA(dst, b, h) do { _Pragma("unroll") for (int m = 0; m < 4; ++m) _Pragma("unroll") for (int k = 0; k < 2; ++k) dst[m][k] = *(const LAS bf16x8*)(lds + PG8_SA(b, h) + aoff + m * 2048 + k * 1024); } while (0)
; #define PG8_LDB(dst, b, h) do { _Pragma("unroll") for (int n = 0; n < 2; ++n) _Pragma("unroll") for (int k = 0; k < 2; ++k) dst[n][k] = *(const LAS bf16x8*)(lds + PG8_SB(b, h) + boff + n * 2048 + k * 1024); } while (0)
; #define PG8_MMA(ai, bj, At, Bt) do { __builtin_amdgcn_s_setprio(1); _Pragma("unroll") for (int m = 0; m < 4; ++m) _Pragma("unroll") for (int n = 0; n < 2; ++n) _Pragma("unroll") for (int k = 0; k < 2; ++k) \
;         acc[ai][bj][m][n] = __builtin_amdgcn_mfma_f32_16x16x32_bf16(Bt[n][k], At[m][k], acc[ai][bj][m][n], 0, 0, 0); __builtin_amdgcn_s_setprio(0); } while (0)
; #define PG8_WAIT_L(n) asm volatile("s_waitcnt lgkmcnt(" #n ")" ::: "memory")
; #define PG8_BAR __builtin_amdgcn_s_barrier()
; template <class Epi>
; DI void gemm_phase(LAS unsigned char* lds, const Gemm g, const StaticOrder& S, const Epi& E) {
;     ...
;         const bool has_next = S.next(ui + 1, nxt);
;         const char* nA = has_next ? (const char*)g.A + (size_t)nxt.pm * tstep : cA; const char* nB = has_next ? (const char*)g.Bt + (size_t)nxt.pn * tstep : cB;
;         for (int t = 0; t < nt; t += 2) {
;             const bool last = (t == nt - 2);
;             const char* a1 = cA + (size_t)(t + 1) * kstep;
;             const char* a2 = last ? nA : cA + (size_t)(t + 2) * kstep; const char* b2 = last ? nB : cB + (size_t)(t + 2) * kstep;
;             const char* a3 = a2 + kstep; const char* b3 = b2 + kstep;
;             PG8_LDB(B0, 0, 0); PG8_SCHED; PG8_LDA(At, 0, 0); PG8_STAGE(PG8_SA(1, 1), a1 + hstep);
;             PG8_WAIT_L(8); PG8_BAR; PG8_WAIT_L(0); PG8_MMA(0, 0, At, B0); PG8_BAR; PG8_SCHED;
;     ...
; #pragma unroll
;         for (int a = 0; a < 2; ++a)
; #pragma unroll
;             for (int b = 0; b < 2; ++b)
; #pragma unroll
;                 for (int m = 0; m < 4; ++m)
; #pragma unroll
;                     for (int n = 0; n < 2; ++n) acc[a][b][m][n] = (f32x4){0.f, 0.f, 0.f, 0.f};
.LBB0_230:
	s_ashr_i32 s11, s10, 31
	s_lshl_b64 s[4:5], s[10:11], 20
	v_cmp_lt_i64_e32 vcc, s[12:13], v[166:167]
	s_add_u32 s12, s92, s4
	s_addc_u32 s13, s93, s5
	s_and_b64 s[4:5], vcc, exec
	s_cselect_b32 s4, s13, s17
	s_cselect_b32 s5, s12, s16
	s_ashr_i32 s9, s8, 31
	s_lshl_b64 s[14:15], s[8:9], 20
	s_add_u32 s14, s3, s14
	s_addc_u32 s15, s22, s15
	s_and_b64 s[20:21], vcc, exec
	s_cselect_b32 s9, s15, s19
	s_cselect_b32 s11, s14, s18
	s_add_u32 s16, s16, 0x80080
	s_addc_u32 s17, s17, 0
	s_add_u32 s34, s18, 0x100
	v_mov_b32_e32 v0, 0
	v_mov_b32_e32 v1, 0
	s_addc_u32 s35, s19, 0
	s_mov_b32 s36, -2
	v_mov_b64_e32 v[2:3], v[0:1]
	v_mov_b64_e32 v[4:5], v[0:1]
	v_mov_b64_e32 v[6:7], v[0:1]
	v_mov_b64_e32 v[8:9], v[0:1]
	v_mov_b64_e32 v[10:11], v[0:1]
	v_mov_b64_e32 v[12:13], v[0:1]
	v_mov_b64_e32 v[14:15], v[0:1]
	v_mov_b64_e32 v[16:17], v[0:1]
	v_mov_b64_e32 v[18:19], v[0:1]
	v_mov_b64_e32 v[20:21], v[0:1]
	v_mov_b64_e32 v[22:23], v[0:1]
	v_mov_b64_e32 v[24:25], v[0:1]
	v_mov_b64_e32 v[26:27], v[0:1]
	v_mov_b64_e32 v[28:29], v[0:1]
	v_mov_b64_e32 v[30:31], v[0:1]
	v_mov_b64_e32 v[32:33], v[0:1]
	v_mov_b64_e32 v[34:35], v[0:1]
	v_mov_b64_e32 v[36:37], v[0:1]
	v_mov_b64_e32 v[38:39], v[0:1]
	v_mov_b64_e32 v[40:41], v[0:1]
	v_mov_b64_e32 v[42:43], v[0:1]
	v_mov_b64_e32 v[44:45], v[0:1]
	v_mov_b64_e32 v[46:47], v[0:1]
	v_mov_b64_e32 v[48:49], v[0:1]
	v_mov_b64_e32 v[50:51], v[0:1]
	v_mov_b64_e32 v[52:53], v[0:1]
	v_mov_b64_e32 v[54:55], v[0:1]
	v_mov_b64_e32 v[56:57], v[0:1]
	v_mov_b64_e32 v[58:59], v[0:1]
	v_mov_b64_e32 v[60:61], v[0:1]
	v_mov_b64_e32 v[62:63], v[0:1]
	v_mov_b64_e32 v[64:65], v[0:1]
	v_mov_b64_e32 v[66:67], v[0:1]
	v_mov_b64_e32 v[68:69], v[0:1]
	v_mov_b64_e32 v[70:71], v[0:1]
	v_mov_b64_e32 v[72:73], v[0:1]
	v_mov_b64_e32 v[74:75], v[0:1]
	v_mov_b64_e32 v[76:77], v[0:1]
	v_mov_b64_e32 v[78:79], v[0:1]
	v_mov_b64_e32 v[80:81], v[0:1]
	v_mov_b64_e32 v[82:83], v[0:1]
	v_mov_b64_e32 v[84:85], v[0:1]
	v_mov_b64_e32 v[86:87], v[0:1]
	v_mov_b64_e32 v[88:89], v[0:1]
	v_mov_b64_e32 v[90:91], v[0:1]
	v_mov_b64_e32 v[92:93], v[0:1]
	v_mov_b64_e32 v[94:95], v[0:1]
	v_mov_b64_e32 v[96:97], v[0:1]
	v_mov_b64_e32 v[98:99], v[0:1]
	v_mov_b64_e32 v[100:101], v[0:1]
	v_mov_b64_e32 v[102:103], v[0:1]
	v_mov_b64_e32 v[104:105], v[0:1]
	v_mov_b64_e32 v[106:107], v[0:1]
	v_mov_b64_e32 v[108:109], v[0:1]
	v_mov_b64_e32 v[110:111], v[0:1]
	v_mov_b64_e32 v[112:113], v[0:1]
	v_mov_b64_e32 v[114:115], v[0:1]
	v_mov_b64_e32 v[116:117], v[0:1]
	v_mov_b64_e32 v[118:119], v[0:1]
	v_mov_b64_e32 v[120:121], v[0:1]
	v_mov_b64_e32 v[122:123], v[0:1]
	v_mov_b64_e32 v[124:125], v[0:1]
	v_mov_b64_e32 v[126:127], v[0:1]
.LBB0_231:
	ds_read_b128 v[138:141], v135
	ds_read_b128 v[142:145], v135 offset:1024
	ds_read_b128 v[146:149], v135 offset:2048
	ds_read_b128 v[150:153], v135 offset:3072
	ds_read_b128 v[186:189], v137
	ds_read_b128 v[190:193], v137 offset:1024
	ds_read_b128 v[194:197], v137 offset:2048
	ds_read_b128 v[198:201], v137 offset:3072
	ds_read_b128 v[202:205], v137 offset:4096
	ds_read_b128 v[206:209], v137 offset:5120
	ds_read_b128 v[210:213], v137 offset:6144
	ds_read_b128 v[214:217], v137 offset:7168
	s_add_u32 s18, s16, 0xfff80080
	s_addc_u32 s19, s17, -1
	s_add_i32 s37, 0, 0x10000
	s_cmp_eq_u32 s36, 28
	s_cselect_b32 s21, s4, s19
	s_cselect_b32 s20, s5, s18
	s_cselect_b32 s19, s9, s35
	s_cselect_b32 s18, s11, s34
	s_add_i32 m0, s24, 0xc000
	s_nop 0
	global_load_lds_dwordx4 v130, s[16:17]
	s_add_i32 m0, s24, 0xe000
	s_nop 0
	global_load_lds_dwordx4 v132, s[16:17]
	s_waitcnt lgkmcnt(8)
	s_setprio 1
	s_barrier
	s_waitcnt lgkmcnt(0)
	v_mfma_f32_16x16x32_bf16 v[124:127], v[138:141], v[186:189], v[124:127]
	v_mfma_f32_16x16x32_bf16 v[120:123], v[146:149], v[186:189], v[120:123]
	v_mfma_f32_16x16x32_bf16 v[116:119], v[138:141], v[194:197], v[116:119]
	v_mfma_f32_16x16x32_bf16 v[112:115], v[146:149], v[194:197], v[112:115]
	v_mfma_f32_16x16x32_bf16 v[100:103], v[138:141], v[202:205], v[100:103]
	v_mfma_f32_16x16x32_bf16 v[96:99], v[146:149], v[202:205], v[96:99]
	v_mfma_f32_16x16x32_bf16 v[84:87], v[138:141], v[210:213], v[84:87]
	v_mfma_f32_16x16x32_bf16 v[80:83], v[146:149], v[210:213], v[80:83]
	v_mfma_f32_16x16x32_bf16 v[124:127], v[142:145], v[190:193], v[124:127]
	v_mfma_f32_16x16x32_bf16 v[120:123], v[150:153], v[190:193], v[120:123]
	v_mfma_f32_16x16x32_bf16 v[116:119], v[142:145], v[198:201], v[116:119]
	v_mfma_f32_16x16x32_bf16 v[112:115], v[150:153], v[198:201], v[112:115]
	v_mfma_f32_16x16x32_bf16 v[100:103], v[142:145], v[206:209], v[100:103]
	v_mfma_f32_16x16x32_bf16 v[96:99], v[150:153], v[206:209], v[96:99]
	v_mfma_f32_16x16x32_bf16 v[84:87], v[142:145], v[214:217], v[84:87]
	s_setprio 0
	v_mfma_f32_16x16x32_bf16 v[80:83], v[150:153], v[214:217], v[80:83]
	s_barrier
	ds_read_b128 v[226:229], v135 offset:16384
	ds_read_b128 v[230:233], v135 offset:17408
	ds_read_b128 v[234:237], v135 offset:18432
	ds_read_b128 v[238:241], v135 offset:19456
	s_add_i32 s40, 0, 0x14000
	s_add_i32 s37, s37, s23
	s_mov_b32 m0, s37
	s_nop 0
	global_load_lds_dwordx4 v158, s[18:19]
	s_add_i32 m0, s37, 0x2000
	s_nop 0
	global_load_lds_dwordx4 v128, s[18:19]
	s_waitcnt lgkmcnt(0)
	s_setprio 1
	s_barrier
; #define PG8_STAGE(bufoff, gbase) do { _Pragma("unroll") for (int _i = 0; _i < 2; ++_i) \
;         __builtin_amdgcn_global_load_lds((const unsigned*)((const char*)(gbase) + voff[_i]), (LAS unsigned*)(lds + (bufoff) + ldsw + _i * 8192), 16, 0, 0); } while (0)
; #define PG8_LDA(dst, b, h) do { _Pragma("unroll") for (int m = 0; m < 4; ++m) _Pragma("unroll") for (int k = 0; k < 2; ++k) dst[m][k] = *(const LAS bf16x8*)(lds + PG8_SA(b, h) + aoff + m * 2048 + k * 1024); } while (0)
; #define PG8_LDB(dst, b, h) do { _Pragma("unroll") for (int n = 0; n < 2; ++n) _Pragma("unroll") for (int k = 0; k < 2; ++k) dst[n][k] = *(const LAS bf16x8*)(lds + PG8_SB(b, h) + boff + n * 2048 + k * 1024); } while (0)
; #define PG8_MMA(ai, bj, At, Bt) do { __builtin_amdgcn_s_setprio(1); _Pragma("unroll") for (int m = 0; m < 4; ++m) _Pragma("unroll") for (int n = 0; n < 2; ++n) _Pragma("unroll") for (int k = 0; k < 2; ++k) \
;         acc[ai][bj][m][n] = __builtin_amdgcn_mfma_f32_16x16x32_bf16(Bt[n][k], At[m][k], acc[ai][bj][m][n], 0, 0, 0); __builtin_amdgcn_s_setprio(0); } while (0)
; #define PG8_WAIT_V(n) asm volatile("s_waitcnt vmcnt(" #n ")" ::: "memory")
; #define PG8_WAIT_L(n) asm volatile("s_waitcnt lgkmcnt(" #n ")" ::: "memory")
; #define PG8_BAR __builtin_amdgcn_s_barrier()
; #define PG8_SCHED __builtin_amdgcn_sched_barrier(0)
; template <class Epi>
; DI void gemm_phase(LAS unsigned char* lds, const Gemm g, const StaticOrder& S, const Epi& E) {
;     ...
;             PG8_LDB(B0, 0, 0); PG8_SCHED; PG8_LDA(At, 0, 0); PG8_STAGE(PG8_SA(1, 1), a1 + hstep);
;             PG8_WAIT_L(8); PG8_BAR; PG8_WAIT_L(0); PG8_MMA(0, 0, At, B0); PG8_BAR; PG8_SCHED;
;             PG8_LDB(B1, 0, 1); PG8_STAGE(PG8_SB(0, 0), b2);
;             PG8_BAR; PG8_WAIT_L(0); PG8_MMA(0, 1, At, B1); PG8_BAR;
;             PG8_LDA(At, 0, 1); PG8_STAGE(PG8_SA(0, 0), a2);
;             PG8_BAR; PG8_WAIT_L(0); PG8_MMA(1, 0, At, B0); PG8_BAR; PG8_SCHED;
;             PG8_STAGE(PG8_SB(0, 1), b2 + hstep);
;             PG8_WAIT_V(6); PG8_BAR; PG8_MMA(1, 1, At, B1); PG8_BAR;
;             PG8_LDB(B0, 1, 0); PG8_SCHED; PG8_LDA(At, 1, 0); PG8_STAGE(PG8_SA(0, 1), a2 + hstep);
;             PG8_WAIT_L(8); PG8_BAR; PG8_WAIT_L(0); PG8_MMA(0, 0, At, B0); PG8_BAR; PG8_SCHED;
	v_mfma_f32_16x16x32_bf16 v[108:111], v[226:229], v[186:189], v[108:111]
	v_mfma_f32_16x16x32_bf16 v[104:107], v[234:237], v[186:189], v[104:107]
	v_mfma_f32_16x16x32_bf16 v[92:95], v[226:229], v[194:197], v[92:95]
	v_mfma_f32_16x16x32_bf16 v[88:91], v[234:237], v[194:197], v[88:91]
	v_mfma_f32_16x16x32_bf16 v[76:79], v[226:229], v[202:205], v[76:79]
	v_mfma_f32_16x16x32_bf16 v[72:75], v[234:237], v[202:205], v[72:75]
	v_mfma_f32_16x16x32_bf16 v[68:71], v[226:229], v[210:213], v[68:71]
	v_mfma_f32_16x16x32_bf16 v[64:67], v[234:237], v[210:213], v[64:67]
	v_mfma_f32_16x16x32_bf16 v[108:111], v[230:233], v[190:193], v[108:111]
	s_mov_b32 m0, s24
	v_mfma_f32_16x16x32_bf16 v[104:107], v[238:241], v[190:193], v[104:107]
	v_mfma_f32_16x16x32_bf16 v[92:95], v[230:233], v[198:201], v[92:95]
	v_mfma_f32_16x16x32_bf16 v[88:91], v[238:241], v[198:201], v[88:91]
	v_mfma_f32_16x16x32_bf16 v[76:79], v[230:233], v[206:209], v[76:79]
	v_mfma_f32_16x16x32_bf16 v[72:75], v[238:241], v[206:209], v[72:75]
	v_mfma_f32_16x16x32_bf16 v[68:71], v[230:233], v[214:217], v[68:71]
	s_setprio 0
	v_mfma_f32_16x16x32_bf16 v[64:67], v[238:241], v[214:217], v[64:67]
	s_barrier
	ds_read_b128 v[186:189], v137 offset:16384
	ds_read_b128 v[190:193], v137 offset:17408
	ds_read_b128 v[194:197], v137 offset:18432
	ds_read_b128 v[198:201], v137 offset:19456
	ds_read_b128 v[202:205], v137 offset:20480
	ds_read_b128 v[206:209], v137 offset:21504
	ds_read_b128 v[210:213], v137 offset:22528
	ds_read_b128 v[214:217], v137 offset:23552
	global_load_lds_dwordx4 v158, s[20:21]
	s_mov_b64 s[100:101], s[20:21]
	s_mov_b32 m0, s25
	s_nop 0
	global_load_lds_dwordx4 v128, s[20:21]
	s_waitcnt lgkmcnt(0)
	s_setprio 1
	s_barrier
	v_mfma_f32_16x16x32_bf16 v[60:63], v[138:141], v[186:189], v[60:63]
	v_mfma_f32_16x16x32_bf16 v[56:59], v[146:149], v[186:189], v[56:59]
	v_mfma_f32_16x16x32_bf16 v[52:55], v[138:141], v[194:197], v[52:55]
	v_mfma_f32_16x16x32_bf16 v[48:51], v[146:149], v[194:197], v[48:51]
	v_mfma_f32_16x16x32_bf16 v[36:39], v[138:141], v[202:205], v[36:39]
	v_mfma_f32_16x16x32_bf16 v[32:35], v[146:149], v[202:205], v[32:35]
	v_mfma_f32_16x16x32_bf16 v[20:23], v[138:141], v[210:213], v[20:23]
	v_mfma_f32_16x16x32_bf16 v[16:19], v[146:149], v[210:213], v[16:19]
	v_mfma_f32_16x16x32_bf16 v[60:63], v[142:145], v[190:193], v[60:63]
	v_mfma_f32_16x16x32_bf16 v[56:59], v[150:153], v[190:193], v[56:59]
	v_mfma_f32_16x16x32_bf16 v[52:55], v[142:145], v[198:201], v[52:55]
	v_mfma_f32_16x16x32_bf16 v[48:51], v[150:153], v[198:201], v[48:51]
	v_mfma_f32_16x16x32_bf16 v[36:39], v[142:145], v[206:209], v[36:39]
	v_mfma_f32_16x16x32_bf16 v[32:35], v[150:153], v[206:209], v[32:35]
	v_mfma_f32_16x16x32_bf16 v[20:23], v[142:145], v[214:217], v[20:23]
	s_setprio 0
	v_mfma_f32_16x16x32_bf16 v[16:19], v[150:153], v[214:217], v[16:19]
	s_barrier
	s_add_u32 s38, s18, 0x80000
	s_addc_u32 s39, s19, 0
	s_add_i32 s37, s40, s23
	s_mov_b32 m0, s37
	s_nop 0
	global_load_lds_dwordx4 v158, s[38:39]
	s_add_i32 m0, s37, 0x2000
	s_nop 0
	global_load_lds_dwordx4 v128, s[38:39]
	s_waitcnt vmcnt(6)
	s_setprio 1
	s_barrier
	v_mfma_f32_16x16x32_bf16 v[44:47], v[226:229], v[186:189], v[44:47]
	v_mfma_f32_16x16x32_bf16 v[40:43], v[234:237], v[186:189], v[40:43]
	v_mfma_f32_16x16x32_bf16 v[28:31], v[226:229], v[194:197], v[28:31]
	v_mfma_f32_16x16x32_bf16 v[24:27], v[234:237], v[194:197], v[24:27]
	v_mfma_f32_16x16x32_bf16 v[12:15], v[226:229], v[202:205], v[12:15]
	v_mfma_f32_16x16x32_bf16 v[8:11], v[234:237], v[202:205], v[8:11]
	v_mfma_f32_16x16x32_bf16 v[4:7], v[226:229], v[210:213], v[4:7]
	v_mfma_f32_16x16x32_bf16 v[0:3], v[234:237], v[210:213], v[0:3]
	v_mfma_f32_16x16x32_bf16 v[44:47], v[230:233], v[190:193], v[44:47]
	s_add_i32 s37, 0, 0x18000
	v_mfma_f32_16x16x32_bf16 v[40:43], v[238:241], v[190:193], v[40:43]
	v_mfma_f32_16x16x32_bf16 v[28:31], v[230:233], v[198:201], v[28:31]
	v_mfma_f32_16x16x32_bf16 v[24:27], v[238:241], v[198:201], v[24:27]
	v_mfma_f32_16x16x32_bf16 v[12:15], v[230:233], v[206:209], v[12:15]
	v_mfma_f32_16x16x32_bf16 v[8:11], v[238:241], v[206:209], v[8:11]
	v_mfma_f32_16x16x32_bf16 v[4:7], v[230:233], v[214:217], v[4:7]
	s_setprio 0
	v_mfma_f32_16x16x32_bf16 v[0:3], v[238:241], v[214:217], v[0:3]
	s_barrier
	ds_read_b128 v[138:141], v135 offset:32768
	ds_read_b128 v[142:145], v135 offset:33792
	ds_read_b128 v[146:149], v135 offset:34816
	ds_read_b128 v[150:153], v135 offset:35840
	ds_read_b128 v[186:189], v137 offset:32768
	ds_read_b128 v[190:193], v137 offset:33792
	ds_read_b128 v[194:197], v137 offset:34816
	ds_read_b128 v[198:201], v137 offset:35840
	ds_read_b128 v[202:205], v137 offset:36864
	ds_read_b128 v[206:209], v137 offset:37888
	ds_read_b128 v[210:213], v137 offset:38912
	ds_read_b128 v[214:217], v137 offset:39936
	s_add_u32 s20, s20, 0x80000
	s_addc_u32 s21, s21, 0
	s_mov_b32 m0, s26
	s_nop 0
	global_load_lds_dwordx4 v158, s[20:21]
	s_mov_b32 m0, s27
	s_nop 0
	global_load_lds_dwordx4 v128, s[20:21]
	s_waitcnt lgkmcnt(8)
	s_setprio 1
	s_barrier
	s_waitcnt lgkmcnt(0)
	v_mfma_f32_16x16x32_bf16 v[124:127], v[138:141], v[186:189], v[124:127]
	v_mfma_f32_16x16x32_bf16 v[120:123], v[146:149], v[186:189], v[120:123]
	v_mfma_f32_16x16x32_bf16 v[116:119], v[138:141], v[194:197], v[116:119]
	v_mfma_f32_16x16x32_bf16 v[112:115], v[146:149], v[194:197], v[112:115]
	v_mfma_f32_16x16x32_bf16 v[100:103], v[138:141], v[202:205], v[100:103]
	v_mfma_f32_16x16x32_bf16 v[96:99], v[146:149], v[202:205], v[96:99]
	v_mfma_f32_16x16x32_bf16 v[84:87], v[138:141], v[210:213], v[84:87]
	v_mfma_f32_16x16x32_bf16 v[80:83], v[146:149], v[210:213], v[80:83]
	v_mfma_f32_16x16x32_bf16 v[124:127], v[142:145], v[190:193], v[124:127]
	v_mfma_f32_16x16x32_bf16 v[120:123], v[150:153], v[190:193], v[120:123]
	v_mfma_f32_16x16x32_bf16 v[116:119], v[142:145], v[198:201], v[116:119]
	v_mfma_f32_16x16x32_bf16 v[112:115], v[150:153], v[198:201], v[112:115]
	v_mfma_f32_16x16x32_bf16 v[100:103], v[142:145], v[206:209], v[100:103]
	v_mfma_f32_16x16x32_bf16 v[96:99], v[150:153], v[206:209], v[96:99]
	v_mfma_f32_16x16x32_bf16 v[84:87], v[142:145], v[214:217], v[84:87]
	s_setprio 0
	v_mfma_f32_16x16x32_bf16 v[80:83], v[150:153], v[214:217], v[80:83]
	s_barrier
; #define PG8_STAGE(bufoff, gbase) do { _Pragma("unroll") for (int _i = 0; _i < 2; ++_i) \
;         __builtin_amdgcn_global_load_lds((const unsigned*)((const char*)(gbase) + voff[_i]), (LAS unsigned*)(lds + (bufoff) + ldsw + _i * 8192), 16, 0, 0); } while (0)
; #define PG8_LDA(dst, b, h) do { _Pragma("unroll") for (int m = 0; m < 4; ++m) _Pragma("unroll") for (int k = 0; k < 2; ++k) dst[m][k] = *(const LAS bf16x8*)(lds + PG8_SA(b, h) + aoff + m * 2048 + k * 1024); } while (0)
; #define PG8_MMA(ai, bj, At, Bt) do { __builtin_amdgcn_s_setprio(1); _Pragma("unroll") for (int m = 0; m < 4; ++m) _Pragma("unroll") for (int n = 0; n < 2; ++n) _Pragma("unroll") for (int k = 0; k < 2; ++k) \
;         acc[ai][bj][m][n] = __builtin_amdgcn_mfma_f32_16x16x32_bf16(Bt[n][k], At[m][k], acc[ai][bj][m][n], 0, 0, 0); __builtin_amdgcn_s_setprio(0); } while (0)
; #define PG8_WAIT_V(n) asm volatile("s_waitcnt vmcnt(" #n ")" ::: "memory")
; #define PG8_WAIT_L(n) asm volatile("s_waitcnt lgkmcnt(" #n ")" ::: "memory")
; #define PG8_BAR __builtin_amdgcn_s_barrier()
; #define PG8_SCHED __builtin_amdgcn_sched_barrier(0)
; template <class Epi>
; DI void gemm_phase(LAS unsigned char* lds, const Gemm g, const StaticOrder& S, const Epi& E) {
;     ...
;             PG8_LDA(At, 1, 1); PG8_STAGE(PG8_SA(1, 0), a3);
;             PG8_BAR; PG8_WAIT_L(0); PG8_MMA(1, 0, At, B0); PG8_BAR; PG8_SCHED;
;             PG8_STAGE(PG8_SB(1, 1), b3 + hstep);
;             PG8_WAIT_V(6); PG8_BAR; PG8_MMA(1, 1, At, B1); PG8_BAR;
	ds_read_b128 v[226:229], v135 offset:49152
	ds_read_b128 v[230:233], v135 offset:50176
	ds_read_b128 v[234:237], v135 offset:51200
	ds_read_b128 v[238:241], v135 offset:52224
	s_add_i32 s20, 0, 0x1c000
	s_add_i32 s21, s37, s23
	s_add_i32 m0, s21, 0xffffff80
	s_nop 0
	global_load_lds_dwordx4 v158, s[18:19] offset:128
	s_add_i32 m0, s21, 0x1f80
	s_nop 0
	global_load_lds_dwordx4 v128, s[18:19] offset:128
	s_waitcnt lgkmcnt(0)
	s_setprio 1
	s_barrier
	v_mfma_f32_16x16x32_bf16 v[108:111], v[226:229], v[186:189], v[108:111]
	v_mfma_f32_16x16x32_bf16 v[104:107], v[234:237], v[186:189], v[104:107]
	v_mfma_f32_16x16x32_bf16 v[92:95], v[226:229], v[194:197], v[92:95]
	v_mfma_f32_16x16x32_bf16 v[88:91], v[234:237], v[194:197], v[88:91]
	v_mfma_f32_16x16x32_bf16 v[76:79], v[226:229], v[202:205], v[76:79]
	v_mfma_f32_16x16x32_bf16 v[72:75], v[234:237], v[202:205], v[72:75]
	v_mfma_f32_16x16x32_bf16 v[68:71], v[226:229], v[210:213], v[68:71]
	v_mfma_f32_16x16x32_bf16 v[64:67], v[234:237], v[210:213], v[64:67]
	v_mfma_f32_16x16x32_bf16 v[108:111], v[230:233], v[190:193], v[108:111]
	s_add_i32 m0, s28, 0xffffff80
	v_mfma_f32_16x16x32_bf16 v[104:107], v[238:241], v[190:193], v[104:107]
	v_mfma_f32_16x16x32_bf16 v[92:95], v[230:233], v[198:201], v[92:95]
	v_mfma_f32_16x16x32_bf16 v[88:91], v[238:241], v[198:201], v[88:91]
	v_mfma_f32_16x16x32_bf16 v[76:79], v[230:233], v[206:209], v[76:79]
	v_mfma_f32_16x16x32_bf16 v[72:75], v[238:241], v[206:209], v[72:75]
	v_mfma_f32_16x16x32_bf16 v[68:71], v[230:233], v[214:217], v[68:71]
	s_setprio 0
	v_mfma_f32_16x16x32_bf16 v[64:67], v[238:241], v[214:217], v[64:67]
	s_barrier
	ds_read_b128 v[186:189], v137 offset:49152
	ds_read_b128 v[190:193], v137 offset:50176
	ds_read_b128 v[194:197], v137 offset:51200
	ds_read_b128 v[198:201], v137 offset:52224
	ds_read_b128 v[202:205], v137 offset:53248
	ds_read_b128 v[206:209], v137 offset:54272
	ds_read_b128 v[210:213], v137 offset:55296
	ds_read_b128 v[214:217], v137 offset:56320
	global_load_lds_dwordx4 v158, s[100:101] offset:128
	s_add_i32 m0, s29, 0xffffff80
	s_nop 0
	global_load_lds_dwordx4 v128, s[100:101] offset:128
	s_waitcnt lgkmcnt(0)
	s_setprio 1
	s_barrier
	v_mfma_f32_16x16x32_bf16 v[60:63], v[138:141], v[186:189], v[60:63]
	v_mfma_f32_16x16x32_bf16 v[56:59], v[146:149], v[186:189], v[56:59]
	v_mfma_f32_16x16x32_bf16 v[52:55], v[138:141], v[194:197], v[52:55]
	v_mfma_f32_16x16x32_bf16 v[48:51], v[146:149], v[194:197], v[48:51]
	v_mfma_f32_16x16x32_bf16 v[36:39], v[138:141], v[202:205], v[36:39]
	v_mfma_f32_16x16x32_bf16 v[32:35], v[146:149], v[202:205], v[32:35]
	v_mfma_f32_16x16x32_bf16 v[20:23], v[138:141], v[210:213], v[20:23]
	v_mfma_f32_16x16x32_bf16 v[16:19], v[146:149], v[210:213], v[16:19]
	v_mfma_f32_16x16x32_bf16 v[60:63], v[142:145], v[190:193], v[60:63]
	v_mfma_f32_16x16x32_bf16 v[56:59], v[150:153], v[190:193], v[56:59]
	v_mfma_f32_16x16x32_bf16 v[52:55], v[142:145], v[198:201], v[52:55]
	v_mfma_f32_16x16x32_bf16 v[48:51], v[150:153], v[198:201], v[48:51]
	v_mfma_f32_16x16x32_bf16 v[36:39], v[142:145], v[206:209], v[36:39]
	v_mfma_f32_16x16x32_bf16 v[32:35], v[150:153], v[206:209], v[32:35]
	v_mfma_f32_16x16x32_bf16 v[20:23], v[142:145], v[214:217], v[20:23]
	s_setprio 0
	v_mfma_f32_16x16x32_bf16 v[16:19], v[150:153], v[214:217], v[16:19]
	s_barrier
	s_add_u32 s18, s18, 0x80080
	s_addc_u32 s19, s19, 0
	s_add_i32 s20, s20, s23
	s_mov_b32 m0, s20
	s_nop 0
	global_load_lds_dwordx4 v158, s[18:19]
	s_add_i32 m0, s20, 0x2000
	s_nop 0
	global_load_lds_dwordx4 v128, s[18:19]
	s_waitcnt vmcnt(6)
	s_setprio 1
	s_barrier
	v_mfma_f32_16x16x32_bf16 v[44:47], v[226:229], v[186:189], v[44:47]
	v_mfma_f32_16x16x32_bf16 v[40:43], v[234:237], v[186:189], v[40:43]
	v_mfma_f32_16x16x32_bf16 v[28:31], v[226:229], v[194:197], v[28:31]
	v_mfma_f32_16x16x32_bf16 v[24:27], v[234:237], v[194:197], v[24:27]
	v_mfma_f32_16x16x32_bf16 v[12:15], v[226:229], v[202:205], v[12:15]
	v_mfma_f32_16x16x32_bf16 v[8:11], v[234:237], v[202:205], v[8:11]
	v_mfma_f32_16x16x32_bf16 v[4:7], v[226:229], v[210:213], v[4:7]
	v_mfma_f32_16x16x32_bf16 v[0:3], v[234:237], v[210:213], v[0:3]
	v_mfma_f32_16x16x32_bf16 v[44:47], v[230:233], v[190:193], v[44:47]
	s_add_i32 s36, s36, 2
	v_mfma_f32_16x16x32_bf16 v[40:43], v[238:241], v[190:193], v[40:43]
	s_add_u32 s16, s16, 0x100
	v_mfma_f32_16x16x32_bf16 v[28:31], v[230:233], v[198:201], v[28:31]
	s_addc_u32 s17, s17, 0
	v_mfma_f32_16x16x32_bf16 v[24:27], v[238:241], v[198:201], v[24:27]
	s_add_u32 s34, s34, 0x100
	v_mfma_f32_16x16x32_bf16 v[12:15], v[230:233], v[206:209], v[12:15]
	s_addc_u32 s35, s35, 0
	v_mfma_f32_16x16x32_bf16 v[8:11], v[238:241], v[206:209], v[8:11]
	s_cmp_gt_u32 s36, 29
	v_mfma_f32_16x16x32_bf16 v[4:7], v[230:233], v[214:217], v[4:7]
	s_setprio 0
	v_mfma_f32_16x16x32_bf16 v[0:3], v[238:241], v[214:217], v[0:3]
	s_barrier
; #define PG8_WAIT_V(n) asm volatile("s_waitcnt vmcnt(" #n ")" ::: "memory")
; #define PG8_BAR __builtin_amdgcn_s_barrier()
; template <class Epi>
; DI void gemm_phase(LAS unsigned char* lds, const Gemm g, const StaticOrder& S, const Epi& E) {
;     ...
;         E(acc, cur, wr, wc, fr, fq);
;         if (!has_next) break;
; #pragma unroll
;         for (int a = 0; a < 2; ++a)
; #pragma unroll
;             for (int b = 0; b < 2; ++b)
; #pragma unroll
;                 for (int m = 0; m < 4; ++m)
; #pragma unroll
;                     for (int n = 0; n < 2; ++n) acc[a][b][m][n] = (f32x4){0.f, 0.f, 0.f, 0.f};
;         cur = nxt; cA = nA; cB = nB; ++ui;
;     }
;     PG8_WAIT_V(0);
;     if (wr == 0) PG8_BAR;
;     PG8_BAR;
;     DI void operator()(const f32x4 (&acc)[2][2][4][2], const Unit& u, int wr, int wc, int fr, int fq) const {
;         const int row0 = u.pm * BM + wr * 64 + fr, col0 = u.pn * BM + wc * 32 + 8 * fq;
; #pragma unroll
;         for (int ai = 0; ai < 2; ++ai)
; #pragma unroll
;             for (int m = 0; m < 4; ++m) { u16* rowp = O + (size_t)(row0 + ai * HALF + m * 16) * ldc + col0;
; #pragma unroll
;                 for (int bj = 0; bj < 2; ++bj) { const f32x4 v0 = acc[ai][bj][m][0], v1 = acc[ai][bj][m][1];
;                     *(u32x4*)(rowp + bj * HALF) = (u32x4){pk(v0[0], v0[1]), pk(v0[2], v0[3]), pk(v1[0], v1[1]), pk(v1[2], v1[3])}; } }
	s_cbranch_scc0 .LBB0_231
	v_lshl_add_u32 v144, s33, 8, v134
	v_lshl_or_b32 v138, s31, 8, v136
	v_ashrrev_i32_e32 v139, 31, v138
	v_mov_b64_e32 v[140:141], s[50:51]
	s_movk_i32 s9, 0x3000
	v_cvt_pk_bf16_f32 v68, v68, v69
	v_cvt_pk_bf16_f32 v69, v70, v71
	v_cvt_pk_bf16_f32 v70, v64, v65
	v_add_u32_e32 v64, 0x80, v144
	v_mad_i64_i32 v[142:143], s[4:5], v144, s9, v[140:141]
	v_lshlrev_b64 v[138:139], 1, v[138:139]
	v_cvt_pk_bf16_f32 v108, v108, v109
	v_cvt_pk_bf16_f32 v109, v110, v111
	v_cvt_pk_bf16_f32 v110, v104, v105
	v_or_b32_e32 v104, 16, v144
	v_mad_i64_i32 v[64:65], s[4:5], v64, s9, v[140:141]
	v_cvt_pk_bf16_f32 v44, v44, v45
	v_cvt_pk_bf16_f32 v45, v46, v47
	v_cvt_pk_bf16_f32 v46, v40, v41
	v_add_u32_e32 v40, 0x90, v144
	v_lshl_add_u64 v[142:143], v[142:143], 0, v[138:139]
	v_cvt_pk_bf16_f32 v111, v106, v107
	v_mad_i64_i32 v[104:105], s[4:5], v104, s9, v[140:141]
	v_cvt_pk_bf16_f32 v92, v92, v93
	v_cvt_pk_bf16_f32 v93, v94, v95
	v_cvt_pk_bf16_f32 v94, v88, v89
	v_or_b32_e32 v88, 32, v144
	v_lshl_add_u64 v[64:65], v[64:65], 0, v[138:139]
	v_cvt_pk_bf16_f32 v47, v42, v43
	v_mad_i64_i32 v[40:41], s[4:5], v40, s9, v[140:141]
	v_cvt_pk_bf16_f32 v28, v28, v29
	v_cvt_pk_bf16_f32 v29, v30, v31
	v_cvt_pk_bf16_f32 v30, v24, v25
	v_add_u32_e32 v24, 0xa0, v144
	global_store_dwordx4 v[142:143], v[108:111], off offset:256
	v_cvt_pk_bf16_f32 v95, v90, v91
	v_mad_i64_i32 v[88:89], s[4:5], v88, s9, v[140:141]
	v_lshl_add_u64 v[108:109], v[104:105], 0, v[138:139]
	v_cvt_pk_bf16_f32 v76, v76, v77
	v_cvt_pk_bf16_f32 v77, v78, v79
	v_cvt_pk_bf16_f32 v78, v72, v73
	v_or_b32_e32 v72, 48, v144
	global_store_dwordx4 v[64:65], v[44:47], off offset:256
	v_cvt_pk_bf16_f32 v31, v26, v27
	v_mad_i64_i32 v[24:25], s[4:5], v24, s9, v[140:141]
	v_lshl_add_u64 v[44:45], v[40:41], 0, v[138:139]
	v_cvt_pk_bf16_f32 v12, v12, v13
	v_cvt_pk_bf16_f32 v13, v14, v15
	v_cvt_pk_bf16_f32 v14, v8, v9
	v_add_u32_e32 v8, 0xb0, v144
	global_store_dwordx4 v[108:109], v[92:95], off offset:256
	v_cvt_pk_bf16_f32 v79, v74, v75
	v_mad_i64_i32 v[72:73], s[4:5], v72, s9, v[140:141]
	v_lshl_add_u64 v[92:93], v[88:89], 0, v[138:139]
	global_store_dwordx4 v[44:45], v[28:31], off offset:256
	v_cvt_pk_bf16_f32 v15, v10, v11
	v_mad_i64_i32 v[8:9], s[4:5], v8, s9, v[140:141]
	v_lshl_add_u64 v[28:29], v[24:25], 0, v[138:139]
	v_cvt_pk_bf16_f32 v124, v124, v125
	v_cvt_pk_bf16_f32 v125, v126, v127
	v_cvt_pk_bf16_f32 v126, v120, v121
	v_cvt_pk_bf16_f32 v127, v122, v123
	v_cvt_pk_bf16_f32 v104, v116, v117
	v_cvt_pk_bf16_f32 v105, v118, v119
	v_cvt_pk_bf16_f32 v106, v112, v113
	v_cvt_pk_bf16_f32 v107, v114, v115
	v_cvt_pk_bf16_f32 v88, v100, v101
	v_cvt_pk_bf16_f32 v89, v102, v103
	v_cvt_pk_bf16_f32 v90, v96, v97
	v_cvt_pk_bf16_f32 v91, v98, v99
	global_store_dwordx4 v[92:93], v[76:79], off offset:256
	v_cvt_pk_bf16_f32 v74, v80, v81
	v_cvt_pk_bf16_f32 v75, v82, v83
	v_lshl_add_u64 v[76:77], v[72:73], 0, v[138:139]
	v_cvt_pk_bf16_f32 v72, v84, v85
	v_cvt_pk_bf16_f32 v73, v86, v87
	v_cvt_pk_bf16_f32 v71, v66, v67
	v_cvt_pk_bf16_f32 v60, v60, v61
	v_cvt_pk_bf16_f32 v61, v62, v63
	v_cvt_pk_bf16_f32 v62, v56, v57
	v_cvt_pk_bf16_f32 v63, v58, v59
	v_cvt_pk_bf16_f32 v40, v52, v53
	v_cvt_pk_bf16_f32 v41, v54, v55
	v_cvt_pk_bf16_f32 v42, v48, v49
	v_cvt_pk_bf16_f32 v43, v50, v51
	v_cvt_pk_bf16_f32 v24, v36, v37
	v_cvt_pk_bf16_f32 v25, v38, v39
	v_cvt_pk_bf16_f32 v26, v32, v33
	v_cvt_pk_bf16_f32 v27, v34, v35
	global_store_dwordx4 v[28:29], v[12:15], off offset:256
	v_cvt_pk_bf16_f32 v10, v16, v17
	v_cvt_pk_bf16_f32 v11, v18, v19
	v_lshl_add_u64 v[12:13], v[8:9], 0, v[138:139]
	v_cvt_pk_bf16_f32 v8, v20, v21
	v_cvt_pk_bf16_f32 v9, v22, v23
	v_cvt_pk_bf16_f32 v4, v4, v5
	v_cvt_pk_bf16_f32 v5, v6, v7
	v_cvt_pk_bf16_f32 v6, v0, v1
	v_cvt_pk_bf16_f32 v7, v2, v3
	s_and_b64 vcc, exec, s[6:7]
	s_mov_b32 s31, s8
	s_mov_b32 s33, s10
	s_mov_b64 s[18:19], s[14:15]
	s_mov_b64 s[16:17], s[12:13]
	global_store_dwordx4 v[142:143], v[124:127], off
	global_store_dwordx4 v[108:109], v[104:107], off
	global_store_dwordx4 v[92:93], v[88:91], off
	global_store_dwordx4 v[76:77], v[72:75], off
	global_store_dwordx4 v[76:77], v[68:71], off offset:256
	global_store_dwordx4 v[64:65], v[60:63], off
	global_store_dwordx4 v[44:45], v[40:43], off
	global_store_dwordx4 v[28:29], v[24:27], off
	global_store_dwordx4 v[12:13], v[8:11], off
	global_store_dwordx4 v[12:13], v[4:7], off offset:256
	s_cbranch_vccz .LBB0_228
	s_waitcnt vmcnt(0)
	s_cmpk_gt_u32 s2, 0xff
	s_cbranch_scc1 .LBB0_235
	s_barrier

; #define PG8_STAGE(bufoff, gbase) do { _Pragma("unroll") for (int _i = 0; _i < 2; ++_i) \
;         __builtin_amdgcn_global_load_lds((const unsigned*)((const char*)(gbase) + voff[_i]), (LAS unsigned*)(lds + (bufoff) + ldsw + _i * 8192), 16, 0, 0); } while (0)
; #define PG8_LDA(dst, b, h) do { _Pragma("unroll") for (int m = 0; m < 4; ++m) _Pragma("unroll") for (int k = 0; k < 2; ++k) dst[m][k] = *(const LAS bf16x8*)(lds + PG8_SA(b, h) + aoff + m * 2048 + k * 1024); } while (0)
; #define PG8_LDB(dst, b, h) do { _Pragma("unroll") for (int n = 0; n < 2; ++n) _Pragma("unroll") for (int k = 0; k < 2; ++k) dst[n][k] = *(const LAS bf16x8*)(lds + PG8_SB(b, h) + boff + n * 2048 + k * 1024); } while (0)
; #define PG8_MMA(ai, bj, At, Bt) do { __builtin_amdgcn_s_setprio(1); _Pragma("unroll") for (int m = 0; m < 4; ++m) _Pragma("unroll") for (int n = 0; n < 2; ++n) _Pragma("unroll") for (int k = 0; k < 2; ++k) \
;         acc[ai][bj][m][n] = __builtin_amdgcn_mfma_f32_16x16x32_bf16(Bt[n][k], At[m][k], acc[ai][bj][m][n], 0, 0, 0); __builtin_amdgcn_s_setprio(0); } while (0)
; #define PG8_WAIT_V(n) asm volatile("s_waitcnt vmcnt(" #n ")" ::: "memory")
; #define PG8_WAIT_L(n) asm volatile("s_waitcnt lgkmcnt(" #n ")" ::: "memory")
; #define PG8_BAR __builtin_amdgcn_s_barrier()
; #define PG8_SCHED __builtin_amdgcn_sched_barrier(0)
; template <class Epi>
; DI void gemm_phase(LAS unsigned char* lds, const Gemm g, const StaticOrder& S, const Epi& E) {
;     ...
;         for (int t = 0; t < nt; t += 2) {
;             const bool last = (t == nt - 2);
;             const char* a1 = cA + (size_t)(t + 1) * kstep;
;             const char* a2 = last ? nA : cA + (size_t)(t + 2) * kstep; const char* b2 = last ? nB : cB + (size_t)(t + 2) * kstep;
;             const char* a3 = a2 + kstep; const char* b3 = b2 + kstep;
;             PG8_LDB(B0, 0, 0); PG8_SCHED; PG8_LDA(At, 0, 0); PG8_STAGE(PG8_SA(1, 1), a1 + hstep);
;             PG8_WAIT_L(8); PG8_BAR; PG8_WAIT_L(0); PG8_MMA(0, 0, At, B0); PG8_BAR; PG8_SCHED;
;             PG8_LDB(B1, 0, 1); PG8_STAGE(PG8_SB(0, 0), b2);
;             PG8_BAR; PG8_WAIT_L(0); PG8_MMA(0, 1, At, B1); PG8_BAR;
;             PG8_LDA(At, 0, 1); PG8_STAGE(PG8_SA(0, 0), a2);
;             PG8_BAR; PG8_WAIT_L(0); PG8_MMA(1, 0, At, B0); PG8_BAR; PG8_SCHED;
;             PG8_STAGE(PG8_SB(0, 1), b2 + hstep);
;             PG8_WAIT_V(6); PG8_BAR; PG8_MMA(1, 1, At, B1); PG8_BAR;
.LBB0_320:
	s_add_u32 s26, s24, 0x100
	s_addc_u32 s27, s25, 0
	s_add_i32 s47, 0, 0x10000
	ds_read_b128 v[128:131], v226
	ds_read_b128 v[132:135], v226 offset:1024
	ds_read_b128 v[136:139], v226 offset:2048
	ds_read_b128 v[140:143], v226 offset:3072
	s_cmp_eq_u32 s46, 28
	s_cselect_b32 s31, s4, s27
	s_cselect_b32 s30, s5, s26
	s_cselect_b32 s29, s9, s45
	s_cselect_b32 s28, s11, s33
	v_lshl_add_u64 v[214:215], s[24:25], 0, v[190:191]
	s_add_i32 m0, s38, 0xc000
	ds_read_b128 v[144:147], v228
	ds_read_b128 v[148:151], v228 offset:1024
	ds_read_b128 v[152:155], v228 offset:2048
	ds_read_b128 v[194:197], v228 offset:3072
	ds_read_b128 v[198:201], v228 offset:4096
	ds_read_b128 v[202:205], v228 offset:5120
	ds_read_b128 v[206:209], v228 offset:6144
	ds_read_b128 v[210:213], v228 offset:7168
	global_load_lds_dwordx4 v[214:215], off
	v_lshl_add_u64 v[214:215], s[24:25], 0, v[192:193]
	s_add_i32 m0, s38, 0xe000
	s_nop 0
	global_load_lds_dwordx4 v[214:215], off
	s_waitcnt lgkmcnt(8)
	s_setprio 1
	s_barrier
	s_waitcnt lgkmcnt(0)
	v_mfma_f32_16x16x32_bf16 v[124:127], v[128:131], v[144:147], v[124:127]
	v_mfma_f32_16x16x32_bf16 v[120:123], v[136:139], v[144:147], v[120:123]
	v_mfma_f32_16x16x32_bf16 v[116:119], v[128:131], v[152:155], v[116:119]
	v_mfma_f32_16x16x32_bf16 v[112:115], v[136:139], v[152:155], v[112:115]
	v_mfma_f32_16x16x32_bf16 v[108:111], v[128:131], v[198:201], v[108:111]
	v_mfma_f32_16x16x32_bf16 v[104:107], v[136:139], v[198:201], v[104:107]
	v_mfma_f32_16x16x32_bf16 v[100:103], v[128:131], v[206:209], v[100:103]
	v_mfma_f32_16x16x32_bf16 v[96:99], v[136:139], v[206:209], v[96:99]
	v_mfma_f32_16x16x32_bf16 v[124:127], v[132:135], v[148:151], v[124:127]
	v_mfma_f32_16x16x32_bf16 v[120:123], v[140:143], v[148:151], v[120:123]
	v_mfma_f32_16x16x32_bf16 v[116:119], v[132:135], v[194:197], v[116:119]
	v_mfma_f32_16x16x32_bf16 v[112:115], v[140:143], v[194:197], v[112:115]
	v_mfma_f32_16x16x32_bf16 v[108:111], v[132:135], v[202:205], v[108:111]
	v_mfma_f32_16x16x32_bf16 v[104:107], v[140:143], v[202:205], v[104:107]
	v_mfma_f32_16x16x32_bf16 v[100:103], v[132:135], v[210:213], v[100:103]
	s_setprio 0
	v_mfma_f32_16x16x32_bf16 v[96:99], v[140:143], v[210:213], v[96:99]
	s_barrier
	ds_read_b128 v[214:217], v226 offset:16384
	ds_read_b128 v[230:233], v226 offset:17408
	ds_read_b128 v[234:237], v226 offset:18432
	ds_read_b128 v[238:241], v226 offset:19456
	s_add_i32 s48, 0, 0x14000
	s_add_i32 s24, s47, s37
	s_mov_b32 m0, s24
	s_nop 0
	global_load_lds_dwordx4 v188, s[28:29]
	s_add_i32 m0, s24, 0x2000
	s_nop 0
	global_load_lds_dwordx4 v186, s[28:29]
	s_waitcnt lgkmcnt(0)
	s_setprio 1
	s_barrier
	v_mfma_f32_16x16x32_bf16 v[60:63], v[214:217], v[144:147], v[60:63]
	v_mfma_f32_16x16x32_bf16 v[56:59], v[234:237], v[144:147], v[56:59]
	v_mfma_f32_16x16x32_bf16 v[52:55], v[214:217], v[152:155], v[52:55]
	v_mfma_f32_16x16x32_bf16 v[48:51], v[234:237], v[152:155], v[48:51]
	v_mfma_f32_16x16x32_bf16 v[44:47], v[214:217], v[198:201], v[44:47]
	v_mfma_f32_16x16x32_bf16 v[40:43], v[234:237], v[198:201], v[40:43]
	v_mfma_f32_16x16x32_bf16 v[36:39], v[214:217], v[206:209], v[36:39]
	v_mfma_f32_16x16x32_bf16 v[32:35], v[234:237], v[206:209], v[32:35]
	v_mfma_f32_16x16x32_bf16 v[60:63], v[230:233], v[148:151], v[60:63]
	s_mov_b32 m0, s38
	v_mfma_f32_16x16x32_bf16 v[56:59], v[238:241], v[148:151], v[56:59]
	v_mfma_f32_16x16x32_bf16 v[52:55], v[230:233], v[194:197], v[52:55]
	v_mfma_f32_16x16x32_bf16 v[48:51], v[238:241], v[194:197], v[48:51]
	v_mfma_f32_16x16x32_bf16 v[44:47], v[230:233], v[202:205], v[44:47]
	v_mfma_f32_16x16x32_bf16 v[40:43], v[238:241], v[202:205], v[40:43]
	v_mfma_f32_16x16x32_bf16 v[36:39], v[230:233], v[210:213], v[36:39]
	s_setprio 0
	v_mfma_f32_16x16x32_bf16 v[32:35], v[238:241], v[210:213], v[32:35]
	s_barrier
	ds_read_b128 v[144:147], v228 offset:16384
	ds_read_b128 v[148:151], v228 offset:17408
	ds_read_b128 v[152:155], v228 offset:18432
	ds_read_b128 v[194:197], v228 offset:19456
	ds_read_b128 v[198:201], v228 offset:20480
	ds_read_b128 v[202:205], v228 offset:21504
	ds_read_b128 v[206:209], v228 offset:22528
	ds_read_b128 v[210:213], v228 offset:23552
	global_load_lds_dwordx4 v188, s[30:31]
	s_mov_b64 s[100:101], s[30:31]
	s_mov_b32 m0, s39
	s_nop 0
	global_load_lds_dwordx4 v186, s[30:31]
	s_waitcnt lgkmcnt(0)
	s_setprio 1
	s_barrier
	v_mfma_f32_16x16x32_bf16 v[92:95], v[128:131], v[144:147], v[92:95]
	v_mfma_f32_16x16x32_bf16 v[88:91], v[136:139], v[144:147], v[88:91]
	v_mfma_f32_16x16x32_bf16 v[84:87], v[128:131], v[152:155], v[84:87]
	v_mfma_f32_16x16x32_bf16 v[80:83], v[136:139], v[152:155], v[80:83]
	v_mfma_f32_16x16x32_bf16 v[76:79], v[128:131], v[198:201], v[76:79]
	v_mfma_f32_16x16x32_bf16 v[72:75], v[136:139], v[198:201], v[72:75]
	v_mfma_f32_16x16x32_bf16 v[68:71], v[128:131], v[206:209], v[68:71]
	v_mfma_f32_16x16x32_bf16 v[64:67], v[136:139], v[206:209], v[64:67]
	v_mfma_f32_16x16x32_bf16 v[92:95], v[132:135], v[148:151], v[92:95]
	v_mfma_f32_16x16x32_bf16 v[88:91], v[140:143], v[148:151], v[88:91]
	v_mfma_f32_16x16x32_bf16 v[84:87], v[132:135], v[194:197], v[84:87]
	v_mfma_f32_16x16x32_bf16 v[80:83], v[140:143], v[194:197], v[80:83]
	v_mfma_f32_16x16x32_bf16 v[76:79], v[132:135], v[202:205], v[76:79]
	v_mfma_f32_16x16x32_bf16 v[72:75], v[140:143], v[202:205], v[72:75]
	v_mfma_f32_16x16x32_bf16 v[68:71], v[132:135], v[210:213], v[68:71]
	s_setprio 0
	v_mfma_f32_16x16x32_bf16 v[64:67], v[140:143], v[210:213], v[64:67]
	s_barrier
	s_add_u32 s24, s28, 0x80000
	s_addc_u32 s25, s29, 0
	s_add_i32 s47, s48, s37
	s_mov_b32 m0, s47
	s_nop 0
	global_load_lds_dwordx4 v188, s[24:25]
	s_add_i32 m0, s47, 0x2000
	s_nop 0
	global_load_lds_dwordx4 v186, s[24:25]
	s_waitcnt vmcnt(6)
	s_setprio 1
	s_barrier
; #define PG8_STAGE(bufoff, gbase) do { _Pragma("unroll") for (int _i = 0; _i < 2; ++_i) \
;         __builtin_amdgcn_global_load_lds((const unsigned*)((const char*)(gbase) + voff[_i]), (LAS unsigned*)(lds + (bufoff) + ldsw + _i * 8192), 16, 0, 0); } while (0)
; #define PG8_LDA(dst, b, h) do { _Pragma("unroll") for (int m = 0; m < 4; ++m) _Pragma("unroll") for (int k = 0; k < 2; ++k) dst[m][k] = *(const LAS bf16x8*)(lds + PG8_SA(b, h) + aoff + m * 2048 + k * 1024); } while (0)
; #define PG8_LDB(dst, b, h) do { _Pragma("unroll") for (int n = 0; n < 2; ++n) _Pragma("unroll") for (int k = 0; k < 2; ++k) dst[n][k] = *(const LAS bf16x8*)(lds + PG8_SB(b, h) + boff + n * 2048 + k * 1024); } while (0)
; #define PG8_MMA(ai, bj, At, Bt) do { __builtin_amdgcn_s_setprio(1); _Pragma("unroll") for (int m = 0; m < 4; ++m) _Pragma("unroll") for (int n = 0; n < 2; ++n) _Pragma("unroll") for (int k = 0; k < 2; ++k) \
;         acc[ai][bj][m][n] = __builtin_amdgcn_mfma_f32_16x16x32_bf16(Bt[n][k], At[m][k], acc[ai][bj][m][n], 0, 0, 0); __builtin_amdgcn_s_setprio(0); } while (0)
; #define PG8_WAIT_L(n) asm volatile("s_waitcnt lgkmcnt(" #n ")" ::: "memory")
; #define PG8_BAR __builtin_amdgcn_s_barrier()
; #define PG8_SCHED __builtin_amdgcn_sched_barrier(0)
; template <class Epi>
; DI void gemm_phase(LAS unsigned char* lds, const Gemm g, const StaticOrder& S, const Epi& E) {
;     ...
;             PG8_LDB(B0, 1, 0); PG8_SCHED; PG8_LDA(At, 1, 0); PG8_STAGE(PG8_SA(0, 1), a2 + hstep);
;             PG8_WAIT_L(8); PG8_BAR; PG8_WAIT_L(0); PG8_MMA(0, 0, At, B0); PG8_BAR; PG8_SCHED;
;             PG8_LDB(B1, 1, 1); PG8_STAGE(PG8_SB(1, 0), b3);
;             PG8_BAR; PG8_WAIT_L(0); PG8_MMA(0, 1, At, B1); PG8_BAR;
;             PG8_LDA(At, 1, 1); PG8_STAGE(PG8_SA(1, 0), a3);
;             PG8_BAR; PG8_WAIT_L(0); PG8_MMA(1, 0, At, B0); PG8_BAR; PG8_SCHED;
	v_mfma_f32_16x16x32_bf16 v[28:31], v[214:217], v[144:147], v[28:31]
	v_mfma_f32_16x16x32_bf16 v[24:27], v[234:237], v[144:147], v[24:27]
	v_mfma_f32_16x16x32_bf16 v[20:23], v[214:217], v[152:155], v[20:23]
	v_mfma_f32_16x16x32_bf16 v[16:19], v[234:237], v[152:155], v[16:19]
	v_mfma_f32_16x16x32_bf16 v[12:15], v[214:217], v[198:201], v[12:15]
	v_mfma_f32_16x16x32_bf16 v[8:11], v[234:237], v[198:201], v[8:11]
	v_mfma_f32_16x16x32_bf16 v[4:7], v[214:217], v[206:209], v[4:7]
	v_mfma_f32_16x16x32_bf16 v[0:3], v[234:237], v[206:209], v[0:3]
	v_mfma_f32_16x16x32_bf16 v[28:31], v[230:233], v[148:151], v[28:31]
	s_add_i32 s47, 0, 0x18000
	v_mfma_f32_16x16x32_bf16 v[24:27], v[238:241], v[148:151], v[24:27]
	v_mfma_f32_16x16x32_bf16 v[20:23], v[230:233], v[194:197], v[20:23]
	v_mfma_f32_16x16x32_bf16 v[16:19], v[238:241], v[194:197], v[16:19]
	v_mfma_f32_16x16x32_bf16 v[12:15], v[230:233], v[202:205], v[12:15]
	v_mfma_f32_16x16x32_bf16 v[8:11], v[238:241], v[202:205], v[8:11]
	v_mfma_f32_16x16x32_bf16 v[4:7], v[230:233], v[210:213], v[4:7]
	s_setprio 0
	v_mfma_f32_16x16x32_bf16 v[0:3], v[238:241], v[210:213], v[0:3]
	s_barrier
	ds_read_b128 v[128:131], v226 offset:32768
	ds_read_b128 v[132:135], v226 offset:33792
	ds_read_b128 v[136:139], v226 offset:34816
	ds_read_b128 v[140:143], v226 offset:35840
	ds_read_b128 v[144:147], v228 offset:32768
	ds_read_b128 v[148:151], v228 offset:33792
	ds_read_b128 v[152:155], v228 offset:34816
	ds_read_b128 v[194:197], v228 offset:35840
	ds_read_b128 v[198:201], v228 offset:36864
	ds_read_b128 v[202:205], v228 offset:37888
	ds_read_b128 v[206:209], v228 offset:38912
	ds_read_b128 v[210:213], v228 offset:39936
	s_add_u32 s24, s30, 0x80000
	s_addc_u32 s25, s31, 0
	s_mov_b32 m0, s40
	s_nop 0
	global_load_lds_dwordx4 v188, s[24:25]
	s_mov_b32 m0, s41
	s_nop 0
	global_load_lds_dwordx4 v186, s[24:25]
	s_waitcnt lgkmcnt(8)
	s_setprio 1
	s_barrier
	s_waitcnt lgkmcnt(0)
	v_mfma_f32_16x16x32_bf16 v[124:127], v[128:131], v[144:147], v[124:127]
	v_mfma_f32_16x16x32_bf16 v[120:123], v[136:139], v[144:147], v[120:123]
	v_mfma_f32_16x16x32_bf16 v[116:119], v[128:131], v[152:155], v[116:119]
	v_mfma_f32_16x16x32_bf16 v[112:115], v[136:139], v[152:155], v[112:115]
	v_mfma_f32_16x16x32_bf16 v[108:111], v[128:131], v[198:201], v[108:111]
	v_mfma_f32_16x16x32_bf16 v[104:107], v[136:139], v[198:201], v[104:107]
	v_mfma_f32_16x16x32_bf16 v[100:103], v[128:131], v[206:209], v[100:103]
	v_mfma_f32_16x16x32_bf16 v[96:99], v[136:139], v[206:209], v[96:99]
	v_mfma_f32_16x16x32_bf16 v[124:127], v[132:135], v[148:151], v[124:127]
	v_mfma_f32_16x16x32_bf16 v[120:123], v[140:143], v[148:151], v[120:123]
	v_mfma_f32_16x16x32_bf16 v[116:119], v[132:135], v[194:197], v[116:119]
	v_mfma_f32_16x16x32_bf16 v[112:115], v[140:143], v[194:197], v[112:115]
	v_mfma_f32_16x16x32_bf16 v[108:111], v[132:135], v[202:205], v[108:111]
	v_mfma_f32_16x16x32_bf16 v[104:107], v[140:143], v[202:205], v[104:107]
	v_mfma_f32_16x16x32_bf16 v[100:103], v[132:135], v[210:213], v[100:103]
	s_setprio 0
	v_mfma_f32_16x16x32_bf16 v[96:99], v[140:143], v[210:213], v[96:99]
	s_barrier
	ds_read_b128 v[214:217], v226 offset:49152
	ds_read_b128 v[230:233], v226 offset:50176
	ds_read_b128 v[234:237], v226 offset:51200
	ds_read_b128 v[238:241], v226 offset:52224
	s_add_i32 s30, 0, 0x1c000
	s_add_i32 s24, s47, s37
	s_add_i32 m0, s24, 0xffffff80
	s_nop 0
	global_load_lds_dwordx4 v188, s[28:29] offset:128
	s_add_i32 m0, s24, 0x1f80
	s_nop 0
	global_load_lds_dwordx4 v186, s[28:29] offset:128
	s_waitcnt lgkmcnt(0)
	s_setprio 1
	s_barrier
	v_mfma_f32_16x16x32_bf16 v[60:63], v[214:217], v[144:147], v[60:63]
	v_mfma_f32_16x16x32_bf16 v[56:59], v[234:237], v[144:147], v[56:59]
	v_mfma_f32_16x16x32_bf16 v[52:55], v[214:217], v[152:155], v[52:55]
	v_mfma_f32_16x16x32_bf16 v[48:51], v[234:237], v[152:155], v[48:51]
	v_mfma_f32_16x16x32_bf16 v[44:47], v[214:217], v[198:201], v[44:47]
	v_mfma_f32_16x16x32_bf16 v[40:43], v[234:237], v[198:201], v[40:43]
	v_mfma_f32_16x16x32_bf16 v[36:39], v[214:217], v[206:209], v[36:39]
	v_mfma_f32_16x16x32_bf16 v[32:35], v[234:237], v[206:209], v[32:35]
	v_mfma_f32_16x16x32_bf16 v[60:63], v[230:233], v[148:151], v[60:63]
	s_add_i32 m0, s42, 0xffffff80
	v_mfma_f32_16x16x32_bf16 v[56:59], v[238:241], v[148:151], v[56:59]
	v_mfma_f32_16x16x32_bf16 v[52:55], v[230:233], v[194:197], v[52:55]
	v_mfma_f32_16x16x32_bf16 v[48:51], v[238:241], v[194:197], v[48:51]
	v_mfma_f32_16x16x32_bf16 v[44:47], v[230:233], v[202:205], v[44:47]
	v_mfma_f32_16x16x32_bf16 v[40:43], v[238:241], v[202:205], v[40:43]
	v_mfma_f32_16x16x32_bf16 v[36:39], v[230:233], v[210:213], v[36:39]
	s_setprio 0
	v_mfma_f32_16x16x32_bf16 v[32:35], v[238:241], v[210:213], v[32:35]
	s_barrier
	ds_read_b128 v[144:147], v228 offset:49152
	ds_read_b128 v[148:151], v228 offset:50176
	ds_read_b128 v[152:155], v228 offset:51200
	ds_read_b128 v[194:197], v228 offset:52224
	ds_read_b128 v[198:201], v228 offset:53248
	ds_read_b128 v[202:205], v228 offset:54272
	ds_read_b128 v[206:209], v228 offset:55296
	ds_read_b128 v[210:213], v228 offset:56320
	global_load_lds_dwordx4 v188, s[100:101] offset:128
	s_add_i32 m0, s43, 0xffffff80
	s_nop 0
	global_load_lds_dwordx4 v186, s[100:101] offset:128
	s_waitcnt lgkmcnt(0)
	s_setprio 1
	s_barrier
; #define PG8_STAGE(bufoff, gbase) do { _Pragma("unroll") for (int _i = 0; _i < 2; ++_i) \
;         __builtin_amdgcn_global_load_lds((const unsigned*)((const char*)(gbase) + voff[_i]), (LAS unsigned*)(lds + (bufoff) + ldsw + _i * 8192), 16, 0, 0); } while (0)
; #define PG8_MMA(ai, bj, At, Bt) do { __builtin_amdgcn_s_setprio(1); _Pragma("unroll") for (int m = 0; m < 4; ++m) _Pragma("unroll") for (int n = 0; n < 2; ++n) _Pragma("unroll") for (int k = 0; k < 2; ++k) \
;         acc[ai][bj][m][n] = __builtin_amdgcn_mfma_f32_16x16x32_bf16(Bt[n][k], At[m][k], acc[ai][bj][m][n], 0, 0, 0); __builtin_amdgcn_s_setprio(0); } while (0)
; #define PG8_WAIT_V(n) asm volatile("s_waitcnt vmcnt(" #n ")" ::: "memory")
; #define PG8_WAIT_L(n) asm volatile("s_waitcnt lgkmcnt(" #n ")" ::: "memory")
; #define PG8_BAR __builtin_amdgcn_s_barrier()
; #define PG8_SCHED __builtin_amdgcn_sched_barrier(0)
; template <class Epi>
; DI void gemm_phase(LAS unsigned char* lds, const Gemm g, const StaticOrder& S, const Epi& E) {
;     ...
;             PG8_BAR; PG8_WAIT_L(0); PG8_MMA(1, 0, At, B0); PG8_BAR; PG8_SCHED;
;             PG8_STAGE(PG8_SB(1, 1), b3 + hstep);
;             PG8_WAIT_V(6); PG8_BAR; PG8_MMA(1, 1, At, B1); PG8_BAR;
;         }
;         E(acc, cur, wr, wc, fr, fq);
;         if (!has_next) break;
;     template <bool LN> DI void run(const f32x4 (&acc)[2][2][4][2], const Unit& u, int wr, int wc, int fr, int fq) const {
;         const unsigned row0 = u.pm * BM + wr * 64 + fr, col0 = u.pn * BM + wc * 32 + 4 * fq;
;         f32x4 gv[2], bv[2];
;         load_gb<LN, 0>(col0, gv, bv);
;         batch<LN, 0, 0, 4>(acc, row0, col0, gv, bv);
	v_mfma_f32_16x16x32_bf16 v[92:95], v[128:131], v[144:147], v[92:95]
	v_mfma_f32_16x16x32_bf16 v[88:91], v[136:139], v[144:147], v[88:91]
	v_mfma_f32_16x16x32_bf16 v[84:87], v[128:131], v[152:155], v[84:87]
	v_mfma_f32_16x16x32_bf16 v[80:83], v[136:139], v[152:155], v[80:83]
	v_mfma_f32_16x16x32_bf16 v[76:79], v[128:131], v[198:201], v[76:79]
	v_mfma_f32_16x16x32_bf16 v[72:75], v[136:139], v[198:201], v[72:75]
	v_mfma_f32_16x16x32_bf16 v[68:71], v[128:131], v[206:209], v[68:71]
	v_mfma_f32_16x16x32_bf16 v[64:67], v[136:139], v[206:209], v[64:67]
	v_mfma_f32_16x16x32_bf16 v[92:95], v[132:135], v[148:151], v[92:95]
	v_mfma_f32_16x16x32_bf16 v[88:91], v[140:143], v[148:151], v[88:91]
	v_mfma_f32_16x16x32_bf16 v[84:87], v[132:135], v[194:197], v[84:87]
	v_mfma_f32_16x16x32_bf16 v[80:83], v[140:143], v[194:197], v[80:83]
	v_mfma_f32_16x16x32_bf16 v[76:79], v[132:135], v[202:205], v[76:79]
	v_mfma_f32_16x16x32_bf16 v[72:75], v[140:143], v[202:205], v[72:75]
	v_mfma_f32_16x16x32_bf16 v[68:71], v[132:135], v[210:213], v[68:71]
	s_setprio 0
	v_mfma_f32_16x16x32_bf16 v[64:67], v[140:143], v[210:213], v[64:67]
	s_barrier
	s_add_u32 s24, s28, 0x80080
	s_addc_u32 s25, s29, 0
	s_add_i32 s28, s30, s37
	s_mov_b32 m0, s28
	s_nop 0
	global_load_lds_dwordx4 v188, s[24:25]
	s_add_i32 m0, s28, 0x2000
	s_nop 0
	global_load_lds_dwordx4 v186, s[24:25]
	s_waitcnt vmcnt(6)
	s_setprio 1
	s_barrier
	v_mfma_f32_16x16x32_bf16 v[28:31], v[214:217], v[144:147], v[28:31]
	v_mfma_f32_16x16x32_bf16 v[24:27], v[234:237], v[144:147], v[24:27]
	v_mfma_f32_16x16x32_bf16 v[20:23], v[214:217], v[152:155], v[20:23]
	v_mfma_f32_16x16x32_bf16 v[16:19], v[234:237], v[152:155], v[16:19]
	v_mfma_f32_16x16x32_bf16 v[12:15], v[214:217], v[198:201], v[12:15]
	v_mfma_f32_16x16x32_bf16 v[8:11], v[234:237], v[198:201], v[8:11]
	v_mfma_f32_16x16x32_bf16 v[4:7], v[214:217], v[206:209], v[4:7]
	v_mfma_f32_16x16x32_bf16 v[0:3], v[234:237], v[206:209], v[0:3]
	v_mfma_f32_16x16x32_bf16 v[28:31], v[230:233], v[148:151], v[28:31]
	s_add_i32 s46, s46, 2
	v_mfma_f32_16x16x32_bf16 v[24:27], v[238:241], v[148:151], v[24:27]
	s_add_u32 s33, s33, 0x100
	v_mfma_f32_16x16x32_bf16 v[20:23], v[230:233], v[194:197], v[20:23]
	s_addc_u32 s45, s45, 0
	v_mfma_f32_16x16x32_bf16 v[16:19], v[238:241], v[194:197], v[16:19]
	s_cmp_gt_u32 s46, 29
	v_mfma_f32_16x16x32_bf16 v[12:15], v[230:233], v[202:205], v[12:15]
	s_mov_b64 s[24:25], s[26:27]
	v_mfma_f32_16x16x32_bf16 v[8:11], v[238:241], v[202:205], v[8:11]
	v_mfma_f32_16x16x32_bf16 v[4:7], v[230:233], v[210:213], v[4:7]
	s_setprio 0
	v_mfma_f32_16x16x32_bf16 v[0:3], v[238:241], v[210:213], v[0:3]
	s_barrier
	s_cbranch_scc0 .LBB0_320
	v_lshl_add_u32 v206, s3, 8, v225
	v_lshl_or_b32 v158, s2, 8, v227
	v_lshlrev_b32_e32 v232, 11, v206
	s_andn2_b64 vcc, exec, s[14:15]
	v_or_b32_e32 v231, 16, v158
	v_add_u32_e32 v194, v232, v158
	v_or_b32_e32 v230, 0x80, v158
	v_or_b32_e32 v229, 0x90, v158
	s_cbranch_vccnz .LBB0_323
	v_lshlrev_b64 v[132:133], 2, v[158:159]
	v_lshl_add_u64 v[140:141], s[16:17], 0, v[132:133]
	global_load_dwordx4 v[128:131], v[140:141], off
	v_lshl_add_u64 v[142:143], s[18:19], 0, v[132:133]
	v_readlane_b32 s2, v253, 8
	v_mov_b32_e32 v195, v159
	v_lshlrev_b32_e32 v136, 1, v206
	v_mov_b32_e32 v137, v159
	v_readlane_b32 s3, v253, 9
	v_lshlrev_b64 v[212:213], 2, v[194:195]
	v_add_u32_e32 v146, v232, v231
	v_lshl_add_u64 v[144:145], v[136:137], 2, s[2:3]
	v_lshl_add_u64 v[136:137], s[88:89], 0, v[212:213]
	v_mov_b32_e32 v147, v159
	v_lshl_add_u64 v[146:147], v[146:147], 2, s[88:89]
	v_or_b32_e32 v195, 16, v206
	v_mov_b32_e32 v201, v159
	v_mov_b32_e32 v209, v159
	v_lshl_add_u64 v[212:213], s[90:91], 0, v[212:213]
	s_waitcnt vmcnt(0)
	v_pk_mul_f32 v[152:153], v[130:131], s[78:79] op_sel_hi:[1,0]
	v_pk_mul_f32 v[154:155], v[128:129], s[78:79] op_sel_hi:[1,0]
	global_load_dwordx4 v[132:135], v[142:143], off
	global_load_dwordx4 v[128:131], v[140:141], off offset:64
	global_load_dwordx2 v[204:205], v[144:145], off
	global_load_dwordx4 v[196:199], v[146:147], off
	v_lshlrev_b32_e32 v146, 1, v195
	global_load_dwordx4 v[136:139], v[136:137], off
	v_lshlrev_b32_e32 v195, 11, v195
	v_mov_b32_e32 v147, v159
	v_add_u32_e32 v200, v195, v158
	v_lshl_add_u64 v[146:147], v[146:147], 2, s[2:3]
	v_lshl_add_u64 v[200:201], v[200:201], 2, s[88:89]
	global_load_dwordx2 v[214:215], v[146:147], off
	v_add_u32_e32 v208, v195, v231
	global_load_dwordx4 v[200:203], v[200:201], off
	v_lshl_add_u64 v[208:209], v[208:209], 2, s[88:89]
	global_load_dwordx4 v[208:211], v[208:209], off
	s_waitcnt vmcnt(0)
	v_pk_mul_f32 v[148:149], v[130:131], s[78:79] op_sel_hi:[1,0]
	v_pk_mul_f32 v[150:151], v[128:129], s[78:79] op_sel_hi:[1,0]
	global_load_dwordx4 v[128:131], v[142:143], off offset:64
	v_sub_f32_e32 v137, v137, v204
	v_sub_f32_e32 v136, v136, v204
	v_sub_f32_e32 v139, v139, v204
	v_sub_f32_e32 v138, v138, v204
	v_pk_mul_f32 v[138:139], v[204:205], v[138:139] op_sel:[1,0]
	v_pk_mul_f32 v[136:137], v[204:205], v[136:137] op_sel:[1,0]
	v_pk_fma_f32 v[138:139], v[152:153], v[138:139], v[126:127]
	v_pk_fma_f32 v[136:137], v[154:155], v[136:137], v[124:125]
	v_pk_fma_f32 v[138:139], v[134:135], s[78:79], v[138:139] op_sel_hi:[1,0,1]
	v_pk_fma_f32 v[136:137], v[132:133], s[78:79], v[136:137] op_sel_hi:[1,0,1]
	global_store_dwordx4 v[212:213], v[136:139], off
	s_nop 1
	v_sub_f32_e32 v137, v197, v204
	v_sub_f32_e32 v136, v196, v204
	v_sub_f32_e32 v139, v199, v204
	v_sub_f32_e32 v138, v198, v204
	v_pk_mul_f32 v[138:139], v[204:205], v[138:139] op_sel:[1,0]
	v_pk_mul_f32 v[136:137], v[204:205], v[136:137] op_sel:[1,0]
	v_pk_fma_f32 v[138:139], v[148:149], v[138:139], v[122:123]
	v_pk_fma_f32 v[136:137], v[150:151], v[136:137], v[120:121]
	v_or_b32_e32 v196, 16, v194
	v_mov_b32_e32 v197, v159
	v_lshl_add_u64 v[196:197], v[196:197], 2, s[90:91]
	s_waitcnt vmcnt(0)
;     template <bool LN, int BJ, int LO, int HI> DI void batch(const f32x4 (&acc)[2][2][4][2], unsigned row0, unsigned col0, const f32x4 (&gv)[2], const f32x4 (&bv)[2]) const {
;         f32x4 r[HI - LO]; float mean[(HI - LO) / 2], rstd[(HI - LO) / 2];
; #pragma unroll
;         for (int i = LO; i < HI; ++i) { const int ai = i >> 3, m = (i >> 1) & 3, n = i & 1; const unsigned row = row0 + ai * HALF + m * 16;
;             if (n == 0) { mean[(i - LO) >> 1] = 0.f; rstd[(i - LO) >> 1] = 1.f;
;                 if (LN) { const float2 st = *(const float2*)(stats + row * 2u); mean[(i - LO) >> 1] = st.x; rstd[(i - LO) >> 1] = st.y; } }
;             r[i - LO] = *(const f32x4*)(src + (row * (unsigned)DM + col0 + BJ * HALF + n * 16)); }
; #pragma unroll
;         for (int i = LO; i < HI; ++i) { const int ai = i >> 3, m = (i >> 1) & 3, n = i & 1; const unsigned row = row0 + ai * HALF + m * 16;
;             *(f32x4*)(Y + (row * (unsigned)DM + col0 + BJ * HALF + n * 16)) = acc[ai][BJ][m][n] + ((r[i - LO] - mean[(i - LO) >> 1]) * rstd[(i - LO) >> 1]) * gv[n] + bv[n]; }
	v_pk_fma_f32 v[138:139], v[130:131], s[78:79], v[138:139] op_sel_hi:[1,0,1]
	v_pk_fma_f32 v[136:137], v[128:129], s[78:79], v[136:137] op_sel_hi:[1,0,1]
	global_store_dwordx4 v[196:197], v[136:139], off
	v_add_u32_e32 v196, 0x8000, v194
	v_mov_b32_e32 v197, v159
	v_sub_f32_e32 v137, v201, v214
	v_sub_f32_e32 v136, v200, v214
	v_sub_f32_e32 v139, v203, v214
	v_sub_f32_e32 v138, v202, v214
	v_pk_mul_f32 v[138:139], v[214:215], v[138:139] op_sel:[1,0]
	v_pk_mul_f32 v[136:137], v[214:215], v[136:137] op_sel:[1,0]
	v_pk_fma_f32 v[138:139], v[152:153], v[138:139], v[118:119]
	v_pk_fma_f32 v[136:137], v[154:155], v[136:137], v[116:117]
	v_pk_fma_f32 v[138:139], v[134:135], s[78:79], v[138:139] op_sel_hi:[1,0,1]
	v_pk_fma_f32 v[136:137], v[132:133], s[78:79], v[136:137] op_sel_hi:[1,0,1]
	v_lshl_add_u64 v[196:197], v[196:197], 2, s[90:91]
	global_store_dwordx4 v[196:197], v[136:139], off
	v_add_u32_e32 v196, 0x8010, v194
	v_mov_b32_e32 v197, v159
	v_sub_f32_e32 v137, v209, v214
	v_sub_f32_e32 v136, v208, v214
	v_sub_f32_e32 v139, v211, v214
	v_sub_f32_e32 v138, v210, v214
	v_pk_mul_f32 v[138:139], v[214:215], v[138:139] op_sel:[1,0]
	v_pk_mul_f32 v[136:137], v[214:215], v[136:137] op_sel:[1,0]
	v_pk_fma_f32 v[138:139], v[148:149], v[138:139], v[114:115]
	v_pk_fma_f32 v[136:137], v[150:151], v[136:137], v[112:113]
	v_pk_fma_f32 v[138:139], v[130:131], s[78:79], v[138:139] op_sel_hi:[1,0,1]
	v_pk_fma_f32 v[136:137], v[128:129], s[78:79], v[136:137] op_sel_hi:[1,0,1]
	v_lshl_add_u64 v[196:197], v[196:197], 2, s[90:91]
	global_store_dwordx4 v[196:197], v[136:139], off
	s_nop 1
	v_or_b32_e32 v138, 32, v206
	v_lshlrev_b32_e32 v136, 1, v138
	v_mov_b32_e32 v137, v159
	v_lshlrev_b32_e32 v236, 11, v138
	v_lshl_add_u64 v[200:201], v[136:137], 2, s[2:3]
	v_add_u32_e32 v136, v236, v158
	v_lshl_add_u64 v[136:137], v[136:137], 2, s[88:89]
	global_load_dwordx2 v[204:205], v[200:201], off
	v_add_u32_e32 v196, v236, v231
	global_load_dwordx4 v[136:139], v[136:137], off
	v_mov_b32_e32 v197, v159
	v_lshl_add_u64 v[196:197], v[196:197], 2, s[88:89]
	global_load_dwordx4 v[196:199], v[196:197], off
	v_or_b32_e32 v207, 48, v206
	v_lshlrev_b32_e32 v235, 11, v207
	v_lshlrev_b32_e32 v202, 1, v207
	v_mov_b32_e32 v203, v159
	v_add_u32_e32 v208, v235, v158
	v_mov_b32_e32 v209, v159
	v_lshl_add_u64 v[202:203], v[202:203], 2, s[2:3]
	v_lshl_add_u64 v[208:209], v[208:209], 2, s[88:89]
	global_load_dwordx2 v[216:217], v[202:203], off
	v_add_u32_e32 v212, v235, v231
	global_load_dwordx4 v[208:211], v[208:209], off
	v_mov_b32_e32 v213, v159
	v_lshl_add_u64 v[212:213], v[212:213], 2, s[88:89]
	global_load_dwordx4 v[212:215], v[212:213], off
	v_add_u32_e32 v218, 0x10000, v194
	v_mov_b32_e32 v219, v159
	v_lshl_add_u64 v[218:219], v[218:219], 2, s[90:91]
	s_waitcnt vmcnt(0)
	v_sub_f32_e32 v137, v137, v204
	v_sub_f32_e32 v136, v136, v204
	v_sub_f32_e32 v139, v139, v204
	v_sub_f32_e32 v138, v138, v204
	v_pk_mul_f32 v[138:139], v[204:205], v[138:139] op_sel:[1,0]
	v_pk_mul_f32 v[136:137], v[204:205], v[136:137] op_sel:[1,0]
	v_pk_fma_f32 v[138:139], v[152:153], v[138:139], v[110:111]
	v_pk_fma_f32 v[136:137], v[154:155], v[136:137], v[108:109]
	v_pk_fma_f32 v[138:139], v[134:135], s[78:79], v[138:139] op_sel_hi:[1,0,1]
	v_pk_fma_f32 v[136:137], v[132:133], s[78:79], v[136:137] op_sel_hi:[1,0,1]
	global_store_dwordx4 v[218:219], v[136:139], off
	s_nop 1
	v_sub_f32_e32 v137, v197, v204
	v_sub_f32_e32 v136, v196, v204
	v_sub_f32_e32 v139, v199, v204
	v_sub_f32_e32 v138, v198, v204
	v_pk_mul_f32 v[138:139], v[204:205], v[138:139] op_sel:[1,0]
	v_pk_mul_f32 v[136:137], v[204:205], v[136:137] op_sel:[1,0]
	v_pk_fma_f32 v[138:139], v[148:149], v[138:139], v[106:107]
	v_pk_fma_f32 v[136:137], v[150:151], v[136:137], v[104:105]
	v_add_u32_e32 v196, 0x10010, v194
	v_mov_b32_e32 v197, v159
	v_pk_fma_f32 v[138:139], v[130:131], s[78:79], v[138:139] op_sel_hi:[1,0,1]
	v_pk_fma_f32 v[136:137], v[128:129], s[78:79], v[136:137] op_sel_hi:[1,0,1]
	v_lshl_add_u64 v[196:197], v[196:197], 2, s[90:91]
	global_store_dwordx4 v[196:197], v[136:139], off
	v_add_u32_e32 v196, 0x18000, v194
	v_mov_b32_e32 v197, v159
	v_sub_f32_e32 v137, v209, v216
	v_sub_f32_e32 v136, v208, v216
	v_sub_f32_e32 v139, v211, v216
	v_sub_f32_e32 v138, v210, v216
	v_pk_mul_f32 v[138:139], v[216:217], v[138:139] op_sel:[1,0]
	v_pk_mul_f32 v[136:137], v[216:217], v[136:137] op_sel:[1,0]
	v_pk_fma_f32 v[138:139], v[152:153], v[138:139], v[102:103]
	v_pk_fma_f32 v[136:137], v[154:155], v[136:137], v[100:101]
	v_pk_fma_f32 v[138:139], v[134:135], s[78:79], v[138:139] op_sel_hi:[1,0,1]
	v_pk_fma_f32 v[136:137], v[132:133], s[78:79], v[136:137] op_sel_hi:[1,0,1]
	v_lshl_add_u64 v[196:197], v[196:197], 2, s[90:91]
	global_store_dwordx4 v[196:197], v[136:139], off
	v_add_u32_e32 v196, 0x18010, v194
	v_mov_b32_e32 v197, v159
	v_sub_f32_e32 v137, v213, v216
	v_sub_f32_e32 v136, v212, v216
	v_sub_f32_e32 v139, v215, v216
	v_sub_f32_e32 v138, v214, v216
	v_pk_mul_f32 v[138:139], v[216:217], v[138:139] op_sel:[1,0]
	v_pk_mul_f32 v[136:137], v[216:217], v[136:137] op_sel:[1,0]
	v_pk_fma_f32 v[138:139], v[148:149], v[138:139], v[98:99]
	v_pk_fma_f32 v[136:137], v[150:151], v[136:137], v[96:97]
	v_pk_fma_f32 v[138:139], v[130:131], s[78:79], v[138:139] op_sel_hi:[1,0,1]
	v_pk_fma_f32 v[136:137], v[128:129], s[78:79], v[136:137] op_sel_hi:[1,0,1]
	v_lshl_add_u64 v[196:197], v[196:197], 2, s[90:91]
	global_store_dwordx4 v[196:197], v[136:139], off
	s_nop 1
	v_add_u32_e32 v138, 0x80, v206
	v_lshlrev_b32_e32 v136, 1, v138
	v_mov_b32_e32 v137, v159
	v_lshlrev_b32_e32 v233, 11, v138
	v_lshl_add_u64 v[196:197], v[136:137], 2, s[2:3]
	v_add_u32_e32 v136, v233, v158
	v_lshl_add_u64 v[136:137], v[136:137], 2, s[88:89]
	global_load_dwordx2 v[204:205], v[196:197], off
	v_add_u32_e32 v198, v233, v231
	global_load_dwordx4 v[136:139], v[136:137], off
	v_mov_b32_e32 v199, v159
	v_add_u32_e32 v207, 0x90, v206
	v_lshl_add_u64 v[198:199], v[198:199], 2, s[88:89]
	v_lshlrev_b32_e32 v234, 11, v207
	global_load_dwordx4 v[208:211], v[198:199], off
	v_add_u32_e32 v212, v234, v158
	v_mov_b32_e32 v213, v159
	v_lshl_add_u64 v[212:213], v[212:213], 2, s[88:89]
	global_load_dwordx4 v[212:215], v[212:213], off
	v_lshlrev_b32_e32 v198, 1, v207
	v_mov_b32_e32 v199, v159
	v_lshl_add_u64 v[198:199], v[198:199], 2, s[2:3]
	global_load_dwordx2 v[238:239], v[198:199], off
	v_add_u32_e32 v216, v234, v231
	v_mov_b32_e32 v217, v159
	v_lshl_add_u64 v[216:217], v[216:217], 2, s[88:89]
	global_load_dwordx4 v[216:219], v[216:217], off
	v_add_u32_e32 v240, 0x40000, v194
	v_mov_b32_e32 v241, v159
	v_lshl_add_u64 v[240:241], v[240:241], 2, s[90:91]
	s_waitcnt vmcnt(0)
;     template <bool LN, int BJ, int LO, int HI> DI void batch(const f32x4 (&acc)[2][2][4][2], unsigned row0, unsigned col0, const f32x4 (&gv)[2], const f32x4 (&bv)[2]) const {
;         f32x4 r[HI - LO]; float mean[(HI - LO) / 2], rstd[(HI - LO) / 2];
; #pragma unroll
;         for (int i = LO; i < HI; ++i) { const int ai = i >> 3, m = (i >> 1) & 3, n = i & 1; const unsigned row = row0 + ai * HALF + m * 16;
;             if (n == 0) { mean[(i - LO) >> 1] = 0.f; rstd[(i - LO) >> 1] = 1.f;
;                 if (LN) { const float2 st = *(const float2*)(stats + row * 2u); mean[(i - LO) >> 1] = st.x; rstd[(i - LO) >> 1] = st.y; } }
;             r[i - LO] = *(const f32x4*)(src + (row * (unsigned)DM + col0 + BJ * HALF + n * 16)); }
; #pragma unroll
;         for (int i = LO; i < HI; ++i) { const int ai = i >> 3, m = (i >> 1) & 3, n = i & 1; const unsigned row = row0 + ai * HALF + m * 16;
;             *(f32x4*)(Y + (row * (unsigned)DM + col0 + BJ * HALF + n * 16)) = acc[ai][BJ][m][n] + ((r[i - LO] - mean[(i - LO) >> 1]) * rstd[(i - LO) >> 1]) * gv[n] + bv[n]; }
;         __builtin_amdgcn_sched_barrier(0);
;     }
;     template <bool LN, int BJ> DI void load_gb(unsigned col0, f32x4 (&gv)[2], f32x4 (&bv)[2]) const {
; #pragma unroll
;         for (int n = 0; n < 2; ++n) {
;             if (LN) { gv[n] = *(const f32x4*)(gam + col0 + BJ * HALF + n * 16) * ALPHA; bv[n] = *(const f32x4*)(bet + col0 + BJ * HALF + n * 16) * ALPHA; }
	v_sub_f32_e32 v137, v137, v204
	v_sub_f32_e32 v136, v136, v204
	v_sub_f32_e32 v139, v139, v204
	v_sub_f32_e32 v138, v138, v204
	v_pk_mul_f32 v[138:139], v[204:205], v[138:139] op_sel:[1,0]
	v_pk_mul_f32 v[136:137], v[204:205], v[136:137] op_sel:[1,0]
	v_pk_fma_f32 v[138:139], v[152:153], v[138:139], v[94:95]
	v_pk_fma_f32 v[136:137], v[154:155], v[136:137], v[92:93]
	v_pk_fma_f32 v[138:139], v[134:135], s[78:79], v[138:139] op_sel_hi:[1,0,1]
	v_pk_fma_f32 v[136:137], v[132:133], s[78:79], v[136:137] op_sel_hi:[1,0,1]
	global_store_dwordx4 v[240:241], v[136:139], off
	s_nop 1
	v_sub_f32_e32 v137, v209, v204
	v_sub_f32_e32 v136, v208, v204
	v_sub_f32_e32 v139, v211, v204
	v_sub_f32_e32 v138, v210, v204
	v_pk_mul_f32 v[138:139], v[204:205], v[138:139] op_sel:[1,0]
	v_pk_mul_f32 v[136:137], v[204:205], v[136:137] op_sel:[1,0]
	v_pk_fma_f32 v[138:139], v[148:149], v[138:139], v[90:91]
	v_pk_fma_f32 v[136:137], v[150:151], v[136:137], v[88:89]
	v_add_u32_e32 v204, 0x40010, v194
	v_mov_b32_e32 v205, v159
	v_pk_fma_f32 v[138:139], v[130:131], s[78:79], v[138:139] op_sel_hi:[1,0,1]
	v_pk_fma_f32 v[136:137], v[128:129], s[78:79], v[136:137] op_sel_hi:[1,0,1]
	v_lshl_add_u64 v[204:205], v[204:205], 2, s[90:91]
	global_store_dwordx4 v[204:205], v[136:139], off
	v_add_u32_e32 v204, 0x48000, v194
	v_mov_b32_e32 v205, v159
	v_sub_f32_e32 v137, v213, v238
	v_sub_f32_e32 v136, v212, v238
	v_sub_f32_e32 v139, v215, v238
	v_sub_f32_e32 v138, v214, v238
	v_pk_mul_f32 v[138:139], v[238:239], v[138:139] op_sel:[1,0]
	v_pk_mul_f32 v[136:137], v[238:239], v[136:137] op_sel:[1,0]
	v_pk_fma_f32 v[138:139], v[152:153], v[138:139], v[86:87]
	v_pk_fma_f32 v[136:137], v[154:155], v[136:137], v[84:85]
	v_pk_fma_f32 v[138:139], v[134:135], s[78:79], v[138:139] op_sel_hi:[1,0,1]
	v_pk_fma_f32 v[136:137], v[132:133], s[78:79], v[136:137] op_sel_hi:[1,0,1]
	v_lshl_add_u64 v[204:205], v[204:205], 2, s[90:91]
	global_store_dwordx4 v[204:205], v[136:139], off
	v_add_u32_e32 v204, 0x48010, v194
	v_mov_b32_e32 v205, v159
	v_sub_f32_e32 v137, v217, v238
	v_sub_f32_e32 v136, v216, v238
	v_sub_f32_e32 v139, v219, v238
	v_sub_f32_e32 v138, v218, v238
	v_pk_mul_f32 v[138:139], v[238:239], v[138:139] op_sel:[1,0]
	v_pk_mul_f32 v[136:137], v[238:239], v[136:137] op_sel:[1,0]
	v_pk_fma_f32 v[138:139], v[148:149], v[138:139], v[82:83]
	v_pk_fma_f32 v[136:137], v[150:151], v[136:137], v[80:81]
	v_pk_fma_f32 v[138:139], v[130:131], s[78:79], v[138:139] op_sel_hi:[1,0,1]
	v_pk_fma_f32 v[136:137], v[128:129], s[78:79], v[136:137] op_sel_hi:[1,0,1]
	v_lshl_add_u64 v[204:205], v[204:205], 2, s[90:91]
	global_store_dwordx4 v[204:205], v[136:139], off
	s_nop 1
	v_add_u32_e32 v138, 0xa0, v206
	v_lshlrev_b32_e32 v136, 1, v138
	v_mov_b32_e32 v137, v159
	v_lshlrev_b32_e32 v237, 11, v138
	v_lshl_add_u64 v[204:205], v[136:137], 2, s[2:3]
	v_add_u32_e32 v136, v237, v158
	v_lshl_add_u64 v[136:137], v[136:137], 2, s[88:89]
	global_load_dwordx2 v[240:241], v[204:205], off
	v_add_u32_e32 v208, v237, v231
	global_load_dwordx4 v[136:139], v[136:137], off
	v_mov_b32_e32 v209, v159
	v_lshl_add_u64 v[208:209], v[208:209], 2, s[88:89]
	global_load_dwordx4 v[212:215], v[208:209], off
	v_add_u32_e32 v208, 0xb0, v206
	v_lshlrev_b32_e32 v206, 1, v208
	v_mov_b32_e32 v207, v159
	v_lshlrev_b32_e32 v238, 11, v208
	v_lshl_add_u64 v[210:211], v[206:207], 2, s[2:3]
	v_add_u32_e32 v206, v238, v158
	v_lshl_add_u64 v[206:207], v[206:207], 2, s[88:89]
	global_load_dwordx2 v[242:243], v[210:211], off
	v_add_u32_e32 v216, v238, v231
	global_load_dwordx4 v[206:209], v[206:207], off
	v_mov_b32_e32 v217, v159
	v_lshl_add_u64 v[216:217], v[216:217], 2, s[88:89]
	global_load_dwordx4 v[216:219], v[216:217], off
	v_add_u32_e32 v244, 0x50000, v194
	v_mov_b32_e32 v245, v159
	v_lshl_add_u64 v[244:245], v[244:245], 2, s[90:91]
	s_waitcnt vmcnt(0)
	v_sub_f32_e32 v137, v137, v240
	v_sub_f32_e32 v136, v136, v240
	v_sub_f32_e32 v139, v139, v240
	v_sub_f32_e32 v138, v138, v240
	v_pk_mul_f32 v[138:139], v[240:241], v[138:139] op_sel:[1,0]
	v_pk_mul_f32 v[136:137], v[240:241], v[136:137] op_sel:[1,0]
	v_pk_fma_f32 v[138:139], v[152:153], v[138:139], v[78:79]
	v_pk_fma_f32 v[136:137], v[154:155], v[136:137], v[76:77]
	v_pk_fma_f32 v[138:139], v[134:135], s[78:79], v[138:139] op_sel_hi:[1,0,1]
	v_pk_fma_f32 v[136:137], v[132:133], s[78:79], v[136:137] op_sel_hi:[1,0,1]
	global_store_dwordx4 v[244:245], v[136:139], off
	s_nop 1
	v_sub_f32_e32 v137, v213, v240
	v_sub_f32_e32 v136, v212, v240
	v_sub_f32_e32 v139, v215, v240
	v_sub_f32_e32 v138, v214, v240
	v_pk_mul_f32 v[138:139], v[240:241], v[138:139] op_sel:[1,0]
	v_pk_mul_f32 v[136:137], v[240:241], v[136:137] op_sel:[1,0]
	v_pk_fma_f32 v[138:139], v[148:149], v[138:139], v[74:75]
	v_pk_fma_f32 v[136:137], v[150:151], v[136:137], v[72:73]
	v_add_u32_e32 v212, 0x50010, v194
	v_mov_b32_e32 v213, v159
	v_pk_fma_f32 v[138:139], v[130:131], s[78:79], v[138:139] op_sel_hi:[1,0,1]
	v_pk_fma_f32 v[136:137], v[128:129], s[78:79], v[136:137] op_sel_hi:[1,0,1]
	v_lshl_add_u64 v[212:213], v[212:213], 2, s[90:91]
	global_store_dwordx4 v[212:213], v[136:139], off
	s_nop 1
	v_sub_f32_e32 v137, v207, v242
	v_sub_f32_e32 v136, v206, v242
	v_sub_f32_e32 v139, v209, v242
	v_sub_f32_e32 v138, v208, v242
	v_pk_mul_f32 v[136:137], v[242:243], v[136:137] op_sel:[1,0]
	v_pk_mul_f32 v[138:139], v[242:243], v[138:139] op_sel:[1,0]
	v_pk_fma_f32 v[136:137], v[154:155], v[136:137], v[68:69]
	v_pk_fma_f32 v[138:139], v[152:153], v[138:139], v[70:71]
	v_pk_fma_f32 v[132:133], v[132:133], s[78:79], v[136:137] op_sel_hi:[1,0,1]
	v_add_u32_e32 v136, 0x58000, v194
	v_mov_b32_e32 v137, v159
	v_pk_fma_f32 v[134:135], v[134:135], s[78:79], v[138:139] op_sel_hi:[1,0,1]
	v_lshl_add_u64 v[136:137], v[136:137], 2, s[90:91]
	global_store_dwordx4 v[136:137], v[132:135], off
	s_nop 1
	v_sub_f32_e32 v133, v217, v242
	v_sub_f32_e32 v132, v216, v242
	v_sub_f32_e32 v135, v219, v242
	v_sub_f32_e32 v134, v218, v242
	v_pk_mul_f32 v[132:133], v[242:243], v[132:133] op_sel:[1,0]
	v_pk_mul_f32 v[134:135], v[242:243], v[134:135] op_sel:[1,0]
	v_pk_fma_f32 v[132:133], v[150:151], v[132:133], v[64:65]
	v_pk_fma_f32 v[134:135], v[148:149], v[134:135], v[66:67]
	v_pk_fma_f32 v[128:129], v[128:129], s[78:79], v[132:133] op_sel_hi:[1,0,1]
	v_add_u32_e32 v132, 0x58010, v194
	v_mov_b32_e32 v133, v159
	v_pk_fma_f32 v[130:131], v[130:131], s[78:79], v[134:135] op_sel_hi:[1,0,1]
	v_lshl_add_u64 v[132:133], v[132:133], 2, s[90:91]
	global_store_dwordx4 v[132:133], v[128:131], off
	global_load_dwordx4 v[128:131], v[140:141], off offset:512
	v_add_u32_e32 v136, v232, v230
	v_mov_b32_e32 v137, v159
	v_lshl_add_u64 v[136:137], v[136:137], 2, s[88:89]
	s_waitcnt vmcnt(0)
;     template <bool LN, int BJ, int LO, int HI> DI void batch(const f32x4 (&acc)[2][2][4][2], unsigned row0, unsigned col0, const f32x4 (&gv)[2], const f32x4 (&bv)[2]) const {
;         f32x4 r[HI - LO]; float mean[(HI - LO) / 2], rstd[(HI - LO) / 2];
; #pragma unroll
;         for (int i = LO; i < HI; ++i) { const int ai = i >> 3, m = (i >> 1) & 3, n = i & 1; const unsigned row = row0 + ai * HALF + m * 16;
;             if (n == 0) { mean[(i - LO) >> 1] = 0.f; rstd[(i - LO) >> 1] = 1.f;
;                 if (LN) { const float2 st = *(const float2*)(stats + row * 2u); mean[(i - LO) >> 1] = st.x; rstd[(i - LO) >> 1] = st.y; } }
;             r[i - LO] = *(const f32x4*)(src + (row * (unsigned)DM + col0 + BJ * HALF + n * 16)); }
; #pragma unroll
;         for (int i = LO; i < HI; ++i) { const int ai = i >> 3, m = (i >> 1) & 3, n = i & 1; const unsigned row = row0 + ai * HALF + m * 16;
;             *(f32x4*)(Y + (row * (unsigned)DM + col0 + BJ * HALF + n * 16)) = acc[ai][BJ][m][n] + ((r[i - LO] - mean[(i - LO) >> 1]) * rstd[(i - LO) >> 1]) * gv[n] + bv[n]; }
;     template <bool LN> DI void run(const f32x4 (&acc)[2][2][4][2], const Unit& u, int wr, int wc, int fr, int fq) const {
;     ...
;         load_gb<LN, 1>(col0, gv, bv);
;         batch<LN, 1, 0, 8>(acc, row0, col0, gv, bv);
	v_pk_mul_f32 v[212:213], v[130:131], s[78:79] op_sel_hi:[1,0]
	v_pk_mul_f32 v[214:215], v[128:129], s[78:79] op_sel_hi:[1,0]
	global_load_dwordx4 v[132:135], v[142:143], off offset:512
	global_load_dwordx4 v[128:131], v[140:141], off offset:576
	s_waitcnt vmcnt(0)
	v_pk_mul_f32 v[206:207], v[130:131], s[78:79] op_sel_hi:[1,0]
	v_pk_mul_f32 v[208:209], v[128:129], s[78:79] op_sel_hi:[1,0]
	global_load_dwordx4 v[128:131], v[142:143], off offset:576
	global_load_dwordx2 v[220:221], v[144:145], off
	global_load_dwordx4 v[240:243], v[136:137], off
	v_add_u32_e32 v136, v232, v229
	v_mov_b32_e32 v137, v159
	v_lshl_add_u64 v[136:137], v[136:137], 2, s[88:89]
	global_load_dwordx4 v[244:247], v[136:137], off
	global_load_dwordx2 v[218:219], v[146:147], off
	v_add_u32_e32 v136, v195, v230
	v_mov_b32_e32 v137, v159
	v_lshl_add_u64 v[136:137], v[136:137], 2, s[88:89]
	global_load_dwordx4 v[248:251], v[136:137], off
	v_add_u32_e32 v136, v195, v229
	v_mov_b32_e32 v137, v159
	v_lshl_add_u64 v[136:137], v[136:137], 2, s[88:89]
	global_load_dwordx4 v[152:155], v[136:137], off
	global_load_dwordx2 v[216:217], v[200:201], off
	v_add_u32_e32 v136, v236, v230
	v_mov_b32_e32 v137, v159
	v_lshl_add_u64 v[136:137], v[136:137], 2, s[88:89]
	global_load_dwordx4 v[148:151], v[136:137], off
	v_add_u32_e32 v136, v236, v229
	v_mov_b32_e32 v137, v159
	v_lshl_add_u64 v[136:137], v[136:137], 2, s[88:89]
	global_load_dwordx4 v[144:147], v[136:137], off
	global_load_dwordx2 v[200:201], v[202:203], off
	v_add_u32_e32 v136, v235, v230
	v_mov_b32_e32 v137, v159
	v_lshl_add_u64 v[136:137], v[136:137], 2, s[88:89]
	global_load_dwordx4 v[140:143], v[136:137], off
	v_add_u32_e32 v136, v235, v229
	v_mov_b32_e32 v137, v159
	v_lshl_add_u64 v[136:137], v[136:137], 2, s[88:89]
	global_load_dwordx4 v[136:139], v[136:137], off
	v_add_u32_e32 v202, 0x80, v194
	v_mov_b32_e32 v203, v159
	v_lshl_add_u64 v[202:203], v[202:203], 2, s[90:91]
	s_waitcnt vmcnt(0)
	v_sub_f32_e32 v241, v241, v220
	v_sub_f32_e32 v240, v240, v220
	v_sub_f32_e32 v243, v243, v220
	v_sub_f32_e32 v242, v242, v220
	v_pk_mul_f32 v[242:243], v[220:221], v[242:243] op_sel:[1,0]
	v_pk_mul_f32 v[240:241], v[220:221], v[240:241] op_sel:[1,0]
	v_pk_fma_f32 v[242:243], v[212:213], v[242:243], v[62:63]
	v_pk_fma_f32 v[240:241], v[214:215], v[240:241], v[60:61]
	v_pk_fma_f32 v[242:243], v[134:135], s[78:79], v[242:243] op_sel_hi:[1,0,1]
	v_pk_fma_f32 v[240:241], v[132:133], s[78:79], v[240:241] op_sel_hi:[1,0,1]
	global_store_dwordx4 v[202:203], v[240:243], off
	v_sub_f32_e32 v203, v245, v220
	v_sub_f32_e32 v202, v244, v220
	v_sub_f32_e32 v241, v247, v220
	v_sub_f32_e32 v240, v246, v220
	v_pk_mul_f32 v[202:203], v[220:221], v[202:203] op_sel:[1,0]
	v_pk_mul_f32 v[240:241], v[220:221], v[240:241] op_sel:[1,0]
	v_pk_fma_f32 v[202:203], v[208:209], v[202:203], v[56:57]
	v_pk_fma_f32 v[220:221], v[206:207], v[240:241], v[58:59]
	v_pk_fma_f32 v[240:241], v[128:129], s[78:79], v[202:203] op_sel_hi:[1,0,1]
	v_add_u32_e32 v202, 0x90, v194
	v_mov_b32_e32 v203, v159
	v_pk_fma_f32 v[242:243], v[130:131], s[78:79], v[220:221] op_sel_hi:[1,0,1]
	v_lshl_add_u64 v[202:203], v[202:203], 2, s[90:91]
	global_store_dwordx4 v[202:203], v[240:243], off
	v_sub_f32_e32 v203, v249, v218
	v_sub_f32_e32 v202, v248, v218
	v_sub_f32_e32 v221, v251, v218
	v_sub_f32_e32 v220, v250, v218
	v_pk_mul_f32 v[202:203], v[218:219], v[202:203] op_sel:[1,0]
	v_pk_mul_f32 v[220:221], v[218:219], v[220:221] op_sel:[1,0]
	v_pk_fma_f32 v[202:203], v[214:215], v[202:203], v[52:53]
	v_pk_fma_f32 v[220:221], v[212:213], v[220:221], v[54:55]
	v_pk_fma_f32 v[240:241], v[132:133], s[78:79], v[202:203] op_sel_hi:[1,0,1]
	v_add_u32_e32 v202, 0x8080, v194
	v_mov_b32_e32 v203, v159
	v_sub_f32_e32 v153, v153, v218
	v_sub_f32_e32 v152, v152, v218
	v_sub_f32_e32 v155, v155, v218
	v_sub_f32_e32 v154, v154, v218
	v_pk_fma_f32 v[242:243], v[134:135], s[78:79], v[220:221] op_sel_hi:[1,0,1]
	v_lshl_add_u64 v[202:203], v[202:203], 2, s[90:91]
	v_pk_mul_f32 v[154:155], v[218:219], v[154:155] op_sel:[1,0]
	v_pk_mul_f32 v[152:153], v[218:219], v[152:153] op_sel:[1,0]
	global_store_dwordx4 v[202:203], v[240:243], off
	v_pk_fma_f32 v[152:153], v[208:209], v[152:153], v[48:49]
	v_pk_fma_f32 v[154:155], v[206:207], v[154:155], v[50:51]
	v_add_u32_e32 v202, 0x8090, v194
	v_mov_b32_e32 v203, v159
	v_sub_f32_e32 v149, v149, v216
	v_sub_f32_e32 v148, v148, v216
	v_sub_f32_e32 v151, v151, v216
	v_sub_f32_e32 v150, v150, v216
	v_pk_fma_f32 v[154:155], v[130:131], s[78:79], v[154:155] op_sel_hi:[1,0,1]
	v_pk_fma_f32 v[152:153], v[128:129], s[78:79], v[152:153] op_sel_hi:[1,0,1]
	v_lshl_add_u64 v[202:203], v[202:203], 2, s[90:91]
	v_pk_mul_f32 v[150:151], v[216:217], v[150:151] op_sel:[1,0]
	v_pk_mul_f32 v[148:149], v[216:217], v[148:149] op_sel:[1,0]
	global_store_dwordx4 v[202:203], v[152:155], off
	v_pk_fma_f32 v[148:149], v[214:215], v[148:149], v[44:45]
	v_pk_fma_f32 v[150:151], v[212:213], v[150:151], v[46:47]
	v_add_u32_e32 v152, 0x10080, v194
	v_mov_b32_e32 v153, v159
	v_sub_f32_e32 v145, v145, v216
	v_sub_f32_e32 v144, v144, v216
	v_sub_f32_e32 v147, v147, v216
	v_sub_f32_e32 v146, v146, v216
	v_pk_fma_f32 v[150:151], v[134:135], s[78:79], v[150:151] op_sel_hi:[1,0,1]
	v_pk_fma_f32 v[148:149], v[132:133], s[78:79], v[148:149] op_sel_hi:[1,0,1]
	v_lshl_add_u64 v[152:153], v[152:153], 2, s[90:91]
	v_pk_mul_f32 v[146:147], v[216:217], v[146:147] op_sel:[1,0]
	v_pk_mul_f32 v[144:145], v[216:217], v[144:145] op_sel:[1,0]
	global_store_dwordx4 v[152:153], v[148:151], off
	v_pk_fma_f32 v[144:145], v[208:209], v[144:145], v[40:41]
	v_pk_fma_f32 v[146:147], v[206:207], v[146:147], v[42:43]
;     template <bool LN, int BJ, int LO, int HI> DI void batch(const f32x4 (&acc)[2][2][4][2], unsigned row0, unsigned col0, const f32x4 (&gv)[2], const f32x4 (&bv)[2]) const {
;         f32x4 r[HI - LO]; float mean[(HI - LO) / 2], rstd[(HI - LO) / 2];
; #pragma unroll
;         for (int i = LO; i < HI; ++i) { const int ai = i >> 3, m = (i >> 1) & 3, n = i & 1; const unsigned row = row0 + ai * HALF + m * 16;
;             if (n == 0) { mean[(i - LO) >> 1] = 0.f; rstd[(i - LO) >> 1] = 1.f;
;                 if (LN) { const float2 st = *(const float2*)(stats + row * 2u); mean[(i - LO) >> 1] = st.x; rstd[(i - LO) >> 1] = st.y; } }
;             r[i - LO] = *(const f32x4*)(src + (row * (unsigned)DM + col0 + BJ * HALF + n * 16)); }
; #pragma unroll
;         for (int i = LO; i < HI; ++i) { const int ai = i >> 3, m = (i >> 1) & 3, n = i & 1; const unsigned row = row0 + ai * HALF + m * 16;
;             *(f32x4*)(Y + (row * (unsigned)DM + col0 + BJ * HALF + n * 16)) = acc[ai][BJ][m][n] + ((r[i - LO] - mean[(i - LO) >> 1]) * rstd[(i - LO) >> 1]) * gv[n] + bv[n]; }
;     template <bool LN> DI void run(const f32x4 (&acc)[2][2][4][2], const Unit& u, int wr, int wc, int fr, int fq) const {
;     ...
;         batch<LN, 1, 8, 16>(acc, row0, col0, gv, bv);
	v_add_u32_e32 v148, 0x10090, v194
	v_mov_b32_e32 v149, v159
	v_sub_f32_e32 v141, v141, v200
	v_sub_f32_e32 v140, v140, v200
	v_sub_f32_e32 v143, v143, v200
	v_sub_f32_e32 v142, v142, v200
	v_pk_fma_f32 v[146:147], v[130:131], s[78:79], v[146:147] op_sel_hi:[1,0,1]
	v_pk_fma_f32 v[144:145], v[128:129], s[78:79], v[144:145] op_sel_hi:[1,0,1]
	v_lshl_add_u64 v[148:149], v[148:149], 2, s[90:91]
	v_pk_mul_f32 v[142:143], v[200:201], v[142:143] op_sel:[1,0]
	v_pk_mul_f32 v[140:141], v[200:201], v[140:141] op_sel:[1,0]
	global_store_dwordx4 v[148:149], v[144:147], off
	v_pk_fma_f32 v[140:141], v[214:215], v[140:141], v[36:37]
	v_pk_fma_f32 v[142:143], v[212:213], v[142:143], v[38:39]
	v_add_u32_e32 v144, 0x18080, v194
	v_mov_b32_e32 v145, v159
	v_sub_f32_e32 v137, v137, v200
	v_sub_f32_e32 v136, v136, v200
	v_sub_f32_e32 v139, v139, v200
	v_sub_f32_e32 v138, v138, v200
	v_pk_fma_f32 v[142:143], v[134:135], s[78:79], v[142:143] op_sel_hi:[1,0,1]
	v_pk_fma_f32 v[140:141], v[132:133], s[78:79], v[140:141] op_sel_hi:[1,0,1]
	v_lshl_add_u64 v[144:145], v[144:145], 2, s[90:91]
	v_pk_mul_f32 v[138:139], v[200:201], v[138:139] op_sel:[1,0]
	v_pk_mul_f32 v[136:137], v[200:201], v[136:137] op_sel:[1,0]
	global_store_dwordx4 v[144:145], v[140:143], off
	v_pk_fma_f32 v[136:137], v[208:209], v[136:137], v[32:33]
	v_pk_fma_f32 v[138:139], v[206:207], v[138:139], v[34:35]
	v_add_u32_e32 v140, 0x18090, v194
	v_mov_b32_e32 v141, v159
	v_pk_fma_f32 v[138:139], v[130:131], s[78:79], v[138:139] op_sel_hi:[1,0,1]
	v_pk_fma_f32 v[136:137], v[128:129], s[78:79], v[136:137] op_sel_hi:[1,0,1]
	v_lshl_add_u64 v[140:141], v[140:141], 2, s[90:91]
	global_store_dwordx4 v[140:141], v[136:139], off
	s_nop 1
	v_add_u32_e32 v136, v233, v230
	v_mov_b32_e32 v137, v159
	v_lshl_add_u64 v[136:137], v[136:137], 2, s[88:89]
	global_load_dwordx2 v[220:221], v[196:197], off
	global_load_dwordx4 v[216:219], v[136:137], off
	v_add_u32_e32 v136, v233, v229
	v_mov_b32_e32 v137, v159
	v_lshl_add_u64 v[136:137], v[136:137], 2, s[88:89]
	global_load_dwordx4 v[240:243], v[136:137], off
	global_load_dwordx2 v[200:201], v[198:199], off
	v_add_u32_e32 v136, v234, v230
	v_mov_b32_e32 v137, v159
	v_lshl_add_u64 v[136:137], v[136:137], 2, s[88:89]
	global_load_dwordx4 v[244:247], v[136:137], off
	v_add_u32_e32 v136, v234, v229
	v_mov_b32_e32 v137, v159
	v_lshl_add_u64 v[136:137], v[136:137], 2, s[88:89]
	global_load_dwordx4 v[152:155], v[136:137], off
	global_load_dwordx2 v[198:199], v[204:205], off
	v_add_u32_e32 v136, v237, v230
	v_mov_b32_e32 v137, v159
	v_lshl_add_u64 v[136:137], v[136:137], 2, s[88:89]
	global_load_dwordx4 v[148:151], v[136:137], off
	v_add_u32_e32 v136, v237, v229
	v_mov_b32_e32 v137, v159
	v_lshl_add_u64 v[136:137], v[136:137], 2, s[88:89]
	global_load_dwordx4 v[144:147], v[136:137], off
	global_load_dwordx2 v[196:197], v[210:211], off
	v_add_u32_e32 v136, v238, v230
	v_mov_b32_e32 v137, v159
	v_lshl_add_u64 v[136:137], v[136:137], 2, s[88:89]
	global_load_dwordx4 v[140:143], v[136:137], off
	v_add_u32_e32 v136, v238, v229
	v_mov_b32_e32 v137, v159
	v_lshl_add_u64 v[136:137], v[136:137], 2, s[88:89]
	global_load_dwordx4 v[136:139], v[136:137], off
	v_add_u32_e32 v210, 0x40080, v194
	v_mov_b32_e32 v211, v159
	v_lshl_add_u64 v[210:211], v[210:211], 2, s[90:91]
	s_waitcnt vmcnt(0)
;     template <bool LN, int BJ, int LO, int HI> DI void batch(const f32x4 (&acc)[2][2][4][2], unsigned row0, unsigned col0, const f32x4 (&gv)[2], const f32x4 (&bv)[2]) const {
;     ...
;         for (int i = LO; i < HI; ++i) { const int ai = i >> 3, m = (i >> 1) & 3, n = i & 1; const unsigned row = row0 + ai * HALF + m * 16;
;             if (n == 0) { mean[(i - LO) >> 1] = 0.f; rstd[(i - LO) >> 1] = 1.f;
;                 if (LN) { const float2 st = *(const float2*)(stats + row * 2u); mean[(i - LO) >> 1] = st.x; rstd[(i - LO) >> 1] = st.y; } }
;             r[i - LO] = *(const f32x4*)(src + (row * (unsigned)DM + col0 + BJ * HALF + n * 16)); }
; #pragma unroll
;         for (int i = LO; i < HI; ++i) { const int ai = i >> 3, m = (i >> 1) & 3, n = i & 1; const unsigned row = row0 + ai * HALF + m * 16;
;             *(f32x4*)(Y + (row * (unsigned)DM + col0 + BJ * HALF + n * 16)) = acc[ai][BJ][m][n] + ((r[i - LO] - mean[(i - LO) >> 1]) * rstd[(i - LO) >> 1]) * gv[n] + bv[n]; }
	v_sub_f32_e32 v203, v217, v220
	v_sub_f32_e32 v202, v216, v220
	v_sub_f32_e32 v205, v219, v220
	v_sub_f32_e32 v204, v218, v220
	v_pk_mul_f32 v[204:205], v[220:221], v[204:205] op_sel:[1,0]
	v_pk_mul_f32 v[202:203], v[220:221], v[202:203] op_sel:[1,0]
	v_pk_fma_f32 v[204:205], v[212:213], v[204:205], v[30:31]
	v_pk_fma_f32 v[202:203], v[214:215], v[202:203], v[28:29]
	v_pk_fma_f32 v[204:205], v[134:135], s[78:79], v[204:205] op_sel_hi:[1,0,1]
	v_pk_fma_f32 v[202:203], v[132:133], s[78:79], v[202:203] op_sel_hi:[1,0,1]
	global_store_dwordx4 v[210:211], v[202:205], off
	v_add_u32_e32 v210, 0x40090, v194
	v_mov_b32_e32 v211, v159
	v_sub_f32_e32 v203, v241, v220
	v_sub_f32_e32 v202, v240, v220
	v_sub_f32_e32 v205, v243, v220
	v_sub_f32_e32 v204, v242, v220
	v_pk_mul_f32 v[204:205], v[220:221], v[204:205] op_sel:[1,0]
	v_pk_mul_f32 v[202:203], v[220:221], v[202:203] op_sel:[1,0]
	v_pk_fma_f32 v[204:205], v[206:207], v[204:205], v[26:27]
	v_pk_fma_f32 v[202:203], v[208:209], v[202:203], v[24:25]
	v_pk_fma_f32 v[204:205], v[130:131], s[78:79], v[204:205] op_sel_hi:[1,0,1]
	v_pk_fma_f32 v[202:203], v[128:129], s[78:79], v[202:203] op_sel_hi:[1,0,1]
	v_lshl_add_u64 v[210:211], v[210:211], 2, s[90:91]
	global_store_dwordx4 v[210:211], v[202:205], off
	v_sub_f32_e32 v149, v149, v198
	v_sub_f32_e32 v148, v148, v198
	v_sub_f32_e32 v203, v245, v200
	v_sub_f32_e32 v202, v244, v200
	v_sub_f32_e32 v141, v141, v196
	v_sub_f32_e32 v140, v140, v196
	v_sub_f32_e32 v205, v247, v200
	v_sub_f32_e32 v204, v246, v200
	v_pk_mul_f32 v[202:203], v[200:201], v[202:203] op_sel:[1,0]
	v_sub_f32_e32 v151, v151, v198
	v_sub_f32_e32 v150, v150, v198
	v_pk_mul_f32 v[148:149], v[198:199], v[148:149] op_sel:[1,0]
	v_sub_f32_e32 v143, v143, v196
	v_sub_f32_e32 v142, v142, v196
	v_pk_mul_f32 v[140:141], v[196:197], v[140:141] op_sel:[1,0]
	v_pk_mul_f32 v[204:205], v[200:201], v[204:205] op_sel:[1,0]
	v_pk_fma_f32 v[202:203], v[214:215], v[202:203], v[20:21]
	v_sub_f32_e32 v153, v153, v200
	v_sub_f32_e32 v152, v152, v200
	v_sub_f32_e32 v155, v155, v200
	v_sub_f32_e32 v154, v154, v200
	v_pk_mul_f32 v[150:151], v[198:199], v[150:151] op_sel:[1,0]
	v_pk_fma_f32 v[148:149], v[214:215], v[148:149], v[12:13]
	v_pk_mul_f32 v[142:143], v[196:197], v[142:143] op_sel:[1,0]
	v_pk_fma_f32 v[140:141], v[214:215], v[140:141], v[4:5]
	v_pk_fma_f32 v[204:205], v[212:213], v[204:205], v[22:23]
	v_pk_fma_f32 v[202:203], v[132:133], s[78:79], v[202:203] op_sel_hi:[1,0,1]
	v_pk_mul_f32 v[154:155], v[200:201], v[154:155] op_sel:[1,0]
	v_pk_mul_f32 v[152:153], v[200:201], v[152:153] op_sel:[1,0]
	v_pk_fma_f32 v[150:151], v[212:213], v[150:151], v[14:15]
	v_pk_fma_f32 v[148:149], v[132:133], s[78:79], v[148:149] op_sel_hi:[1,0,1]
	v_pk_fma_f32 v[142:143], v[212:213], v[142:143], v[6:7]
	v_pk_fma_f32 v[132:133], v[132:133], s[78:79], v[140:141] op_sel_hi:[1,0,1]
	v_add_u32_e32 v140, 0x58080, v194
	v_mov_b32_e32 v141, v159
	v_pk_fma_f32 v[204:205], v[134:135], s[78:79], v[204:205] op_sel_hi:[1,0,1]
	v_pk_fma_f32 v[152:153], v[208:209], v[152:153], v[16:17]
	v_pk_fma_f32 v[154:155], v[206:207], v[154:155], v[18:19]
	v_add_u32_e32 v200, 0x48090, v194
	v_mov_b32_e32 v201, v159
	v_pk_fma_f32 v[150:151], v[134:135], s[78:79], v[150:151] op_sel_hi:[1,0,1]
	v_pk_fma_f32 v[134:135], v[134:135], s[78:79], v[142:143] op_sel_hi:[1,0,1]
	v_lshl_add_u64 v[140:141], v[140:141], 2, s[90:91]
	v_pk_fma_f32 v[154:155], v[130:131], s[78:79], v[154:155] op_sel_hi:[1,0,1]
	v_pk_fma_f32 v[152:153], v[128:129], s[78:79], v[152:153] op_sel_hi:[1,0,1]
	v_lshl_add_u64 v[200:201], v[200:201], 2, s[90:91]
	v_sub_f32_e32 v145, v145, v198
	v_sub_f32_e32 v144, v144, v198
	global_store_dwordx4 v[140:141], v[132:135], off
	global_store_dwordx4 v[200:201], v[152:155], off
	v_sub_f32_e32 v147, v147, v198
	v_sub_f32_e32 v133, v137, v196
	v_sub_f32_e32 v132, v136, v196
	v_add_u32_e32 v152, 0x50080, v194
	v_mov_b32_e32 v153, v159
	v_sub_f32_e32 v146, v146, v198
	v_pk_mul_f32 v[144:145], v[198:199], v[144:145] op_sel:[1,0]
	v_sub_f32_e32 v135, v139, v196
	v_sub_f32_e32 v134, v138, v196
	v_pk_mul_f32 v[132:133], v[196:197], v[132:133] op_sel:[1,0]
	v_lshl_add_u64 v[152:153], v[152:153], 2, s[90:91]
	v_pk_mul_f32 v[146:147], v[198:199], v[146:147] op_sel:[1,0]
	v_pk_fma_f32 v[144:145], v[208:209], v[144:145], v[8:9]
	v_pk_mul_f32 v[134:135], v[196:197], v[134:135] op_sel:[1,0]
	v_pk_fma_f32 v[132:133], v[208:209], v[132:133], v[0:1]
	v_add_u32_e32 v210, 0x48080, v194
	v_mov_b32_e32 v211, v159
	global_store_dwordx4 v[152:153], v[148:151], off
	v_pk_fma_f32 v[146:147], v[206:207], v[146:147], v[10:11]
	v_pk_fma_f32 v[144:145], v[128:129], s[78:79], v[144:145] op_sel_hi:[1,0,1]
	v_add_u32_e32 v148, 0x50090, v194
	v_mov_b32_e32 v149, v159
	v_pk_fma_f32 v[134:135], v[206:207], v[134:135], v[2:3]
	v_pk_fma_f32 v[128:129], v[128:129], s[78:79], v[132:133] op_sel_hi:[1,0,1]
	v_add_u32_e32 v132, 0x58090, v194
	v_mov_b32_e32 v133, v159
	v_lshl_add_u64 v[210:211], v[210:211], 2, s[90:91]
	v_pk_fma_f32 v[146:147], v[130:131], s[78:79], v[146:147] op_sel_hi:[1,0,1]
	v_lshl_add_u64 v[148:149], v[148:149], 2, s[90:91]
	v_pk_fma_f32 v[130:131], v[130:131], s[78:79], v[134:135] op_sel_hi:[1,0,1]
	v_lshl_add_u64 v[132:133], v[132:133], 2, s[90:91]
	global_store_dwordx4 v[210:211], v[202:205], off
	global_store_dwordx4 v[148:149], v[144:147], off
	global_store_dwordx4 v[132:133], v[128:131], off
	s_mov_b64 s[24:25], 0
	s_branch .LBB0_324
